# side gemv: one pass per job, both K halves (128 rows) and both activation pairs loaded at once, fma chain as two v_fma_f32 per row
# speedup vs baseline: 1.1425x; 1.0058x over previous
.LBB0_636:
	v_cndmask_b32_e64 v0, 0, 1, s[0:1]
	v_cmp_ne_u32_e32 vcc, 1, v0
	v_or_b32_e32 v0, s3, v10
	v_lshlrev_b64 v[8:9], 2, v[0:1]
	v_lshl_add_u64 v[12:13], s[8:9], 0, v[8:9]
	v_lshl_add_u64 v[8:9], s[12:13], 0, v[8:9]
	s_mul_i32 s90, s3, 0x3830
	global_load_dword v3, v[12:13], off
	global_load_dword v11, v[8:9], off
	global_load_dword v28, v[12:13], off offset:256
	global_load_dword v29, v[8:9], off offset:256
	v_lshl_add_u64 v[8:9], s[90:91], 2, v[4:5]
	s_mov_b32 s14, 0xe0c0
	s_mov_b32 s15, 0
	global_load_dword v32, v[8:9], off
	v_lshl_add_u64 v[8:9], v[8:9], 0, s[14:15]
	global_load_dword v33, v[8:9], off
	v_lshl_add_u64 v[8:9], v[8:9], 0, s[14:15]
	global_load_dword v34, v[8:9], off
	v_lshl_add_u64 v[8:9], v[8:9], 0, s[14:15]
	global_load_dword v35, v[8:9], off
	v_lshl_add_u64 v[8:9], v[8:9], 0, s[14:15]
	global_load_dword v36, v[8:9], off
	v_lshl_add_u64 v[8:9], v[8:9], 0, s[14:15]
	global_load_dword v37, v[8:9], off
	v_lshl_add_u64 v[8:9], v[8:9], 0, s[14:15]
	global_load_dword v38, v[8:9], off
	v_lshl_add_u64 v[8:9], v[8:9], 0, s[14:15]
	global_load_dword v39, v[8:9], off
	v_lshl_add_u64 v[8:9], v[8:9], 0, s[14:15]
	global_load_dword v40, v[8:9], off
	v_lshl_add_u64 v[8:9], v[8:9], 0, s[14:15]
	global_load_dword v41, v[8:9], off
	v_lshl_add_u64 v[8:9], v[8:9], 0, s[14:15]
	global_load_dword v42, v[8:9], off
	v_lshl_add_u64 v[8:9], v[8:9], 0, s[14:15]
	global_load_dword v43, v[8:9], off
	v_lshl_add_u64 v[8:9], v[8:9], 0, s[14:15]
	global_load_dword v44, v[8:9], off
	v_lshl_add_u64 v[8:9], v[8:9], 0, s[14:15]
	global_load_dword v45, v[8:9], off
	v_lshl_add_u64 v[8:9], v[8:9], 0, s[14:15]
	global_load_dword v46, v[8:9], off
	v_lshl_add_u64 v[8:9], v[8:9], 0, s[14:15]
	global_load_dword v47, v[8:9], off
	v_lshl_add_u64 v[8:9], v[8:9], 0, s[14:15]
	global_load_dword v48, v[8:9], off
	v_lshl_add_u64 v[8:9], v[8:9], 0, s[14:15]
	global_load_dword v49, v[8:9], off
	v_lshl_add_u64 v[8:9], v[8:9], 0, s[14:15]
	global_load_dword v50, v[8:9], off
	v_lshl_add_u64 v[8:9], v[8:9], 0, s[14:15]
	global_load_dword v51, v[8:9], off
	v_lshl_add_u64 v[8:9], v[8:9], 0, s[14:15]
	global_load_dword v52, v[8:9], off
	v_lshl_add_u64 v[8:9], v[8:9], 0, s[14:15]
	global_load_dword v53, v[8:9], off
	v_lshl_add_u64 v[8:9], v[8:9], 0, s[14:15]
	global_load_dword v54, v[8:9], off
	v_lshl_add_u64 v[8:9], v[8:9], 0, s[14:15]
	global_load_dword v55, v[8:9], off
	v_lshl_add_u64 v[8:9], v[8:9], 0, s[14:15]
	global_load_dword v58, v[8:9], off
	v_lshl_add_u64 v[8:9], v[8:9], 0, s[14:15]
	global_load_dword v59, v[8:9], off
	v_lshl_add_u64 v[8:9], v[8:9], 0, s[14:15]
	global_load_dword v60, v[8:9], off
	v_lshl_add_u64 v[8:9], v[8:9], 0, s[14:15]
	global_load_dword v61, v[8:9], off
	v_lshl_add_u64 v[8:9], v[8:9], 0, s[14:15]
	global_load_dword v62, v[8:9], off
	v_lshl_add_u64 v[8:9], v[8:9], 0, s[14:15]
	global_load_dword v63, v[8:9], off
	v_lshl_add_u64 v[8:9], v[8:9], 0, s[14:15]
	global_load_dword v64, v[8:9], off
	v_lshl_add_u64 v[8:9], v[8:9], 0, s[14:15]
	global_load_dword v65, v[8:9], off
	v_lshl_add_u64 v[8:9], v[8:9], 0, s[14:15]
	global_load_dword v66, v[8:9], off
	v_lshl_add_u64 v[8:9], v[8:9], 0, s[14:15]
	global_load_dword v67, v[8:9], off
	v_lshl_add_u64 v[8:9], v[8:9], 0, s[14:15]
	global_load_dword v68, v[8:9], off
	v_lshl_add_u64 v[8:9], v[8:9], 0, s[14:15]
	global_load_dword v69, v[8:9], off
	v_lshl_add_u64 v[8:9], v[8:9], 0, s[14:15]
	global_load_dword v70, v[8:9], off
	v_lshl_add_u64 v[8:9], v[8:9], 0, s[14:15]
	global_load_dword v71, v[8:9], off
	v_lshl_add_u64 v[8:9], v[8:9], 0, s[14:15]
	global_load_dword v72, v[8:9], off
	v_lshl_add_u64 v[8:9], v[8:9], 0, s[14:15]
	global_load_dword v73, v[8:9], off
	v_lshl_add_u64 v[8:9], v[8:9], 0, s[14:15]
	global_load_dword v74, v[8:9], off
	v_lshl_add_u64 v[8:9], v[8:9], 0, s[14:15]
	global_load_dword v75, v[8:9], off
	v_lshl_add_u64 v[8:9], v[8:9], 0, s[14:15]
	global_load_dword v76, v[8:9], off
	v_lshl_add_u64 v[8:9], v[8:9], 0, s[14:15]
	global_load_dword v77, v[8:9], off
	v_lshl_add_u64 v[8:9], v[8:9], 0, s[14:15]
	global_load_dword v78, v[8:9], off
	v_lshl_add_u64 v[8:9], v[8:9], 0, s[14:15]
	global_load_dword v79, v[8:9], off
	v_lshl_add_u64 v[8:9], v[8:9], 0, s[14:15]
	global_load_dword v80, v[8:9], off
	v_lshl_add_u64 v[8:9], v[8:9], 0, s[14:15]
	global_load_dword v81, v[8:9], off
	v_lshl_add_u64 v[8:9], v[8:9], 0, s[14:15]
	global_load_dword v82, v[8:9], off
	v_lshl_add_u64 v[8:9], v[8:9], 0, s[14:15]
	global_load_dword v83, v[8:9], off
	v_lshl_add_u64 v[8:9], v[8:9], 0, s[14:15]
	global_load_dword v84, v[8:9], off
	v_lshl_add_u64 v[8:9], v[8:9], 0, s[14:15]
	global_load_dword v85, v[8:9], off
	v_lshl_add_u64 v[8:9], v[8:9], 0, s[14:15]
	global_load_dword v86, v[8:9], off
	v_lshl_add_u64 v[8:9], v[8:9], 0, s[14:15]
	global_load_dword v87, v[8:9], off
	v_lshl_add_u64 v[8:9], v[8:9], 0, s[14:15]
	global_load_dword v88, v[8:9], off
	v_lshl_add_u64 v[8:9], v[8:9], 0, s[14:15]
	global_load_dword v89, v[8:9], off
	v_lshl_add_u64 v[8:9], v[8:9], 0, s[14:15]
	global_load_dword v90, v[8:9], off
	v_lshl_add_u64 v[8:9], v[8:9], 0, s[14:15]
	global_load_dword v91, v[8:9], off
	v_lshl_add_u64 v[8:9], v[8:9], 0, s[14:15]
	global_load_dword v92, v[8:9], off
	v_lshl_add_u64 v[8:9], v[8:9], 0, s[14:15]
	global_load_dword v93, v[8:9], off
	v_lshl_add_u64 v[8:9], v[8:9], 0, s[14:15]
	global_load_dword v94, v[8:9], off
	v_lshl_add_u64 v[8:9], v[8:9], 0, s[14:15]
	global_load_dword v95, v[8:9], off
	v_lshl_add_u64 v[8:9], v[8:9], 0, s[14:15]
	global_load_dword v96, v[8:9], off
	v_lshl_add_u64 v[8:9], v[8:9], 0, s[14:15]
	global_load_dword v97, v[8:9], off
	v_lshl_add_u64 v[8:9], v[8:9], 0, s[14:15]
	global_load_dword v98, v[8:9], off
	v_lshl_add_u64 v[8:9], v[8:9], 0, s[14:15]
	global_load_dword v99, v[8:9], off
	v_lshl_add_u64 v[8:9], v[8:9], 0, s[14:15]
	global_load_dword v100, v[8:9], off
	v_lshl_add_u64 v[8:9], v[8:9], 0, s[14:15]
	global_load_dword v101, v[8:9], off
	v_lshl_add_u64 v[8:9], v[8:9], 0, s[14:15]
	global_load_dword v102, v[8:9], off
	v_lshl_add_u64 v[8:9], v[8:9], 0, s[14:15]
	global_load_dword v103, v[8:9], off
	v_lshl_add_u64 v[8:9], v[8:9], 0, s[14:15]
	global_load_dword v104, v[8:9], off
	v_lshl_add_u64 v[8:9], v[8:9], 0, s[14:15]
	global_load_dword v105, v[8:9], off
	v_lshl_add_u64 v[8:9], v[8:9], 0, s[14:15]
	global_load_dword v106, v[8:9], off
	v_lshl_add_u64 v[8:9], v[8:9], 0, s[14:15]
	global_load_dword v107, v[8:9], off
	v_lshl_add_u64 v[8:9], v[8:9], 0, s[14:15]
	global_load_dword v108, v[8:9], off
	v_lshl_add_u64 v[8:9], v[8:9], 0, s[14:15]
	global_load_dword v109, v[8:9], off
	v_lshl_add_u64 v[8:9], v[8:9], 0, s[14:15]
	global_load_dword v110, v[8:9], off
	v_lshl_add_u64 v[8:9], v[8:9], 0, s[14:15]
	global_load_dword v111, v[8:9], off
	v_lshl_add_u64 v[8:9], v[8:9], 0, s[14:15]
	global_load_dword v112, v[8:9], off
	v_lshl_add_u64 v[8:9], v[8:9], 0, s[14:15]
	global_load_dword v113, v[8:9], off
	v_lshl_add_u64 v[8:9], v[8:9], 0, s[14:15]
	global_load_dword v114, v[8:9], off
	v_lshl_add_u64 v[8:9], v[8:9], 0, s[14:15]
	global_load_dword v115, v[8:9], off
	v_lshl_add_u64 v[8:9], v[8:9], 0, s[14:15]
	global_load_dword v116, v[8:9], off
	v_lshl_add_u64 v[8:9], v[8:9], 0, s[14:15]
	global_load_dword v117, v[8:9], off
	v_lshl_add_u64 v[8:9], v[8:9], 0, s[14:15]
	global_load_dword v118, v[8:9], off
	v_lshl_add_u64 v[8:9], v[8:9], 0, s[14:15]
	global_load_dword v119, v[8:9], off
	v_lshl_add_u64 v[8:9], v[8:9], 0, s[14:15]
	global_load_dword v120, v[8:9], off
	v_lshl_add_u64 v[8:9], v[8:9], 0, s[14:15]
	global_load_dword v121, v[8:9], off
	v_lshl_add_u64 v[8:9], v[8:9], 0, s[14:15]
	global_load_dword v122, v[8:9], off
	v_lshl_add_u64 v[8:9], v[8:9], 0, s[14:15]
	global_load_dword v123, v[8:9], off
	v_lshl_add_u64 v[8:9], v[8:9], 0, s[14:15]
	global_load_dword v124, v[8:9], off
	v_lshl_add_u64 v[8:9], v[8:9], 0, s[14:15]
	global_load_dword v125, v[8:9], off
	v_lshl_add_u64 v[8:9], v[8:9], 0, s[14:15]
	global_load_dword v126, v[8:9], off
	v_lshl_add_u64 v[8:9], v[8:9], 0, s[14:15]
	global_load_dword v127, v[8:9], off
	v_lshl_add_u64 v[8:9], v[8:9], 0, s[14:15]
	global_load_dword v128, v[8:9], off
	v_lshl_add_u64 v[8:9], v[8:9], 0, s[14:15]
	global_load_dword v129, v[8:9], off
	v_lshl_add_u64 v[8:9], v[8:9], 0, s[14:15]
	global_load_dword v130, v[8:9], off
	v_lshl_add_u64 v[8:9], v[8:9], 0, s[14:15]
	global_load_dword v131, v[8:9], off
	v_lshl_add_u64 v[8:9], v[8:9], 0, s[14:15]
	global_load_dword v132, v[8:9], off
	v_lshl_add_u64 v[8:9], v[8:9], 0, s[14:15]
	global_load_dword v133, v[8:9], off
	v_lshl_add_u64 v[8:9], v[8:9], 0, s[14:15]
	global_load_dword v134, v[8:9], off
	v_lshl_add_u64 v[8:9], v[8:9], 0, s[14:15]
	global_load_dword v135, v[8:9], off
	v_lshl_add_u64 v[8:9], v[8:9], 0, s[14:15]
	global_load_dword v136, v[8:9], off
	v_lshl_add_u64 v[8:9], v[8:9], 0, s[14:15]
	global_load_dword v137, v[8:9], off
	v_lshl_add_u64 v[8:9], v[8:9], 0, s[14:15]
	global_load_dword v138, v[8:9], off
	v_lshl_add_u64 v[8:9], v[8:9], 0, s[14:15]
	global_load_dword v139, v[8:9], off
	v_lshl_add_u64 v[8:9], v[8:9], 0, s[14:15]
	global_load_dword v140, v[8:9], off
	v_lshl_add_u64 v[8:9], v[8:9], 0, s[14:15]
	global_load_dword v141, v[8:9], off
	v_lshl_add_u64 v[8:9], v[8:9], 0, s[14:15]
	global_load_dword v142, v[8:9], off
	v_lshl_add_u64 v[8:9], v[8:9], 0, s[14:15]
	global_load_dword v143, v[8:9], off
	v_lshl_add_u64 v[8:9], v[8:9], 0, s[14:15]
	global_load_dword v144, v[8:9], off
	v_lshl_add_u64 v[8:9], v[8:9], 0, s[14:15]
	global_load_dword v145, v[8:9], off
	v_lshl_add_u64 v[8:9], v[8:9], 0, s[14:15]
	global_load_dword v146, v[8:9], off
	v_lshl_add_u64 v[8:9], v[8:9], 0, s[14:15]
	global_load_dword v147, v[8:9], off
	v_lshl_add_u64 v[8:9], v[8:9], 0, s[14:15]
	global_load_dword v148, v[8:9], off
	v_lshl_add_u64 v[8:9], v[8:9], 0, s[14:15]
	global_load_dword v149, v[8:9], off
	v_lshl_add_u64 v[8:9], v[8:9], 0, s[14:15]
	global_load_dword v150, v[8:9], off
	v_lshl_add_u64 v[8:9], v[8:9], 0, s[14:15]
	global_load_dword v151, v[8:9], off
	v_lshl_add_u64 v[8:9], v[8:9], 0, s[14:15]
	global_load_dword v152, v[8:9], off
	v_lshl_add_u64 v[8:9], v[8:9], 0, s[14:15]
	global_load_dword v153, v[8:9], off
	v_lshl_add_u64 v[8:9], v[8:9], 0, s[14:15]
	global_load_dword v154, v[8:9], off
	v_lshl_add_u64 v[8:9], v[8:9], 0, s[14:15]
	global_load_dword v155, v[8:9], off
	v_lshl_add_u64 v[8:9], v[8:9], 0, s[14:15]
	global_load_dword v156, v[8:9], off
	v_lshl_add_u64 v[8:9], v[8:9], 0, s[14:15]
	global_load_dword v157, v[8:9], off
	v_lshl_add_u64 v[8:9], v[8:9], 0, s[14:15]
	global_load_dword v158, v[8:9], off
	v_lshl_add_u64 v[8:9], v[8:9], 0, s[14:15]
	global_load_dword v159, v[8:9], off
	v_lshl_add_u64 v[8:9], v[8:9], 0, s[14:15]
	global_load_dword v164, v[8:9], off
	v_lshl_add_u64 v[8:9], v[8:9], 0, s[14:15]
	global_load_dword v165, v[8:9], off
	s_mov_b32 s3, 64
	s_and_b64 vcc, exec, vcc
	s_waitcnt vmcnt(63)
	v_readlane_b32 s16, v3, 0
	v_readlane_b32 s17, v11, 0
	v_readlane_b32 s18, v3, 1
	v_readlane_b32 s19, v11, 1
	v_readlane_b32 s20, v3, 2
	v_readlane_b32 s21, v11, 2
	v_fma_f32 v6, v32, s16, v6
	v_fma_f32 v7, v32, s17, v7
	v_readlane_b32 s22, v3, 3
	v_readlane_b32 s23, v11, 3
	v_fma_f32 v6, v33, s18, v6
	v_fma_f32 v7, v33, s19, v7
	v_readlane_b32 s16, v3, 4
	v_readlane_b32 s17, v11, 4
	v_fma_f32 v6, v34, s20, v6
	v_fma_f32 v7, v34, s21, v7
	v_readlane_b32 s18, v3, 5
	v_readlane_b32 s19, v11, 5
	v_fma_f32 v6, v35, s22, v6
	v_fma_f32 v7, v35, s23, v7
	v_readlane_b32 s20, v3, 6
	v_readlane_b32 s21, v11, 6
	v_fma_f32 v6, v36, s16, v6
	v_fma_f32 v7, v36, s17, v7
	v_readlane_b32 s22, v3, 7
	v_readlane_b32 s23, v11, 7
	v_fma_f32 v6, v37, s18, v6
	v_fma_f32 v7, v37, s19, v7
	v_readlane_b32 s16, v3, 8
	v_readlane_b32 s17, v11, 8
	v_fma_f32 v6, v38, s20, v6
	v_fma_f32 v7, v38, s21, v7
	v_readlane_b32 s18, v3, 9
	v_readlane_b32 s19, v11, 9
	v_fma_f32 v6, v39, s22, v6
	v_fma_f32 v7, v39, s23, v7
	v_readlane_b32 s20, v3, 10
	v_readlane_b32 s21, v11, 10
	v_fma_f32 v6, v40, s16, v6
	v_fma_f32 v7, v40, s17, v7
	v_readlane_b32 s22, v3, 11
	v_readlane_b32 s23, v11, 11
	v_fma_f32 v6, v41, s18, v6
	v_fma_f32 v7, v41, s19, v7
	v_readlane_b32 s16, v3, 12
	v_readlane_b32 s17, v11, 12
	v_fma_f32 v6, v42, s20, v6
	v_fma_f32 v7, v42, s21, v7
	v_readlane_b32 s18, v3, 13
	v_readlane_b32 s19, v11, 13
	v_fma_f32 v6, v43, s22, v6
	v_fma_f32 v7, v43, s23, v7
	v_readlane_b32 s20, v3, 14
	v_readlane_b32 s21, v11, 14
	v_fma_f32 v6, v44, s16, v6
	v_fma_f32 v7, v44, s17, v7
	v_readlane_b32 s22, v3, 15
	v_readlane_b32 s23, v11, 15
	v_fma_f32 v6, v45, s18, v6
	v_fma_f32 v7, v45, s19, v7
	v_readlane_b32 s16, v3, 16
	v_readlane_b32 s17, v11, 16
	v_fma_f32 v6, v46, s20, v6
	v_fma_f32 v7, v46, s21, v7
	v_readlane_b32 s18, v3, 17
	v_readlane_b32 s19, v11, 17
	v_fma_f32 v6, v47, s22, v6
	v_fma_f32 v7, v47, s23, v7
	v_readlane_b32 s20, v3, 18
	v_readlane_b32 s21, v11, 18
	v_fma_f32 v6, v48, s16, v6
	v_fma_f32 v7, v48, s17, v7
	v_readlane_b32 s22, v3, 19
	v_readlane_b32 s23, v11, 19
	v_fma_f32 v6, v49, s18, v6
	v_fma_f32 v7, v49, s19, v7
	v_readlane_b32 s16, v3, 20
	v_readlane_b32 s17, v11, 20
	v_fma_f32 v6, v50, s20, v6
	v_fma_f32 v7, v50, s21, v7
	v_readlane_b32 s18, v3, 21
	v_readlane_b32 s19, v11, 21
	v_fma_f32 v6, v51, s22, v6
	v_fma_f32 v7, v51, s23, v7
	v_readlane_b32 s20, v3, 22
	v_readlane_b32 s21, v11, 22
	v_fma_f32 v6, v52, s16, v6
	v_fma_f32 v7, v52, s17, v7
	v_readlane_b32 s22, v3, 23
	v_readlane_b32 s23, v11, 23
	v_fma_f32 v6, v53, s18, v6
	v_fma_f32 v7, v53, s19, v7
	v_readlane_b32 s16, v3, 24
	v_readlane_b32 s17, v11, 24
	v_fma_f32 v6, v54, s20, v6
	v_fma_f32 v7, v54, s21, v7
	v_readlane_b32 s18, v3, 25
	v_readlane_b32 s19, v11, 25
	v_fma_f32 v6, v55, s22, v6
	v_fma_f32 v7, v55, s23, v7
	v_readlane_b32 s20, v3, 26
	v_readlane_b32 s21, v11, 26
	v_fma_f32 v6, v58, s16, v6
	v_fma_f32 v7, v58, s17, v7
	v_readlane_b32 s22, v3, 27
	v_readlane_b32 s23, v11, 27
	v_fma_f32 v6, v59, s18, v6
	v_fma_f32 v7, v59, s19, v7
	v_readlane_b32 s16, v3, 28
	v_readlane_b32 s17, v11, 28
	v_fma_f32 v6, v60, s20, v6
	v_fma_f32 v7, v60, s21, v7
	v_readlane_b32 s18, v3, 29
	v_readlane_b32 s19, v11, 29
	v_fma_f32 v6, v61, s22, v6
	v_fma_f32 v7, v61, s23, v7
	v_readlane_b32 s20, v3, 30
	v_readlane_b32 s21, v11, 30
	v_fma_f32 v6, v62, s16, v6
	v_fma_f32 v7, v62, s17, v7
	v_readlane_b32 s22, v3, 31
	v_readlane_b32 s23, v11, 31
	v_fma_f32 v6, v63, s18, v6
	v_fma_f32 v7, v63, s19, v7
	v_readlane_b32 s16, v3, 32
	v_readlane_b32 s17, v11, 32
	v_fma_f32 v6, v64, s20, v6
	v_fma_f32 v7, v64, s21, v7
	v_readlane_b32 s18, v3, 33
	v_readlane_b32 s19, v11, 33
	v_fma_f32 v6, v65, s22, v6
	v_fma_f32 v7, v65, s23, v7
	v_readlane_b32 s20, v3, 34
	v_readlane_b32 s21, v11, 34
	v_fma_f32 v6, v66, s16, v6
	v_fma_f32 v7, v66, s17, v7
	v_readlane_b32 s22, v3, 35
	v_readlane_b32 s23, v11, 35
	v_fma_f32 v6, v67, s18, v6
	v_fma_f32 v7, v67, s19, v7
	v_readlane_b32 s16, v3, 36
	v_readlane_b32 s17, v11, 36
	v_fma_f32 v6, v68, s20, v6
	v_fma_f32 v7, v68, s21, v7
	v_readlane_b32 s18, v3, 37
	v_readlane_b32 s19, v11, 37
	v_fma_f32 v6, v69, s22, v6
	v_fma_f32 v7, v69, s23, v7
	v_readlane_b32 s20, v3, 38
	v_readlane_b32 s21, v11, 38
	v_fma_f32 v6, v70, s16, v6
	v_fma_f32 v7, v70, s17, v7
	v_readlane_b32 s22, v3, 39
	v_readlane_b32 s23, v11, 39
	v_fma_f32 v6, v71, s18, v6
	v_fma_f32 v7, v71, s19, v7
	v_readlane_b32 s16, v3, 40
	v_readlane_b32 s17, v11, 40
	v_fma_f32 v6, v72, s20, v6
	v_fma_f32 v7, v72, s21, v7
	v_readlane_b32 s18, v3, 41
	v_readlane_b32 s19, v11, 41
	v_fma_f32 v6, v73, s22, v6
	v_fma_f32 v7, v73, s23, v7
	v_readlane_b32 s20, v3, 42
	v_readlane_b32 s21, v11, 42
	v_fma_f32 v6, v74, s16, v6
	v_fma_f32 v7, v74, s17, v7
	v_readlane_b32 s22, v3, 43
	v_readlane_b32 s23, v11, 43
	v_fma_f32 v6, v75, s18, v6
	v_fma_f32 v7, v75, s19, v7
	v_readlane_b32 s16, v3, 44
	v_readlane_b32 s17, v11, 44
	v_fma_f32 v6, v76, s20, v6
	v_fma_f32 v7, v76, s21, v7
	v_readlane_b32 s18, v3, 45
	v_readlane_b32 s19, v11, 45
	v_fma_f32 v6, v77, s22, v6
	v_fma_f32 v7, v77, s23, v7
	v_readlane_b32 s20, v3, 46
	v_readlane_b32 s21, v11, 46
	v_fma_f32 v6, v78, s16, v6
	v_fma_f32 v7, v78, s17, v7
	v_readlane_b32 s22, v3, 47
	v_readlane_b32 s23, v11, 47
	v_fma_f32 v6, v79, s18, v6
	v_fma_f32 v7, v79, s19, v7
	v_readlane_b32 s16, v3, 48
	v_readlane_b32 s17, v11, 48
	v_fma_f32 v6, v80, s20, v6
	v_fma_f32 v7, v80, s21, v7
	v_readlane_b32 s18, v3, 49
	v_readlane_b32 s19, v11, 49
	v_fma_f32 v6, v81, s22, v6
	v_fma_f32 v7, v81, s23, v7
	v_readlane_b32 s20, v3, 50
	v_readlane_b32 s21, v11, 50
	v_fma_f32 v6, v82, s16, v6
	v_fma_f32 v7, v82, s17, v7
	v_readlane_b32 s22, v3, 51
	v_readlane_b32 s23, v11, 51
	v_fma_f32 v6, v83, s18, v6
	v_fma_f32 v7, v83, s19, v7
	v_readlane_b32 s16, v3, 52
	v_readlane_b32 s17, v11, 52
	v_fma_f32 v6, v84, s20, v6
	v_fma_f32 v7, v84, s21, v7
	v_readlane_b32 s18, v3, 53
	v_readlane_b32 s19, v11, 53
	v_fma_f32 v6, v85, s22, v6
	v_fma_f32 v7, v85, s23, v7
	v_readlane_b32 s20, v3, 54
	v_readlane_b32 s21, v11, 54
	v_fma_f32 v6, v86, s16, v6
	v_fma_f32 v7, v86, s17, v7
	v_readlane_b32 s22, v3, 55
	v_readlane_b32 s23, v11, 55
	v_fma_f32 v6, v87, s18, v6
	v_fma_f32 v7, v87, s19, v7
	v_readlane_b32 s16, v3, 56
	v_readlane_b32 s17, v11, 56
	v_fma_f32 v6, v88, s20, v6
	v_fma_f32 v7, v88, s21, v7
	v_readlane_b32 s18, v3, 57
	v_readlane_b32 s19, v11, 57
	v_fma_f32 v6, v89, s22, v6
	v_fma_f32 v7, v89, s23, v7
	v_readlane_b32 s20, v3, 58
	v_readlane_b32 s21, v11, 58
	v_fma_f32 v6, v90, s16, v6
	v_fma_f32 v7, v90, s17, v7
	v_readlane_b32 s22, v3, 59
	v_readlane_b32 s23, v11, 59
	v_fma_f32 v6, v91, s18, v6
	v_fma_f32 v7, v91, s19, v7
	v_readlane_b32 s16, v3, 60
	v_readlane_b32 s17, v11, 60
	v_fma_f32 v6, v92, s20, v6
	v_fma_f32 v7, v92, s21, v7
	v_readlane_b32 s18, v3, 61
	v_readlane_b32 s19, v11, 61
	v_fma_f32 v6, v93, s22, v6
	v_fma_f32 v7, v93, s23, v7
	v_readlane_b32 s20, v3, 62
	v_readlane_b32 s21, v11, 62
	v_fma_f32 v6, v94, s16, v6
	v_fma_f32 v7, v94, s17, v7
	v_readlane_b32 s22, v3, 63
	v_readlane_b32 s23, v11, 63
	v_fma_f32 v6, v95, s18, v6
	v_fma_f32 v7, v95, s19, v7
	v_readlane_b32 s16, v28, 0
	v_readlane_b32 s17, v29, 0
	v_fma_f32 v6, v96, s20, v6
	v_fma_f32 v7, v96, s21, v7
	v_readlane_b32 s18, v28, 1
	v_readlane_b32 s19, v29, 1
	v_fma_f32 v6, v97, s22, v6
	v_fma_f32 v7, v97, s23, v7
	v_readlane_b32 s20, v28, 2
	v_readlane_b32 s21, v29, 2
	v_fma_f32 v6, v98, s16, v6
	v_fma_f32 v7, v98, s17, v7
	v_readlane_b32 s22, v28, 3
	v_readlane_b32 s23, v29, 3
	s_waitcnt vmcnt(62)
	v_fma_f32 v6, v99, s18, v6
	v_fma_f32 v7, v99, s19, v7
	v_readlane_b32 s16, v28, 4
	v_readlane_b32 s17, v29, 4
	s_waitcnt vmcnt(61)
	v_fma_f32 v6, v100, s20, v6
	v_fma_f32 v7, v100, s21, v7
	v_readlane_b32 s18, v28, 5
	v_readlane_b32 s19, v29, 5
	s_waitcnt vmcnt(60)
	v_fma_f32 v6, v101, s22, v6
	v_fma_f32 v7, v101, s23, v7
	v_readlane_b32 s20, v28, 6
	v_readlane_b32 s21, v29, 6
	s_waitcnt vmcnt(59)
	v_fma_f32 v6, v102, s16, v6
	v_fma_f32 v7, v102, s17, v7
	v_readlane_b32 s22, v28, 7
	v_readlane_b32 s23, v29, 7
	s_waitcnt vmcnt(58)
	v_fma_f32 v6, v103, s18, v6
	v_fma_f32 v7, v103, s19, v7
	v_readlane_b32 s16, v28, 8
	v_readlane_b32 s17, v29, 8
	s_waitcnt vmcnt(57)
	v_fma_f32 v6, v104, s20, v6
	v_fma_f32 v7, v104, s21, v7
	v_readlane_b32 s18, v28, 9
	v_readlane_b32 s19, v29, 9
	s_waitcnt vmcnt(56)
	v_fma_f32 v6, v105, s22, v6
	v_fma_f32 v7, v105, s23, v7
	v_readlane_b32 s20, v28, 10
	v_readlane_b32 s21, v29, 10
	s_waitcnt vmcnt(55)
	v_fma_f32 v6, v106, s16, v6
	v_fma_f32 v7, v106, s17, v7
	v_readlane_b32 s22, v28, 11
	v_readlane_b32 s23, v29, 11
	s_waitcnt vmcnt(54)
	v_fma_f32 v6, v107, s18, v6
	v_fma_f32 v7, v107, s19, v7
	v_readlane_b32 s16, v28, 12
	v_readlane_b32 s17, v29, 12
	s_waitcnt vmcnt(53)
	v_fma_f32 v6, v108, s20, v6
	v_fma_f32 v7, v108, s21, v7
	v_readlane_b32 s18, v28, 13
	v_readlane_b32 s19, v29, 13
	s_waitcnt vmcnt(52)
	v_fma_f32 v6, v109, s22, v6
	v_fma_f32 v7, v109, s23, v7
	v_readlane_b32 s20, v28, 14
	v_readlane_b32 s21, v29, 14
	s_waitcnt vmcnt(51)
	v_fma_f32 v6, v110, s16, v6
	v_fma_f32 v7, v110, s17, v7
	v_readlane_b32 s22, v28, 15
	v_readlane_b32 s23, v29, 15
	s_waitcnt vmcnt(50)
	v_fma_f32 v6, v111, s18, v6
	v_fma_f32 v7, v111, s19, v7
	v_readlane_b32 s16, v28, 16
	v_readlane_b32 s17, v29, 16
	s_waitcnt vmcnt(49)
	v_fma_f32 v6, v112, s20, v6
	v_fma_f32 v7, v112, s21, v7
	v_readlane_b32 s18, v28, 17
	v_readlane_b32 s19, v29, 17
	s_waitcnt vmcnt(48)
	v_fma_f32 v6, v113, s22, v6
	v_fma_f32 v7, v113, s23, v7
	v_readlane_b32 s20, v28, 18
	v_readlane_b32 s21, v29, 18
	s_waitcnt vmcnt(47)
	v_fma_f32 v6, v114, s16, v6
	v_fma_f32 v7, v114, s17, v7
	v_readlane_b32 s22, v28, 19
	v_readlane_b32 s23, v29, 19
	s_waitcnt vmcnt(46)
	v_fma_f32 v6, v115, s18, v6
	v_fma_f32 v7, v115, s19, v7
	v_readlane_b32 s16, v28, 20
	v_readlane_b32 s17, v29, 20
	s_waitcnt vmcnt(45)
	v_fma_f32 v6, v116, s20, v6
	v_fma_f32 v7, v116, s21, v7
	v_readlane_b32 s18, v28, 21
	v_readlane_b32 s19, v29, 21
	s_waitcnt vmcnt(44)
	v_fma_f32 v6, v117, s22, v6
	v_fma_f32 v7, v117, s23, v7
	v_readlane_b32 s20, v28, 22
	v_readlane_b32 s21, v29, 22
	s_waitcnt vmcnt(43)
	v_fma_f32 v6, v118, s16, v6
	v_fma_f32 v7, v118, s17, v7
	v_readlane_b32 s22, v28, 23
	v_readlane_b32 s23, v29, 23
	s_waitcnt vmcnt(42)
	v_fma_f32 v6, v119, s18, v6
	v_fma_f32 v7, v119, s19, v7
	v_readlane_b32 s16, v28, 24
	v_readlane_b32 s17, v29, 24
	s_waitcnt vmcnt(41)
	v_fma_f32 v6, v120, s20, v6
	v_fma_f32 v7, v120, s21, v7
	v_readlane_b32 s18, v28, 25
	v_readlane_b32 s19, v29, 25
	s_waitcnt vmcnt(40)
	v_fma_f32 v6, v121, s22, v6
	v_fma_f32 v7, v121, s23, v7
	v_readlane_b32 s20, v28, 26
	v_readlane_b32 s21, v29, 26
	s_waitcnt vmcnt(39)
	v_fma_f32 v6, v122, s16, v6
	v_fma_f32 v7, v122, s17, v7
	v_readlane_b32 s22, v28, 27
	v_readlane_b32 s23, v29, 27
	s_waitcnt vmcnt(38)
	v_fma_f32 v6, v123, s18, v6
	v_fma_f32 v7, v123, s19, v7
	v_readlane_b32 s16, v28, 28
	v_readlane_b32 s17, v29, 28
	s_waitcnt vmcnt(37)
	v_fma_f32 v6, v124, s20, v6
	v_fma_f32 v7, v124, s21, v7
	v_readlane_b32 s18, v28, 29
	v_readlane_b32 s19, v29, 29
	s_waitcnt vmcnt(36)
	v_fma_f32 v6, v125, s22, v6
	v_fma_f32 v7, v125, s23, v7
	v_readlane_b32 s20, v28, 30
	v_readlane_b32 s21, v29, 30
	s_waitcnt vmcnt(35)
	v_fma_f32 v6, v126, s16, v6
	v_fma_f32 v7, v126, s17, v7
	v_readlane_b32 s22, v28, 31
	v_readlane_b32 s23, v29, 31
	s_waitcnt vmcnt(34)
	v_fma_f32 v6, v127, s18, v6
	v_fma_f32 v7, v127, s19, v7
	v_readlane_b32 s16, v28, 32
	v_readlane_b32 s17, v29, 32
	s_waitcnt vmcnt(33)
	v_fma_f32 v6, v128, s20, v6
	v_fma_f32 v7, v128, s21, v7
	v_readlane_b32 s18, v28, 33
	v_readlane_b32 s19, v29, 33
	s_waitcnt vmcnt(32)
	v_fma_f32 v6, v129, s22, v6
	v_fma_f32 v7, v129, s23, v7
	v_readlane_b32 s20, v28, 34
	v_readlane_b32 s21, v29, 34
	s_waitcnt vmcnt(31)
	v_fma_f32 v6, v130, s16, v6
	v_fma_f32 v7, v130, s17, v7
	v_readlane_b32 s22, v28, 35
	v_readlane_b32 s23, v29, 35
	s_waitcnt vmcnt(30)
	v_fma_f32 v6, v131, s18, v6
	v_fma_f32 v7, v131, s19, v7
	v_readlane_b32 s16, v28, 36
	v_readlane_b32 s17, v29, 36
	s_waitcnt vmcnt(29)
	v_fma_f32 v6, v132, s20, v6
	v_fma_f32 v7, v132, s21, v7
	v_readlane_b32 s18, v28, 37
	v_readlane_b32 s19, v29, 37
	s_waitcnt vmcnt(28)
	v_fma_f32 v6, v133, s22, v6
	v_fma_f32 v7, v133, s23, v7
	v_readlane_b32 s20, v28, 38
	v_readlane_b32 s21, v29, 38
	s_waitcnt vmcnt(27)
	v_fma_f32 v6, v134, s16, v6
	v_fma_f32 v7, v134, s17, v7
	v_readlane_b32 s22, v28, 39
	v_readlane_b32 s23, v29, 39
	s_waitcnt vmcnt(26)
	v_fma_f32 v6, v135, s18, v6
	v_fma_f32 v7, v135, s19, v7
	v_readlane_b32 s16, v28, 40
	v_readlane_b32 s17, v29, 40
	s_waitcnt vmcnt(25)
	v_fma_f32 v6, v136, s20, v6
	v_fma_f32 v7, v136, s21, v7
	v_readlane_b32 s18, v28, 41
	v_readlane_b32 s19, v29, 41
	s_waitcnt vmcnt(24)
	v_fma_f32 v6, v137, s22, v6
	v_fma_f32 v7, v137, s23, v7
	v_readlane_b32 s20, v28, 42
	v_readlane_b32 s21, v29, 42
	s_waitcnt vmcnt(23)
	v_fma_f32 v6, v138, s16, v6
	v_fma_f32 v7, v138, s17, v7
	v_readlane_b32 s22, v28, 43
	v_readlane_b32 s23, v29, 43
	s_waitcnt vmcnt(22)
	v_fma_f32 v6, v139, s18, v6
	v_fma_f32 v7, v139, s19, v7
	v_readlane_b32 s16, v28, 44
	v_readlane_b32 s17, v29, 44
	s_waitcnt vmcnt(21)
	v_fma_f32 v6, v140, s20, v6
	v_fma_f32 v7, v140, s21, v7
	v_readlane_b32 s18, v28, 45
	v_readlane_b32 s19, v29, 45
	s_waitcnt vmcnt(20)
	v_fma_f32 v6, v141, s22, v6
	v_fma_f32 v7, v141, s23, v7
	v_readlane_b32 s20, v28, 46
	v_readlane_b32 s21, v29, 46
	s_waitcnt vmcnt(19)
	v_fma_f32 v6, v142, s16, v6
	v_fma_f32 v7, v142, s17, v7
	v_readlane_b32 s22, v28, 47
	v_readlane_b32 s23, v29, 47
	s_waitcnt vmcnt(18)
	v_fma_f32 v6, v143, s18, v6
	v_fma_f32 v7, v143, s19, v7
	v_readlane_b32 s16, v28, 48
	v_readlane_b32 s17, v29, 48
	s_waitcnt vmcnt(17)
	v_fma_f32 v6, v144, s20, v6
	v_fma_f32 v7, v144, s21, v7
	v_readlane_b32 s18, v28, 49
	v_readlane_b32 s19, v29, 49
	s_waitcnt vmcnt(16)
	v_fma_f32 v6, v145, s22, v6
	v_fma_f32 v7, v145, s23, v7
	v_readlane_b32 s20, v28, 50
	v_readlane_b32 s21, v29, 50
	s_waitcnt vmcnt(15)
	v_fma_f32 v6, v146, s16, v6
	v_fma_f32 v7, v146, s17, v7
	v_readlane_b32 s22, v28, 51
	v_readlane_b32 s23, v29, 51
	s_waitcnt vmcnt(14)
	v_fma_f32 v6, v147, s18, v6
	v_fma_f32 v7, v147, s19, v7
	v_readlane_b32 s16, v28, 52
	v_readlane_b32 s17, v29, 52
	s_waitcnt vmcnt(13)
	v_fma_f32 v6, v148, s20, v6
	v_fma_f32 v7, v148, s21, v7
	v_readlane_b32 s18, v28, 53
	v_readlane_b32 s19, v29, 53
	s_waitcnt vmcnt(12)
	v_fma_f32 v6, v149, s22, v6
	v_fma_f32 v7, v149, s23, v7
	v_readlane_b32 s20, v28, 54
	v_readlane_b32 s21, v29, 54
	s_waitcnt vmcnt(11)
	v_fma_f32 v6, v150, s16, v6
	v_fma_f32 v7, v150, s17, v7
	v_readlane_b32 s22, v28, 55
	v_readlane_b32 s23, v29, 55
	s_waitcnt vmcnt(10)
	v_fma_f32 v6, v151, s18, v6
	v_fma_f32 v7, v151, s19, v7
	v_readlane_b32 s16, v28, 56
	v_readlane_b32 s17, v29, 56
	s_waitcnt vmcnt(9)
	v_fma_f32 v6, v152, s20, v6
	v_fma_f32 v7, v152, s21, v7
	v_readlane_b32 s18, v28, 57
	v_readlane_b32 s19, v29, 57
	s_waitcnt vmcnt(8)
	v_fma_f32 v6, v153, s22, v6
	v_fma_f32 v7, v153, s23, v7
	v_readlane_b32 s20, v28, 58
	v_readlane_b32 s21, v29, 58
	s_waitcnt vmcnt(7)
	v_fma_f32 v6, v154, s16, v6
	v_fma_f32 v7, v154, s17, v7
	v_readlane_b32 s22, v28, 59
	v_readlane_b32 s23, v29, 59
	s_waitcnt vmcnt(6)
	v_fma_f32 v6, v155, s18, v6
	v_fma_f32 v7, v155, s19, v7
	v_readlane_b32 s16, v28, 60
	v_readlane_b32 s17, v29, 60
	s_waitcnt vmcnt(5)
	v_fma_f32 v6, v156, s20, v6
	v_fma_f32 v7, v156, s21, v7
	v_readlane_b32 s18, v28, 61
	v_readlane_b32 s19, v29, 61
	s_waitcnt vmcnt(4)
	v_fma_f32 v6, v157, s22, v6
	v_fma_f32 v7, v157, s23, v7
	v_readlane_b32 s20, v28, 62
	v_readlane_b32 s21, v29, 62
	s_waitcnt vmcnt(3)
	v_fma_f32 v6, v158, s16, v6
	v_fma_f32 v7, v158, s17, v7
	v_readlane_b32 s22, v28, 63
	v_readlane_b32 s23, v29, 63
	s_waitcnt vmcnt(2)
	v_fma_f32 v6, v159, s18, v6
	v_fma_f32 v7, v159, s19, v7
	s_waitcnt vmcnt(1)
	v_fma_f32 v6, v164, s20, v6
	v_fma_f32 v7, v164, s21, v7
	s_waitcnt vmcnt(0)
	v_fma_f32 v6, v165, s22, v6
	v_fma_f32 v7, v165, s23, v7
	s_mov_b64 s[0:1], 0
	v_readlane_b32 s2, v254, 51
	v_readlane_b32 s3, v254, 52
	s_and_saveexec_b64 s[0:1], s[2:3]
	s_cbranch_execz .LBB0_634
	v_ashrrev_i32_e32 v3, 31, v2
	v_readlane_b32 s4, v250, 30
	v_lshlrev_b64 v[2:3], 2, v[2:3]
	v_readlane_b32 s5, v250, 31
	s_nop 1
	v_lshl_add_u64 v[4:5], s[4:5], 0, v[2:3]
	v_readlane_b32 s4, v249, 18
	v_readlane_b32 s5, v249, 19
	s_nop 1
	v_lshl_add_u64 v[2:3], s[4:5], 0, v[2:3]
	global_atomic_add_f32 v[2:3], v6, off
	global_atomic_add_f32 v[4:5], v7, off
	s_branch .LBB0_634

.LBB0_668:
	v_cndmask_b32_e64 v0, 0, 1, s[0:1]
	v_cmp_ne_u32_e32 vcc, 1, v0
	v_or_b32_e32 v0, s11, v10
	v_lshlrev_b64 v[8:9], 2, v[0:1]
	s_lshl_b32 s90, s11, 10
	v_lshl_add_u64 v[12:13], s[2:3], 0, v[8:9]
	v_lshl_add_u64 v[8:9], s[4:5], 0, v[8:9]
	global_load_dword v3, v[12:13], off
	global_load_dword v11, v[8:9], off
	global_load_dword v28, v[12:13], off offset:256
	global_load_dword v29, v[8:9], off offset:256
	v_lshl_add_u64 v[8:9], s[90:91], 2, v[4:5]
	s_mov_b32 s14, 0x1000
	s_mov_b32 s15, 0
	global_load_dword v32, v[8:9], off
	v_lshl_add_u64 v[8:9], v[8:9], 0, s[14:15]
	global_load_dword v33, v[8:9], off
	v_lshl_add_u64 v[8:9], v[8:9], 0, s[14:15]
	global_load_dword v34, v[8:9], off
	v_lshl_add_u64 v[8:9], v[8:9], 0, s[14:15]
	global_load_dword v35, v[8:9], off
	v_lshl_add_u64 v[8:9], v[8:9], 0, s[14:15]
	global_load_dword v36, v[8:9], off
	v_lshl_add_u64 v[8:9], v[8:9], 0, s[14:15]
	global_load_dword v37, v[8:9], off
	v_lshl_add_u64 v[8:9], v[8:9], 0, s[14:15]
	global_load_dword v38, v[8:9], off
	v_lshl_add_u64 v[8:9], v[8:9], 0, s[14:15]
	global_load_dword v39, v[8:9], off
	v_lshl_add_u64 v[8:9], v[8:9], 0, s[14:15]
	global_load_dword v40, v[8:9], off
	v_lshl_add_u64 v[8:9], v[8:9], 0, s[14:15]
	global_load_dword v41, v[8:9], off
	v_lshl_add_u64 v[8:9], v[8:9], 0, s[14:15]
	global_load_dword v42, v[8:9], off
	v_lshl_add_u64 v[8:9], v[8:9], 0, s[14:15]
	global_load_dword v43, v[8:9], off
	v_lshl_add_u64 v[8:9], v[8:9], 0, s[14:15]
	global_load_dword v44, v[8:9], off
	v_lshl_add_u64 v[8:9], v[8:9], 0, s[14:15]
	global_load_dword v45, v[8:9], off
	v_lshl_add_u64 v[8:9], v[8:9], 0, s[14:15]
	global_load_dword v46, v[8:9], off
	v_lshl_add_u64 v[8:9], v[8:9], 0, s[14:15]
	global_load_dword v47, v[8:9], off
	v_lshl_add_u64 v[8:9], v[8:9], 0, s[14:15]
	global_load_dword v48, v[8:9], off
	v_lshl_add_u64 v[8:9], v[8:9], 0, s[14:15]
	global_load_dword v49, v[8:9], off
	v_lshl_add_u64 v[8:9], v[8:9], 0, s[14:15]
	global_load_dword v50, v[8:9], off
	v_lshl_add_u64 v[8:9], v[8:9], 0, s[14:15]
	global_load_dword v51, v[8:9], off
	v_lshl_add_u64 v[8:9], v[8:9], 0, s[14:15]
	global_load_dword v52, v[8:9], off
	v_lshl_add_u64 v[8:9], v[8:9], 0, s[14:15]
	global_load_dword v53, v[8:9], off
	v_lshl_add_u64 v[8:9], v[8:9], 0, s[14:15]
	global_load_dword v54, v[8:9], off
	v_lshl_add_u64 v[8:9], v[8:9], 0, s[14:15]
	global_load_dword v55, v[8:9], off
	v_lshl_add_u64 v[8:9], v[8:9], 0, s[14:15]
	global_load_dword v58, v[8:9], off
	v_lshl_add_u64 v[8:9], v[8:9], 0, s[14:15]
	global_load_dword v59, v[8:9], off
	v_lshl_add_u64 v[8:9], v[8:9], 0, s[14:15]
	global_load_dword v60, v[8:9], off
	v_lshl_add_u64 v[8:9], v[8:9], 0, s[14:15]
	global_load_dword v61, v[8:9], off
	v_lshl_add_u64 v[8:9], v[8:9], 0, s[14:15]
	global_load_dword v62, v[8:9], off
	v_lshl_add_u64 v[8:9], v[8:9], 0, s[14:15]
	global_load_dword v63, v[8:9], off
	v_lshl_add_u64 v[8:9], v[8:9], 0, s[14:15]
	global_load_dword v64, v[8:9], off
	v_lshl_add_u64 v[8:9], v[8:9], 0, s[14:15]
	global_load_dword v65, v[8:9], off
	v_lshl_add_u64 v[8:9], v[8:9], 0, s[14:15]
	global_load_dword v66, v[8:9], off
	v_lshl_add_u64 v[8:9], v[8:9], 0, s[14:15]
	global_load_dword v67, v[8:9], off
	v_lshl_add_u64 v[8:9], v[8:9], 0, s[14:15]
	global_load_dword v68, v[8:9], off
	v_lshl_add_u64 v[8:9], v[8:9], 0, s[14:15]
	global_load_dword v69, v[8:9], off
	v_lshl_add_u64 v[8:9], v[8:9], 0, s[14:15]
	global_load_dword v70, v[8:9], off
	v_lshl_add_u64 v[8:9], v[8:9], 0, s[14:15]
	global_load_dword v71, v[8:9], off
	v_lshl_add_u64 v[8:9], v[8:9], 0, s[14:15]
	global_load_dword v72, v[8:9], off
	v_lshl_add_u64 v[8:9], v[8:9], 0, s[14:15]
	global_load_dword v73, v[8:9], off
	v_lshl_add_u64 v[8:9], v[8:9], 0, s[14:15]
	global_load_dword v74, v[8:9], off
	v_lshl_add_u64 v[8:9], v[8:9], 0, s[14:15]
	global_load_dword v75, v[8:9], off
	v_lshl_add_u64 v[8:9], v[8:9], 0, s[14:15]
	global_load_dword v76, v[8:9], off
	v_lshl_add_u64 v[8:9], v[8:9], 0, s[14:15]
	global_load_dword v77, v[8:9], off
	v_lshl_add_u64 v[8:9], v[8:9], 0, s[14:15]
	global_load_dword v78, v[8:9], off
	v_lshl_add_u64 v[8:9], v[8:9], 0, s[14:15]
	global_load_dword v79, v[8:9], off
	v_lshl_add_u64 v[8:9], v[8:9], 0, s[14:15]
	global_load_dword v80, v[8:9], off
	v_lshl_add_u64 v[8:9], v[8:9], 0, s[14:15]
	global_load_dword v81, v[8:9], off
	v_lshl_add_u64 v[8:9], v[8:9], 0, s[14:15]
	global_load_dword v82, v[8:9], off
	v_lshl_add_u64 v[8:9], v[8:9], 0, s[14:15]
	global_load_dword v83, v[8:9], off
	v_lshl_add_u64 v[8:9], v[8:9], 0, s[14:15]
	global_load_dword v84, v[8:9], off
	v_lshl_add_u64 v[8:9], v[8:9], 0, s[14:15]
	global_load_dword v85, v[8:9], off
	v_lshl_add_u64 v[8:9], v[8:9], 0, s[14:15]
	global_load_dword v86, v[8:9], off
	v_lshl_add_u64 v[8:9], v[8:9], 0, s[14:15]
	global_load_dword v87, v[8:9], off
	v_lshl_add_u64 v[8:9], v[8:9], 0, s[14:15]
	global_load_dword v88, v[8:9], off
	v_lshl_add_u64 v[8:9], v[8:9], 0, s[14:15]
	global_load_dword v89, v[8:9], off
	v_lshl_add_u64 v[8:9], v[8:9], 0, s[14:15]
	global_load_dword v90, v[8:9], off
	v_lshl_add_u64 v[8:9], v[8:9], 0, s[14:15]
	global_load_dword v91, v[8:9], off
	v_lshl_add_u64 v[8:9], v[8:9], 0, s[14:15]
	global_load_dword v92, v[8:9], off
	v_lshl_add_u64 v[8:9], v[8:9], 0, s[14:15]
	global_load_dword v93, v[8:9], off
	v_lshl_add_u64 v[8:9], v[8:9], 0, s[14:15]
	global_load_dword v94, v[8:9], off
	v_lshl_add_u64 v[8:9], v[8:9], 0, s[14:15]
	global_load_dword v95, v[8:9], off
	v_lshl_add_u64 v[8:9], v[8:9], 0, s[14:15]
	global_load_dword v96, v[8:9], off
	v_lshl_add_u64 v[8:9], v[8:9], 0, s[14:15]
	global_load_dword v97, v[8:9], off
	v_lshl_add_u64 v[8:9], v[8:9], 0, s[14:15]
	global_load_dword v98, v[8:9], off
	v_lshl_add_u64 v[8:9], v[8:9], 0, s[14:15]
	global_load_dword v99, v[8:9], off
	v_lshl_add_u64 v[8:9], v[8:9], 0, s[14:15]
	global_load_dword v100, v[8:9], off
	v_lshl_add_u64 v[8:9], v[8:9], 0, s[14:15]
	global_load_dword v101, v[8:9], off
	v_lshl_add_u64 v[8:9], v[8:9], 0, s[14:15]
	global_load_dword v102, v[8:9], off
	v_lshl_add_u64 v[8:9], v[8:9], 0, s[14:15]
	global_load_dword v103, v[8:9], off
	v_lshl_add_u64 v[8:9], v[8:9], 0, s[14:15]
	global_load_dword v104, v[8:9], off
	v_lshl_add_u64 v[8:9], v[8:9], 0, s[14:15]
	global_load_dword v105, v[8:9], off
	v_lshl_add_u64 v[8:9], v[8:9], 0, s[14:15]
	global_load_dword v106, v[8:9], off
	v_lshl_add_u64 v[8:9], v[8:9], 0, s[14:15]
	global_load_dword v107, v[8:9], off
	v_lshl_add_u64 v[8:9], v[8:9], 0, s[14:15]
	global_load_dword v108, v[8:9], off
	v_lshl_add_u64 v[8:9], v[8:9], 0, s[14:15]
	global_load_dword v109, v[8:9], off
	v_lshl_add_u64 v[8:9], v[8:9], 0, s[14:15]
	global_load_dword v110, v[8:9], off
	v_lshl_add_u64 v[8:9], v[8:9], 0, s[14:15]
	global_load_dword v111, v[8:9], off
	v_lshl_add_u64 v[8:9], v[8:9], 0, s[14:15]
	global_load_dword v112, v[8:9], off
	v_lshl_add_u64 v[8:9], v[8:9], 0, s[14:15]
	global_load_dword v113, v[8:9], off
	v_lshl_add_u64 v[8:9], v[8:9], 0, s[14:15]
	global_load_dword v114, v[8:9], off
	v_lshl_add_u64 v[8:9], v[8:9], 0, s[14:15]
	global_load_dword v115, v[8:9], off
	v_lshl_add_u64 v[8:9], v[8:9], 0, s[14:15]
	global_load_dword v116, v[8:9], off
	v_lshl_add_u64 v[8:9], v[8:9], 0, s[14:15]
	global_load_dword v117, v[8:9], off
	v_lshl_add_u64 v[8:9], v[8:9], 0, s[14:15]
	global_load_dword v118, v[8:9], off
	v_lshl_add_u64 v[8:9], v[8:9], 0, s[14:15]
	global_load_dword v119, v[8:9], off
	v_lshl_add_u64 v[8:9], v[8:9], 0, s[14:15]
	global_load_dword v120, v[8:9], off
	v_lshl_add_u64 v[8:9], v[8:9], 0, s[14:15]
	global_load_dword v121, v[8:9], off
	v_lshl_add_u64 v[8:9], v[8:9], 0, s[14:15]
	global_load_dword v122, v[8:9], off
	v_lshl_add_u64 v[8:9], v[8:9], 0, s[14:15]
	global_load_dword v123, v[8:9], off
	v_lshl_add_u64 v[8:9], v[8:9], 0, s[14:15]
	global_load_dword v124, v[8:9], off
	v_lshl_add_u64 v[8:9], v[8:9], 0, s[14:15]
	global_load_dword v125, v[8:9], off
	v_lshl_add_u64 v[8:9], v[8:9], 0, s[14:15]
	global_load_dword v126, v[8:9], off
	v_lshl_add_u64 v[8:9], v[8:9], 0, s[14:15]
	global_load_dword v127, v[8:9], off
	v_lshl_add_u64 v[8:9], v[8:9], 0, s[14:15]
	global_load_dword v128, v[8:9], off
	v_lshl_add_u64 v[8:9], v[8:9], 0, s[14:15]
	global_load_dword v129, v[8:9], off
	v_lshl_add_u64 v[8:9], v[8:9], 0, s[14:15]
	global_load_dword v130, v[8:9], off
	v_lshl_add_u64 v[8:9], v[8:9], 0, s[14:15]
	global_load_dword v131, v[8:9], off
	v_lshl_add_u64 v[8:9], v[8:9], 0, s[14:15]
	global_load_dword v132, v[8:9], off
	v_lshl_add_u64 v[8:9], v[8:9], 0, s[14:15]
	global_load_dword v133, v[8:9], off
	v_lshl_add_u64 v[8:9], v[8:9], 0, s[14:15]
	global_load_dword v134, v[8:9], off
	v_lshl_add_u64 v[8:9], v[8:9], 0, s[14:15]
	global_load_dword v135, v[8:9], off
	v_lshl_add_u64 v[8:9], v[8:9], 0, s[14:15]
	global_load_dword v136, v[8:9], off
	v_lshl_add_u64 v[8:9], v[8:9], 0, s[14:15]
	global_load_dword v137, v[8:9], off
	v_lshl_add_u64 v[8:9], v[8:9], 0, s[14:15]
	global_load_dword v138, v[8:9], off
	v_lshl_add_u64 v[8:9], v[8:9], 0, s[14:15]
	global_load_dword v139, v[8:9], off
	v_lshl_add_u64 v[8:9], v[8:9], 0, s[14:15]
	global_load_dword v140, v[8:9], off
	v_lshl_add_u64 v[8:9], v[8:9], 0, s[14:15]
	global_load_dword v141, v[8:9], off
	v_lshl_add_u64 v[8:9], v[8:9], 0, s[14:15]
	global_load_dword v142, v[8:9], off
	v_lshl_add_u64 v[8:9], v[8:9], 0, s[14:15]
	global_load_dword v143, v[8:9], off
	v_lshl_add_u64 v[8:9], v[8:9], 0, s[14:15]
	global_load_dword v144, v[8:9], off
	v_lshl_add_u64 v[8:9], v[8:9], 0, s[14:15]
	global_load_dword v145, v[8:9], off
	v_lshl_add_u64 v[8:9], v[8:9], 0, s[14:15]
	global_load_dword v146, v[8:9], off
	v_lshl_add_u64 v[8:9], v[8:9], 0, s[14:15]
	global_load_dword v147, v[8:9], off
	v_lshl_add_u64 v[8:9], v[8:9], 0, s[14:15]
	global_load_dword v148, v[8:9], off
	v_lshl_add_u64 v[8:9], v[8:9], 0, s[14:15]
	global_load_dword v149, v[8:9], off
	v_lshl_add_u64 v[8:9], v[8:9], 0, s[14:15]
	global_load_dword v150, v[8:9], off
	v_lshl_add_u64 v[8:9], v[8:9], 0, s[14:15]
	global_load_dword v151, v[8:9], off
	v_lshl_add_u64 v[8:9], v[8:9], 0, s[14:15]
	global_load_dword v152, v[8:9], off
	v_lshl_add_u64 v[8:9], v[8:9], 0, s[14:15]
	global_load_dword v153, v[8:9], off
	v_lshl_add_u64 v[8:9], v[8:9], 0, s[14:15]
	global_load_dword v154, v[8:9], off
	v_lshl_add_u64 v[8:9], v[8:9], 0, s[14:15]
	global_load_dword v155, v[8:9], off
	v_lshl_add_u64 v[8:9], v[8:9], 0, s[14:15]
	global_load_dword v156, v[8:9], off
	v_lshl_add_u64 v[8:9], v[8:9], 0, s[14:15]
	global_load_dword v157, v[8:9], off
	v_lshl_add_u64 v[8:9], v[8:9], 0, s[14:15]
	global_load_dword v158, v[8:9], off
	v_lshl_add_u64 v[8:9], v[8:9], 0, s[14:15]
	global_load_dword v159, v[8:9], off
	v_lshl_add_u64 v[8:9], v[8:9], 0, s[14:15]
	global_load_dword v164, v[8:9], off
	v_lshl_add_u64 v[8:9], v[8:9], 0, s[14:15]
	global_load_dword v165, v[8:9], off
	s_mov_b32 s11, 64
	s_and_b64 vcc, exec, vcc
	s_waitcnt vmcnt(63)
	v_readlane_b32 s16, v3, 0
	v_readlane_b32 s17, v11, 0
	v_readlane_b32 s18, v3, 1
	v_readlane_b32 s19, v11, 1
	v_readlane_b32 s20, v3, 2
	v_readlane_b32 s21, v11, 2
	v_fma_f32 v6, v32, s16, v6
	v_fma_f32 v7, v32, s17, v7
	v_readlane_b32 s22, v3, 3
	v_readlane_b32 s23, v11, 3
	v_fma_f32 v6, v33, s18, v6
	v_fma_f32 v7, v33, s19, v7
	v_readlane_b32 s16, v3, 4
	v_readlane_b32 s17, v11, 4
	v_fma_f32 v6, v34, s20, v6
	v_fma_f32 v7, v34, s21, v7
	v_readlane_b32 s18, v3, 5
	v_readlane_b32 s19, v11, 5
	v_fma_f32 v6, v35, s22, v6
	v_fma_f32 v7, v35, s23, v7
	v_readlane_b32 s20, v3, 6
	v_readlane_b32 s21, v11, 6
	v_fma_f32 v6, v36, s16, v6
	v_fma_f32 v7, v36, s17, v7
	v_readlane_b32 s22, v3, 7
	v_readlane_b32 s23, v11, 7
	v_fma_f32 v6, v37, s18, v6
	v_fma_f32 v7, v37, s19, v7
	v_readlane_b32 s16, v3, 8
	v_readlane_b32 s17, v11, 8
	v_fma_f32 v6, v38, s20, v6
	v_fma_f32 v7, v38, s21, v7
	v_readlane_b32 s18, v3, 9
	v_readlane_b32 s19, v11, 9
	v_fma_f32 v6, v39, s22, v6
	v_fma_f32 v7, v39, s23, v7
	v_readlane_b32 s20, v3, 10
	v_readlane_b32 s21, v11, 10
	v_fma_f32 v6, v40, s16, v6
	v_fma_f32 v7, v40, s17, v7
	v_readlane_b32 s22, v3, 11
	v_readlane_b32 s23, v11, 11
	v_fma_f32 v6, v41, s18, v6
	v_fma_f32 v7, v41, s19, v7
	v_readlane_b32 s16, v3, 12
	v_readlane_b32 s17, v11, 12
	v_fma_f32 v6, v42, s20, v6
	v_fma_f32 v7, v42, s21, v7
	v_readlane_b32 s18, v3, 13
	v_readlane_b32 s19, v11, 13
	v_fma_f32 v6, v43, s22, v6
	v_fma_f32 v7, v43, s23, v7
	v_readlane_b32 s20, v3, 14
	v_readlane_b32 s21, v11, 14
	v_fma_f32 v6, v44, s16, v6
	v_fma_f32 v7, v44, s17, v7
	v_readlane_b32 s22, v3, 15
	v_readlane_b32 s23, v11, 15
	v_fma_f32 v6, v45, s18, v6
	v_fma_f32 v7, v45, s19, v7
	v_readlane_b32 s16, v3, 16
	v_readlane_b32 s17, v11, 16
	v_fma_f32 v6, v46, s20, v6
	v_fma_f32 v7, v46, s21, v7
	v_readlane_b32 s18, v3, 17
	v_readlane_b32 s19, v11, 17
	v_fma_f32 v6, v47, s22, v6
	v_fma_f32 v7, v47, s23, v7
	v_readlane_b32 s20, v3, 18
	v_readlane_b32 s21, v11, 18
	v_fma_f32 v6, v48, s16, v6
	v_fma_f32 v7, v48, s17, v7
	v_readlane_b32 s22, v3, 19
	v_readlane_b32 s23, v11, 19
	v_fma_f32 v6, v49, s18, v6
	v_fma_f32 v7, v49, s19, v7
	v_readlane_b32 s16, v3, 20
	v_readlane_b32 s17, v11, 20
	v_fma_f32 v6, v50, s20, v6
	v_fma_f32 v7, v50, s21, v7
	v_readlane_b32 s18, v3, 21
	v_readlane_b32 s19, v11, 21
	v_fma_f32 v6, v51, s22, v6
	v_fma_f32 v7, v51, s23, v7
	v_readlane_b32 s20, v3, 22
	v_readlane_b32 s21, v11, 22
	v_fma_f32 v6, v52, s16, v6
	v_fma_f32 v7, v52, s17, v7
	v_readlane_b32 s22, v3, 23
	v_readlane_b32 s23, v11, 23
	v_fma_f32 v6, v53, s18, v6
	v_fma_f32 v7, v53, s19, v7
	v_readlane_b32 s16, v3, 24
	v_readlane_b32 s17, v11, 24
	v_fma_f32 v6, v54, s20, v6
	v_fma_f32 v7, v54, s21, v7
	v_readlane_b32 s18, v3, 25
	v_readlane_b32 s19, v11, 25
	v_fma_f32 v6, v55, s22, v6
	v_fma_f32 v7, v55, s23, v7
	v_readlane_b32 s20, v3, 26
	v_readlane_b32 s21, v11, 26
	v_fma_f32 v6, v58, s16, v6
	v_fma_f32 v7, v58, s17, v7
	v_readlane_b32 s22, v3, 27
	v_readlane_b32 s23, v11, 27
	v_fma_f32 v6, v59, s18, v6
	v_fma_f32 v7, v59, s19, v7
	v_readlane_b32 s16, v3, 28
	v_readlane_b32 s17, v11, 28
	v_fma_f32 v6, v60, s20, v6
	v_fma_f32 v7, v60, s21, v7
	v_readlane_b32 s18, v3, 29
	v_readlane_b32 s19, v11, 29
	v_fma_f32 v6, v61, s22, v6
	v_fma_f32 v7, v61, s23, v7
	v_readlane_b32 s20, v3, 30
	v_readlane_b32 s21, v11, 30
	v_fma_f32 v6, v62, s16, v6
	v_fma_f32 v7, v62, s17, v7
	v_readlane_b32 s22, v3, 31
	v_readlane_b32 s23, v11, 31
	v_fma_f32 v6, v63, s18, v6
	v_fma_f32 v7, v63, s19, v7
	v_readlane_b32 s16, v3, 32
	v_readlane_b32 s17, v11, 32
	v_fma_f32 v6, v64, s20, v6
	v_fma_f32 v7, v64, s21, v7
	v_readlane_b32 s18, v3, 33
	v_readlane_b32 s19, v11, 33
	v_fma_f32 v6, v65, s22, v6
	v_fma_f32 v7, v65, s23, v7
	v_readlane_b32 s20, v3, 34
	v_readlane_b32 s21, v11, 34
	v_fma_f32 v6, v66, s16, v6
	v_fma_f32 v7, v66, s17, v7
	v_readlane_b32 s22, v3, 35
	v_readlane_b32 s23, v11, 35
	v_fma_f32 v6, v67, s18, v6
	v_fma_f32 v7, v67, s19, v7
	v_readlane_b32 s16, v3, 36
	v_readlane_b32 s17, v11, 36
	v_fma_f32 v6, v68, s20, v6
	v_fma_f32 v7, v68, s21, v7
	v_readlane_b32 s18, v3, 37
	v_readlane_b32 s19, v11, 37
	v_fma_f32 v6, v69, s22, v6
	v_fma_f32 v7, v69, s23, v7
	v_readlane_b32 s20, v3, 38
	v_readlane_b32 s21, v11, 38
	v_fma_f32 v6, v70, s16, v6
	v_fma_f32 v7, v70, s17, v7
	v_readlane_b32 s22, v3, 39
	v_readlane_b32 s23, v11, 39
	v_fma_f32 v6, v71, s18, v6
	v_fma_f32 v7, v71, s19, v7
	v_readlane_b32 s16, v3, 40
	v_readlane_b32 s17, v11, 40
	v_fma_f32 v6, v72, s20, v6
	v_fma_f32 v7, v72, s21, v7
	v_readlane_b32 s18, v3, 41
	v_readlane_b32 s19, v11, 41
	v_fma_f32 v6, v73, s22, v6
	v_fma_f32 v7, v73, s23, v7
	v_readlane_b32 s20, v3, 42
	v_readlane_b32 s21, v11, 42
	v_fma_f32 v6, v74, s16, v6
	v_fma_f32 v7, v74, s17, v7
	v_readlane_b32 s22, v3, 43
	v_readlane_b32 s23, v11, 43
	v_fma_f32 v6, v75, s18, v6
	v_fma_f32 v7, v75, s19, v7
	v_readlane_b32 s16, v3, 44
	v_readlane_b32 s17, v11, 44
	v_fma_f32 v6, v76, s20, v6
	v_fma_f32 v7, v76, s21, v7
	v_readlane_b32 s18, v3, 45
	v_readlane_b32 s19, v11, 45
	v_fma_f32 v6, v77, s22, v6
	v_fma_f32 v7, v77, s23, v7
	v_readlane_b32 s20, v3, 46
	v_readlane_b32 s21, v11, 46
	v_fma_f32 v6, v78, s16, v6
	v_fma_f32 v7, v78, s17, v7
	v_readlane_b32 s22, v3, 47
	v_readlane_b32 s23, v11, 47
	v_fma_f32 v6, v79, s18, v6
	v_fma_f32 v7, v79, s19, v7
	v_readlane_b32 s16, v3, 48
	v_readlane_b32 s17, v11, 48
	v_fma_f32 v6, v80, s20, v6
	v_fma_f32 v7, v80, s21, v7
	v_readlane_b32 s18, v3, 49
	v_readlane_b32 s19, v11, 49
	v_fma_f32 v6, v81, s22, v6
	v_fma_f32 v7, v81, s23, v7
	v_readlane_b32 s20, v3, 50
	v_readlane_b32 s21, v11, 50
	v_fma_f32 v6, v82, s16, v6
	v_fma_f32 v7, v82, s17, v7
	v_readlane_b32 s22, v3, 51
	v_readlane_b32 s23, v11, 51
	v_fma_f32 v6, v83, s18, v6
	v_fma_f32 v7, v83, s19, v7
	v_readlane_b32 s16, v3, 52
	v_readlane_b32 s17, v11, 52
	v_fma_f32 v6, v84, s20, v6
	v_fma_f32 v7, v84, s21, v7
	v_readlane_b32 s18, v3, 53
	v_readlane_b32 s19, v11, 53
	v_fma_f32 v6, v85, s22, v6
	v_fma_f32 v7, v85, s23, v7
	v_readlane_b32 s20, v3, 54
	v_readlane_b32 s21, v11, 54
	v_fma_f32 v6, v86, s16, v6
	v_fma_f32 v7, v86, s17, v7
	v_readlane_b32 s22, v3, 55
	v_readlane_b32 s23, v11, 55
	v_fma_f32 v6, v87, s18, v6
	v_fma_f32 v7, v87, s19, v7
	v_readlane_b32 s16, v3, 56
	v_readlane_b32 s17, v11, 56
	v_fma_f32 v6, v88, s20, v6
	v_fma_f32 v7, v88, s21, v7
	v_readlane_b32 s18, v3, 57
	v_readlane_b32 s19, v11, 57
	v_fma_f32 v6, v89, s22, v6
	v_fma_f32 v7, v89, s23, v7
	v_readlane_b32 s20, v3, 58
	v_readlane_b32 s21, v11, 58
	v_fma_f32 v6, v90, s16, v6
	v_fma_f32 v7, v90, s17, v7
	v_readlane_b32 s22, v3, 59
	v_readlane_b32 s23, v11, 59
	v_fma_f32 v6, v91, s18, v6
	v_fma_f32 v7, v91, s19, v7
	v_readlane_b32 s16, v3, 60
	v_readlane_b32 s17, v11, 60
	v_fma_f32 v6, v92, s20, v6
	v_fma_f32 v7, v92, s21, v7
	v_readlane_b32 s18, v3, 61
	v_readlane_b32 s19, v11, 61
	v_fma_f32 v6, v93, s22, v6
	v_fma_f32 v7, v93, s23, v7
	v_readlane_b32 s20, v3, 62
	v_readlane_b32 s21, v11, 62
	v_fma_f32 v6, v94, s16, v6
	v_fma_f32 v7, v94, s17, v7
	v_readlane_b32 s22, v3, 63
	v_readlane_b32 s23, v11, 63
	v_fma_f32 v6, v95, s18, v6
	v_fma_f32 v7, v95, s19, v7
	v_readlane_b32 s16, v28, 0
	v_readlane_b32 s17, v29, 0
	v_fma_f32 v6, v96, s20, v6
	v_fma_f32 v7, v96, s21, v7
	v_readlane_b32 s18, v28, 1
	v_readlane_b32 s19, v29, 1
	v_fma_f32 v6, v97, s22, v6
	v_fma_f32 v7, v97, s23, v7
	v_readlane_b32 s20, v28, 2
	v_readlane_b32 s21, v29, 2
	v_fma_f32 v6, v98, s16, v6
	v_fma_f32 v7, v98, s17, v7
	v_readlane_b32 s22, v28, 3
	v_readlane_b32 s23, v29, 3
	s_waitcnt vmcnt(62)
	v_fma_f32 v6, v99, s18, v6
	v_fma_f32 v7, v99, s19, v7
	v_readlane_b32 s16, v28, 4
	v_readlane_b32 s17, v29, 4
	s_waitcnt vmcnt(61)
	v_fma_f32 v6, v100, s20, v6
	v_fma_f32 v7, v100, s21, v7
	v_readlane_b32 s18, v28, 5
	v_readlane_b32 s19, v29, 5
	s_waitcnt vmcnt(60)
	v_fma_f32 v6, v101, s22, v6
	v_fma_f32 v7, v101, s23, v7
	v_readlane_b32 s20, v28, 6
	v_readlane_b32 s21, v29, 6
	s_waitcnt vmcnt(59)
	v_fma_f32 v6, v102, s16, v6
	v_fma_f32 v7, v102, s17, v7
	v_readlane_b32 s22, v28, 7
	v_readlane_b32 s23, v29, 7
	s_waitcnt vmcnt(58)
	v_fma_f32 v6, v103, s18, v6
	v_fma_f32 v7, v103, s19, v7
	v_readlane_b32 s16, v28, 8
	v_readlane_b32 s17, v29, 8
	s_waitcnt vmcnt(57)
	v_fma_f32 v6, v104, s20, v6
	v_fma_f32 v7, v104, s21, v7
	v_readlane_b32 s18, v28, 9
	v_readlane_b32 s19, v29, 9
	s_waitcnt vmcnt(56)
	v_fma_f32 v6, v105, s22, v6
	v_fma_f32 v7, v105, s23, v7
	v_readlane_b32 s20, v28, 10
	v_readlane_b32 s21, v29, 10
	s_waitcnt vmcnt(55)
	v_fma_f32 v6, v106, s16, v6
	v_fma_f32 v7, v106, s17, v7
	v_readlane_b32 s22, v28, 11
	v_readlane_b32 s23, v29, 11
	s_waitcnt vmcnt(54)
	v_fma_f32 v6, v107, s18, v6
	v_fma_f32 v7, v107, s19, v7
	v_readlane_b32 s16, v28, 12
	v_readlane_b32 s17, v29, 12
	s_waitcnt vmcnt(53)
	v_fma_f32 v6, v108, s20, v6
	v_fma_f32 v7, v108, s21, v7
	v_readlane_b32 s18, v28, 13
	v_readlane_b32 s19, v29, 13
	s_waitcnt vmcnt(52)
	v_fma_f32 v6, v109, s22, v6
	v_fma_f32 v7, v109, s23, v7
	v_readlane_b32 s20, v28, 14
	v_readlane_b32 s21, v29, 14
	s_waitcnt vmcnt(51)
	v_fma_f32 v6, v110, s16, v6
	v_fma_f32 v7, v110, s17, v7
	v_readlane_b32 s22, v28, 15
	v_readlane_b32 s23, v29, 15
	s_waitcnt vmcnt(50)
	v_fma_f32 v6, v111, s18, v6
	v_fma_f32 v7, v111, s19, v7
	v_readlane_b32 s16, v28, 16
	v_readlane_b32 s17, v29, 16
	s_waitcnt vmcnt(49)
	v_fma_f32 v6, v112, s20, v6
	v_fma_f32 v7, v112, s21, v7
	v_readlane_b32 s18, v28, 17
	v_readlane_b32 s19, v29, 17
	s_waitcnt vmcnt(48)
	v_fma_f32 v6, v113, s22, v6
	v_fma_f32 v7, v113, s23, v7
	v_readlane_b32 s20, v28, 18
	v_readlane_b32 s21, v29, 18
	s_waitcnt vmcnt(47)
	v_fma_f32 v6, v114, s16, v6
	v_fma_f32 v7, v114, s17, v7
	v_readlane_b32 s22, v28, 19
	v_readlane_b32 s23, v29, 19
	s_waitcnt vmcnt(46)
	v_fma_f32 v6, v115, s18, v6
	v_fma_f32 v7, v115, s19, v7
	v_readlane_b32 s16, v28, 20
	v_readlane_b32 s17, v29, 20
	s_waitcnt vmcnt(45)
	v_fma_f32 v6, v116, s20, v6
	v_fma_f32 v7, v116, s21, v7
	v_readlane_b32 s18, v28, 21
	v_readlane_b32 s19, v29, 21
	s_waitcnt vmcnt(44)
	v_fma_f32 v6, v117, s22, v6
	v_fma_f32 v7, v117, s23, v7
	v_readlane_b32 s20, v28, 22
	v_readlane_b32 s21, v29, 22
	s_waitcnt vmcnt(43)
	v_fma_f32 v6, v118, s16, v6
	v_fma_f32 v7, v118, s17, v7
	v_readlane_b32 s22, v28, 23
	v_readlane_b32 s23, v29, 23
	s_waitcnt vmcnt(42)
	v_fma_f32 v6, v119, s18, v6
	v_fma_f32 v7, v119, s19, v7
	v_readlane_b32 s16, v28, 24
	v_readlane_b32 s17, v29, 24
	s_waitcnt vmcnt(41)
	v_fma_f32 v6, v120, s20, v6
	v_fma_f32 v7, v120, s21, v7
	v_readlane_b32 s18, v28, 25
	v_readlane_b32 s19, v29, 25
	s_waitcnt vmcnt(40)
	v_fma_f32 v6, v121, s22, v6
	v_fma_f32 v7, v121, s23, v7
	v_readlane_b32 s20, v28, 26
	v_readlane_b32 s21, v29, 26
	s_waitcnt vmcnt(39)
	v_fma_f32 v6, v122, s16, v6
	v_fma_f32 v7, v122, s17, v7
	v_readlane_b32 s22, v28, 27
	v_readlane_b32 s23, v29, 27
	s_waitcnt vmcnt(38)
	v_fma_f32 v6, v123, s18, v6
	v_fma_f32 v7, v123, s19, v7
	v_readlane_b32 s16, v28, 28
	v_readlane_b32 s17, v29, 28
	s_waitcnt vmcnt(37)
	v_fma_f32 v6, v124, s20, v6
	v_fma_f32 v7, v124, s21, v7
	v_readlane_b32 s18, v28, 29
	v_readlane_b32 s19, v29, 29
	s_waitcnt vmcnt(36)
	v_fma_f32 v6, v125, s22, v6
	v_fma_f32 v7, v125, s23, v7
	v_readlane_b32 s20, v28, 30
	v_readlane_b32 s21, v29, 30
	s_waitcnt vmcnt(35)
	v_fma_f32 v6, v126, s16, v6
	v_fma_f32 v7, v126, s17, v7
	v_readlane_b32 s22, v28, 31
	v_readlane_b32 s23, v29, 31
	s_waitcnt vmcnt(34)
	v_fma_f32 v6, v127, s18, v6
	v_fma_f32 v7, v127, s19, v7
	v_readlane_b32 s16, v28, 32
	v_readlane_b32 s17, v29, 32
	s_waitcnt vmcnt(33)
	v_fma_f32 v6, v128, s20, v6
	v_fma_f32 v7, v128, s21, v7
	v_readlane_b32 s18, v28, 33
	v_readlane_b32 s19, v29, 33
	s_waitcnt vmcnt(32)
	v_fma_f32 v6, v129, s22, v6
	v_fma_f32 v7, v129, s23, v7
	v_readlane_b32 s20, v28, 34
	v_readlane_b32 s21, v29, 34
	s_waitcnt vmcnt(31)
	v_fma_f32 v6, v130, s16, v6
	v_fma_f32 v7, v130, s17, v7
	v_readlane_b32 s22, v28, 35
	v_readlane_b32 s23, v29, 35
	s_waitcnt vmcnt(30)
	v_fma_f32 v6, v131, s18, v6
	v_fma_f32 v7, v131, s19, v7
	v_readlane_b32 s16, v28, 36
	v_readlane_b32 s17, v29, 36
	s_waitcnt vmcnt(29)
	v_fma_f32 v6, v132, s20, v6
	v_fma_f32 v7, v132, s21, v7
	v_readlane_b32 s18, v28, 37
	v_readlane_b32 s19, v29, 37
	s_waitcnt vmcnt(28)
	v_fma_f32 v6, v133, s22, v6
	v_fma_f32 v7, v133, s23, v7
	v_readlane_b32 s20, v28, 38
	v_readlane_b32 s21, v29, 38
	s_waitcnt vmcnt(27)
	v_fma_f32 v6, v134, s16, v6
	v_fma_f32 v7, v134, s17, v7
	v_readlane_b32 s22, v28, 39
	v_readlane_b32 s23, v29, 39
	s_waitcnt vmcnt(26)
	v_fma_f32 v6, v135, s18, v6
	v_fma_f32 v7, v135, s19, v7
	v_readlane_b32 s16, v28, 40
	v_readlane_b32 s17, v29, 40
	s_waitcnt vmcnt(25)
	v_fma_f32 v6, v136, s20, v6
	v_fma_f32 v7, v136, s21, v7
	v_readlane_b32 s18, v28, 41
	v_readlane_b32 s19, v29, 41
	s_waitcnt vmcnt(24)
	v_fma_f32 v6, v137, s22, v6
	v_fma_f32 v7, v137, s23, v7
	v_readlane_b32 s20, v28, 42
	v_readlane_b32 s21, v29, 42
	s_waitcnt vmcnt(23)
	v_fma_f32 v6, v138, s16, v6
	v_fma_f32 v7, v138, s17, v7
	v_readlane_b32 s22, v28, 43
	v_readlane_b32 s23, v29, 43
	s_waitcnt vmcnt(22)
	v_fma_f32 v6, v139, s18, v6
	v_fma_f32 v7, v139, s19, v7
	v_readlane_b32 s16, v28, 44
	v_readlane_b32 s17, v29, 44
	s_waitcnt vmcnt(21)
	v_fma_f32 v6, v140, s20, v6
	v_fma_f32 v7, v140, s21, v7
	v_readlane_b32 s18, v28, 45
	v_readlane_b32 s19, v29, 45
	s_waitcnt vmcnt(20)
	v_fma_f32 v6, v141, s22, v6
	v_fma_f32 v7, v141, s23, v7
	v_readlane_b32 s20, v28, 46
	v_readlane_b32 s21, v29, 46
	s_waitcnt vmcnt(19)
	v_fma_f32 v6, v142, s16, v6
	v_fma_f32 v7, v142, s17, v7
	v_readlane_b32 s22, v28, 47
	v_readlane_b32 s23, v29, 47
	s_waitcnt vmcnt(18)
	v_fma_f32 v6, v143, s18, v6
	v_fma_f32 v7, v143, s19, v7
	v_readlane_b32 s16, v28, 48
	v_readlane_b32 s17, v29, 48
	s_waitcnt vmcnt(17)
	v_fma_f32 v6, v144, s20, v6
	v_fma_f32 v7, v144, s21, v7
	v_readlane_b32 s18, v28, 49
	v_readlane_b32 s19, v29, 49
	s_waitcnt vmcnt(16)
	v_fma_f32 v6, v145, s22, v6
	v_fma_f32 v7, v145, s23, v7
	v_readlane_b32 s20, v28, 50
	v_readlane_b32 s21, v29, 50
	s_waitcnt vmcnt(15)
	v_fma_f32 v6, v146, s16, v6
	v_fma_f32 v7, v146, s17, v7
	v_readlane_b32 s22, v28, 51
	v_readlane_b32 s23, v29, 51
	s_waitcnt vmcnt(14)
	v_fma_f32 v6, v147, s18, v6
	v_fma_f32 v7, v147, s19, v7
	v_readlane_b32 s16, v28, 52
	v_readlane_b32 s17, v29, 52
	s_waitcnt vmcnt(13)
	v_fma_f32 v6, v148, s20, v6
	v_fma_f32 v7, v148, s21, v7
	v_readlane_b32 s18, v28, 53
	v_readlane_b32 s19, v29, 53
	s_waitcnt vmcnt(12)
	v_fma_f32 v6, v149, s22, v6
	v_fma_f32 v7, v149, s23, v7
	v_readlane_b32 s20, v28, 54
	v_readlane_b32 s21, v29, 54
	s_waitcnt vmcnt(11)
	v_fma_f32 v6, v150, s16, v6
	v_fma_f32 v7, v150, s17, v7
	v_readlane_b32 s22, v28, 55
	v_readlane_b32 s23, v29, 55
	s_waitcnt vmcnt(10)
	v_fma_f32 v6, v151, s18, v6
	v_fma_f32 v7, v151, s19, v7
	v_readlane_b32 s16, v28, 56
	v_readlane_b32 s17, v29, 56
	s_waitcnt vmcnt(9)
	v_fma_f32 v6, v152, s20, v6
	v_fma_f32 v7, v152, s21, v7
	v_readlane_b32 s18, v28, 57
	v_readlane_b32 s19, v29, 57
	s_waitcnt vmcnt(8)
	v_fma_f32 v6, v153, s22, v6
	v_fma_f32 v7, v153, s23, v7
	v_readlane_b32 s20, v28, 58
	v_readlane_b32 s21, v29, 58
	s_waitcnt vmcnt(7)
	v_fma_f32 v6, v154, s16, v6
	v_fma_f32 v7, v154, s17, v7
	v_readlane_b32 s22, v28, 59
	v_readlane_b32 s23, v29, 59
	s_waitcnt vmcnt(6)
	v_fma_f32 v6, v155, s18, v6
	v_fma_f32 v7, v155, s19, v7
	v_readlane_b32 s16, v28, 60
	v_readlane_b32 s17, v29, 60
	s_waitcnt vmcnt(5)
	v_fma_f32 v6, v156, s20, v6
	v_fma_f32 v7, v156, s21, v7
	v_readlane_b32 s18, v28, 61
	v_readlane_b32 s19, v29, 61
	s_waitcnt vmcnt(4)
	v_fma_f32 v6, v157, s22, v6
	v_fma_f32 v7, v157, s23, v7
	v_readlane_b32 s20, v28, 62
	v_readlane_b32 s21, v29, 62
	s_waitcnt vmcnt(3)
	v_fma_f32 v6, v158, s16, v6
	v_fma_f32 v7, v158, s17, v7
	v_readlane_b32 s22, v28, 63
	v_readlane_b32 s23, v29, 63
	s_waitcnt vmcnt(2)
	v_fma_f32 v6, v159, s18, v6
	v_fma_f32 v7, v159, s19, v7
	s_waitcnt vmcnt(1)
	v_fma_f32 v6, v164, s20, v6
	v_fma_f32 v7, v164, s21, v7
	s_waitcnt vmcnt(0)
	v_fma_f32 v6, v165, s22, v6
	v_fma_f32 v7, v165, s23, v7
	s_mov_b64 s[0:1], 0
	s_and_saveexec_b64 s[0:1], s[6:7]
	v_readlane_b32 s4, v250, 34
	v_readlane_b32 s5, v250, 35
	s_cbranch_execz .LBB0_666
	v_ashrrev_i32_e32 v3, 31, v2
	v_readlane_b32 s2, v250, 40
	v_lshlrev_b64 v[2:3], 2, v[2:3]
	v_readlane_b32 s3, v250, 41
	s_nop 1
	v_lshl_add_u64 v[4:5], s[2:3], 0, v[2:3]
	v_lshl_add_u64 v[2:3], s[4:5], 0, v[2:3]
	global_atomic_add_f32 v[2:3], v6, off
	global_atomic_add_f32 v[4:5], v7, off
	s_branch .LBB0_666

.LBB0_698:
	v_cndmask_b32_e64 v0, 0, 1, s[0:1]
	v_cmp_ne_u32_e32 vcc, 1, v0
	v_or_b32_e32 v0, s2, v10
	v_lshlrev_b64 v[8:9], 2, v[0:1]
	s_lshl_b32 s90, s2, 12
	v_lshl_add_u64 v[12:13], s[10:11], 0, v[8:9]
	v_lshl_add_u64 v[8:9], s[12:13], 0, v[8:9]
	global_load_dword v0, v[12:13], off
	global_load_dword v3, v[8:9], off
	global_load_dword v28, v[12:13], off offset:256
	global_load_dword v29, v[8:9], off offset:256
	v_lshl_add_u64 v[8:9], s[90:91], 2, v[4:5]
	s_mov_b32 s14, 0x4000
	s_mov_b32 s15, 0
	global_load_dword v32, v[8:9], off
	v_lshl_add_u64 v[8:9], v[8:9], 0, s[14:15]
	global_load_dword v33, v[8:9], off
	v_lshl_add_u64 v[8:9], v[8:9], 0, s[14:15]
	global_load_dword v34, v[8:9], off
	v_lshl_add_u64 v[8:9], v[8:9], 0, s[14:15]
	global_load_dword v35, v[8:9], off
	v_lshl_add_u64 v[8:9], v[8:9], 0, s[14:15]
	global_load_dword v36, v[8:9], off
	v_lshl_add_u64 v[8:9], v[8:9], 0, s[14:15]
	global_load_dword v37, v[8:9], off
	v_lshl_add_u64 v[8:9], v[8:9], 0, s[14:15]
	global_load_dword v38, v[8:9], off
	v_lshl_add_u64 v[8:9], v[8:9], 0, s[14:15]
	global_load_dword v39, v[8:9], off
	v_lshl_add_u64 v[8:9], v[8:9], 0, s[14:15]
	global_load_dword v40, v[8:9], off
	v_lshl_add_u64 v[8:9], v[8:9], 0, s[14:15]
	global_load_dword v41, v[8:9], off
	v_lshl_add_u64 v[8:9], v[8:9], 0, s[14:15]
	global_load_dword v42, v[8:9], off
	v_lshl_add_u64 v[8:9], v[8:9], 0, s[14:15]
	global_load_dword v43, v[8:9], off
	v_lshl_add_u64 v[8:9], v[8:9], 0, s[14:15]
	global_load_dword v44, v[8:9], off
	v_lshl_add_u64 v[8:9], v[8:9], 0, s[14:15]
	global_load_dword v45, v[8:9], off
	v_lshl_add_u64 v[8:9], v[8:9], 0, s[14:15]
	global_load_dword v46, v[8:9], off
	v_lshl_add_u64 v[8:9], v[8:9], 0, s[14:15]
	global_load_dword v47, v[8:9], off
	v_lshl_add_u64 v[8:9], v[8:9], 0, s[14:15]
	global_load_dword v48, v[8:9], off
	v_lshl_add_u64 v[8:9], v[8:9], 0, s[14:15]
	global_load_dword v49, v[8:9], off
	v_lshl_add_u64 v[8:9], v[8:9], 0, s[14:15]
	global_load_dword v50, v[8:9], off
	v_lshl_add_u64 v[8:9], v[8:9], 0, s[14:15]
	global_load_dword v51, v[8:9], off
	v_lshl_add_u64 v[8:9], v[8:9], 0, s[14:15]
	global_load_dword v52, v[8:9], off
	v_lshl_add_u64 v[8:9], v[8:9], 0, s[14:15]
	global_load_dword v53, v[8:9], off
	v_lshl_add_u64 v[8:9], v[8:9], 0, s[14:15]
	global_load_dword v54, v[8:9], off
	v_lshl_add_u64 v[8:9], v[8:9], 0, s[14:15]
	global_load_dword v55, v[8:9], off
	v_lshl_add_u64 v[8:9], v[8:9], 0, s[14:15]
	global_load_dword v58, v[8:9], off
	v_lshl_add_u64 v[8:9], v[8:9], 0, s[14:15]
	global_load_dword v59, v[8:9], off
	v_lshl_add_u64 v[8:9], v[8:9], 0, s[14:15]
	global_load_dword v60, v[8:9], off
	v_lshl_add_u64 v[8:9], v[8:9], 0, s[14:15]
	global_load_dword v61, v[8:9], off
	v_lshl_add_u64 v[8:9], v[8:9], 0, s[14:15]
	global_load_dword v62, v[8:9], off
	v_lshl_add_u64 v[8:9], v[8:9], 0, s[14:15]
	global_load_dword v63, v[8:9], off
	v_lshl_add_u64 v[8:9], v[8:9], 0, s[14:15]
	global_load_dword v64, v[8:9], off
	v_lshl_add_u64 v[8:9], v[8:9], 0, s[14:15]
	global_load_dword v65, v[8:9], off
	v_lshl_add_u64 v[8:9], v[8:9], 0, s[14:15]
	global_load_dword v66, v[8:9], off
	v_lshl_add_u64 v[8:9], v[8:9], 0, s[14:15]
	global_load_dword v67, v[8:9], off
	v_lshl_add_u64 v[8:9], v[8:9], 0, s[14:15]
	global_load_dword v68, v[8:9], off
	v_lshl_add_u64 v[8:9], v[8:9], 0, s[14:15]
	global_load_dword v69, v[8:9], off
	v_lshl_add_u64 v[8:9], v[8:9], 0, s[14:15]
	global_load_dword v70, v[8:9], off
	v_lshl_add_u64 v[8:9], v[8:9], 0, s[14:15]
	global_load_dword v71, v[8:9], off
	v_lshl_add_u64 v[8:9], v[8:9], 0, s[14:15]
	global_load_dword v72, v[8:9], off
	v_lshl_add_u64 v[8:9], v[8:9], 0, s[14:15]
	global_load_dword v73, v[8:9], off
	v_lshl_add_u64 v[8:9], v[8:9], 0, s[14:15]
	global_load_dword v74, v[8:9], off
	v_lshl_add_u64 v[8:9], v[8:9], 0, s[14:15]
	global_load_dword v75, v[8:9], off
	v_lshl_add_u64 v[8:9], v[8:9], 0, s[14:15]
	global_load_dword v76, v[8:9], off
	v_lshl_add_u64 v[8:9], v[8:9], 0, s[14:15]
	global_load_dword v77, v[8:9], off
	v_lshl_add_u64 v[8:9], v[8:9], 0, s[14:15]
	global_load_dword v78, v[8:9], off
	v_lshl_add_u64 v[8:9], v[8:9], 0, s[14:15]
	global_load_dword v79, v[8:9], off
	v_lshl_add_u64 v[8:9], v[8:9], 0, s[14:15]
	global_load_dword v80, v[8:9], off
	v_lshl_add_u64 v[8:9], v[8:9], 0, s[14:15]
	global_load_dword v81, v[8:9], off
	v_lshl_add_u64 v[8:9], v[8:9], 0, s[14:15]
	global_load_dword v82, v[8:9], off
	v_lshl_add_u64 v[8:9], v[8:9], 0, s[14:15]
	global_load_dword v83, v[8:9], off
	v_lshl_add_u64 v[8:9], v[8:9], 0, s[14:15]
	global_load_dword v84, v[8:9], off
	v_lshl_add_u64 v[8:9], v[8:9], 0, s[14:15]
	global_load_dword v85, v[8:9], off
	v_lshl_add_u64 v[8:9], v[8:9], 0, s[14:15]
	global_load_dword v86, v[8:9], off
	v_lshl_add_u64 v[8:9], v[8:9], 0, s[14:15]
	global_load_dword v87, v[8:9], off
	v_lshl_add_u64 v[8:9], v[8:9], 0, s[14:15]
	global_load_dword v88, v[8:9], off
	v_lshl_add_u64 v[8:9], v[8:9], 0, s[14:15]
	global_load_dword v89, v[8:9], off
	v_lshl_add_u64 v[8:9], v[8:9], 0, s[14:15]
	global_load_dword v90, v[8:9], off
	v_lshl_add_u64 v[8:9], v[8:9], 0, s[14:15]
	global_load_dword v91, v[8:9], off
	v_lshl_add_u64 v[8:9], v[8:9], 0, s[14:15]
	global_load_dword v92, v[8:9], off
	v_lshl_add_u64 v[8:9], v[8:9], 0, s[14:15]
	global_load_dword v93, v[8:9], off
	v_lshl_add_u64 v[8:9], v[8:9], 0, s[14:15]
	global_load_dword v94, v[8:9], off
	v_lshl_add_u64 v[8:9], v[8:9], 0, s[14:15]
	global_load_dword v95, v[8:9], off
	v_lshl_add_u64 v[8:9], v[8:9], 0, s[14:15]
	global_load_dword v96, v[8:9], off
	v_lshl_add_u64 v[8:9], v[8:9], 0, s[14:15]
	global_load_dword v97, v[8:9], off
	v_lshl_add_u64 v[8:9], v[8:9], 0, s[14:15]
	global_load_dword v98, v[8:9], off
	v_lshl_add_u64 v[8:9], v[8:9], 0, s[14:15]
	global_load_dword v99, v[8:9], off
	v_lshl_add_u64 v[8:9], v[8:9], 0, s[14:15]
	global_load_dword v100, v[8:9], off
	v_lshl_add_u64 v[8:9], v[8:9], 0, s[14:15]
	global_load_dword v101, v[8:9], off
	v_lshl_add_u64 v[8:9], v[8:9], 0, s[14:15]
	global_load_dword v102, v[8:9], off
	v_lshl_add_u64 v[8:9], v[8:9], 0, s[14:15]
	global_load_dword v103, v[8:9], off
	v_lshl_add_u64 v[8:9], v[8:9], 0, s[14:15]
	global_load_dword v104, v[8:9], off
	v_lshl_add_u64 v[8:9], v[8:9], 0, s[14:15]
	global_load_dword v105, v[8:9], off
	v_lshl_add_u64 v[8:9], v[8:9], 0, s[14:15]
	global_load_dword v106, v[8:9], off
	v_lshl_add_u64 v[8:9], v[8:9], 0, s[14:15]
	global_load_dword v107, v[8:9], off
	v_lshl_add_u64 v[8:9], v[8:9], 0, s[14:15]
	global_load_dword v108, v[8:9], off
	v_lshl_add_u64 v[8:9], v[8:9], 0, s[14:15]
	global_load_dword v109, v[8:9], off
	v_lshl_add_u64 v[8:9], v[8:9], 0, s[14:15]
	global_load_dword v110, v[8:9], off
	v_lshl_add_u64 v[8:9], v[8:9], 0, s[14:15]
	global_load_dword v111, v[8:9], off
	v_lshl_add_u64 v[8:9], v[8:9], 0, s[14:15]
	global_load_dword v112, v[8:9], off
	v_lshl_add_u64 v[8:9], v[8:9], 0, s[14:15]
	global_load_dword v113, v[8:9], off
	v_lshl_add_u64 v[8:9], v[8:9], 0, s[14:15]
	global_load_dword v114, v[8:9], off
	v_lshl_add_u64 v[8:9], v[8:9], 0, s[14:15]
	global_load_dword v115, v[8:9], off
	v_lshl_add_u64 v[8:9], v[8:9], 0, s[14:15]
	global_load_dword v116, v[8:9], off
	v_lshl_add_u64 v[8:9], v[8:9], 0, s[14:15]
	global_load_dword v117, v[8:9], off
	v_lshl_add_u64 v[8:9], v[8:9], 0, s[14:15]
	global_load_dword v118, v[8:9], off
	v_lshl_add_u64 v[8:9], v[8:9], 0, s[14:15]
	global_load_dword v119, v[8:9], off
	v_lshl_add_u64 v[8:9], v[8:9], 0, s[14:15]
	global_load_dword v120, v[8:9], off
	v_lshl_add_u64 v[8:9], v[8:9], 0, s[14:15]
	global_load_dword v121, v[8:9], off
	v_lshl_add_u64 v[8:9], v[8:9], 0, s[14:15]
	global_load_dword v122, v[8:9], off
	v_lshl_add_u64 v[8:9], v[8:9], 0, s[14:15]
	global_load_dword v123, v[8:9], off
	v_lshl_add_u64 v[8:9], v[8:9], 0, s[14:15]
	global_load_dword v124, v[8:9], off
	v_lshl_add_u64 v[8:9], v[8:9], 0, s[14:15]
	global_load_dword v125, v[8:9], off
	v_lshl_add_u64 v[8:9], v[8:9], 0, s[14:15]
	global_load_dword v126, v[8:9], off
	v_lshl_add_u64 v[8:9], v[8:9], 0, s[14:15]
	global_load_dword v127, v[8:9], off
	v_lshl_add_u64 v[8:9], v[8:9], 0, s[14:15]
	global_load_dword v128, v[8:9], off
	v_lshl_add_u64 v[8:9], v[8:9], 0, s[14:15]
	global_load_dword v129, v[8:9], off
	v_lshl_add_u64 v[8:9], v[8:9], 0, s[14:15]
	global_load_dword v130, v[8:9], off
	v_lshl_add_u64 v[8:9], v[8:9], 0, s[14:15]
	global_load_dword v131, v[8:9], off
	v_lshl_add_u64 v[8:9], v[8:9], 0, s[14:15]
	global_load_dword v132, v[8:9], off
	v_lshl_add_u64 v[8:9], v[8:9], 0, s[14:15]
	global_load_dword v133, v[8:9], off
	v_lshl_add_u64 v[8:9], v[8:9], 0, s[14:15]
	global_load_dword v134, v[8:9], off
	v_lshl_add_u64 v[8:9], v[8:9], 0, s[14:15]
	global_load_dword v135, v[8:9], off
	v_lshl_add_u64 v[8:9], v[8:9], 0, s[14:15]
	global_load_dword v136, v[8:9], off
	v_lshl_add_u64 v[8:9], v[8:9], 0, s[14:15]
	global_load_dword v137, v[8:9], off
	v_lshl_add_u64 v[8:9], v[8:9], 0, s[14:15]
	global_load_dword v138, v[8:9], off
	v_lshl_add_u64 v[8:9], v[8:9], 0, s[14:15]
	global_load_dword v139, v[8:9], off
	v_lshl_add_u64 v[8:9], v[8:9], 0, s[14:15]
	global_load_dword v140, v[8:9], off
	v_lshl_add_u64 v[8:9], v[8:9], 0, s[14:15]
	global_load_dword v141, v[8:9], off
	v_lshl_add_u64 v[8:9], v[8:9], 0, s[14:15]
	global_load_dword v142, v[8:9], off
	v_lshl_add_u64 v[8:9], v[8:9], 0, s[14:15]
	global_load_dword v143, v[8:9], off
	v_lshl_add_u64 v[8:9], v[8:9], 0, s[14:15]
	global_load_dword v144, v[8:9], off
	v_lshl_add_u64 v[8:9], v[8:9], 0, s[14:15]
	global_load_dword v145, v[8:9], off
	v_lshl_add_u64 v[8:9], v[8:9], 0, s[14:15]
	global_load_dword v146, v[8:9], off
	v_lshl_add_u64 v[8:9], v[8:9], 0, s[14:15]
	global_load_dword v147, v[8:9], off
	v_lshl_add_u64 v[8:9], v[8:9], 0, s[14:15]
	global_load_dword v148, v[8:9], off
	v_lshl_add_u64 v[8:9], v[8:9], 0, s[14:15]
	global_load_dword v149, v[8:9], off
	v_lshl_add_u64 v[8:9], v[8:9], 0, s[14:15]
	global_load_dword v150, v[8:9], off
	v_lshl_add_u64 v[8:9], v[8:9], 0, s[14:15]
	global_load_dword v151, v[8:9], off
	v_lshl_add_u64 v[8:9], v[8:9], 0, s[14:15]
	global_load_dword v152, v[8:9], off
	v_lshl_add_u64 v[8:9], v[8:9], 0, s[14:15]
	global_load_dword v153, v[8:9], off
	v_lshl_add_u64 v[8:9], v[8:9], 0, s[14:15]
	global_load_dword v154, v[8:9], off
	v_lshl_add_u64 v[8:9], v[8:9], 0, s[14:15]
	global_load_dword v155, v[8:9], off
	v_lshl_add_u64 v[8:9], v[8:9], 0, s[14:15]
	global_load_dword v156, v[8:9], off
	v_lshl_add_u64 v[8:9], v[8:9], 0, s[14:15]
	global_load_dword v157, v[8:9], off
	v_lshl_add_u64 v[8:9], v[8:9], 0, s[14:15]
	global_load_dword v158, v[8:9], off
	v_lshl_add_u64 v[8:9], v[8:9], 0, s[14:15]
	global_load_dword v159, v[8:9], off
	v_lshl_add_u64 v[8:9], v[8:9], 0, s[14:15]
	global_load_dword v164, v[8:9], off
	v_lshl_add_u64 v[8:9], v[8:9], 0, s[14:15]
	global_load_dword v165, v[8:9], off
	s_and_b64 vcc, exec, vcc
	s_mov_b32 s2, 64
	s_waitcnt vmcnt(63)
	v_readlane_b32 s16, v0, 0
	v_readlane_b32 s17, v3, 0
	v_readlane_b32 s18, v0, 1
	v_readlane_b32 s19, v3, 1
	v_readlane_b32 s20, v0, 2
	v_readlane_b32 s21, v3, 2
	v_fma_f32 v6, v32, s16, v6
	v_fma_f32 v7, v32, s17, v7
	v_readlane_b32 s22, v0, 3
	v_readlane_b32 s23, v3, 3
	v_fma_f32 v6, v33, s18, v6
	v_fma_f32 v7, v33, s19, v7
	v_readlane_b32 s16, v0, 4
	v_readlane_b32 s17, v3, 4
	v_fma_f32 v6, v34, s20, v6
	v_fma_f32 v7, v34, s21, v7
	v_readlane_b32 s18, v0, 5
	v_readlane_b32 s19, v3, 5
	v_fma_f32 v6, v35, s22, v6
	v_fma_f32 v7, v35, s23, v7
	v_readlane_b32 s20, v0, 6
	v_readlane_b32 s21, v3, 6
	v_fma_f32 v6, v36, s16, v6
	v_fma_f32 v7, v36, s17, v7
	v_readlane_b32 s22, v0, 7
	v_readlane_b32 s23, v3, 7
	v_fma_f32 v6, v37, s18, v6
	v_fma_f32 v7, v37, s19, v7
	v_readlane_b32 s16, v0, 8
	v_readlane_b32 s17, v3, 8
	v_fma_f32 v6, v38, s20, v6
	v_fma_f32 v7, v38, s21, v7
	v_readlane_b32 s18, v0, 9
	v_readlane_b32 s19, v3, 9
	v_fma_f32 v6, v39, s22, v6
	v_fma_f32 v7, v39, s23, v7
	v_readlane_b32 s20, v0, 10
	v_readlane_b32 s21, v3, 10
	v_fma_f32 v6, v40, s16, v6
	v_fma_f32 v7, v40, s17, v7
	v_readlane_b32 s22, v0, 11
	v_readlane_b32 s23, v3, 11
	v_fma_f32 v6, v41, s18, v6
	v_fma_f32 v7, v41, s19, v7
	v_readlane_b32 s16, v0, 12
	v_readlane_b32 s17, v3, 12
	v_fma_f32 v6, v42, s20, v6
	v_fma_f32 v7, v42, s21, v7
	v_readlane_b32 s18, v0, 13
	v_readlane_b32 s19, v3, 13
	v_fma_f32 v6, v43, s22, v6
	v_fma_f32 v7, v43, s23, v7
	v_readlane_b32 s20, v0, 14
	v_readlane_b32 s21, v3, 14
	v_fma_f32 v6, v44, s16, v6
	v_fma_f32 v7, v44, s17, v7
	v_readlane_b32 s22, v0, 15
	v_readlane_b32 s23, v3, 15
	v_fma_f32 v6, v45, s18, v6
	v_fma_f32 v7, v45, s19, v7
	v_readlane_b32 s16, v0, 16
	v_readlane_b32 s17, v3, 16
	v_fma_f32 v6, v46, s20, v6
	v_fma_f32 v7, v46, s21, v7
	v_readlane_b32 s18, v0, 17
	v_readlane_b32 s19, v3, 17
	v_fma_f32 v6, v47, s22, v6
	v_fma_f32 v7, v47, s23, v7
	v_readlane_b32 s20, v0, 18
	v_readlane_b32 s21, v3, 18
	v_fma_f32 v6, v48, s16, v6
	v_fma_f32 v7, v48, s17, v7
	v_readlane_b32 s22, v0, 19
	v_readlane_b32 s23, v3, 19
	v_fma_f32 v6, v49, s18, v6
	v_fma_f32 v7, v49, s19, v7
	v_readlane_b32 s16, v0, 20
	v_readlane_b32 s17, v3, 20
	v_fma_f32 v6, v50, s20, v6
	v_fma_f32 v7, v50, s21, v7
	v_readlane_b32 s18, v0, 21
	v_readlane_b32 s19, v3, 21
	v_fma_f32 v6, v51, s22, v6
	v_fma_f32 v7, v51, s23, v7
	v_readlane_b32 s20, v0, 22
	v_readlane_b32 s21, v3, 22
	v_fma_f32 v6, v52, s16, v6
	v_fma_f32 v7, v52, s17, v7
	v_readlane_b32 s22, v0, 23
	v_readlane_b32 s23, v3, 23
	v_fma_f32 v6, v53, s18, v6
	v_fma_f32 v7, v53, s19, v7
	v_readlane_b32 s16, v0, 24
	v_readlane_b32 s17, v3, 24
	v_fma_f32 v6, v54, s20, v6
	v_fma_f32 v7, v54, s21, v7
	v_readlane_b32 s18, v0, 25
	v_readlane_b32 s19, v3, 25
	v_fma_f32 v6, v55, s22, v6
	v_fma_f32 v7, v55, s23, v7
	v_readlane_b32 s20, v0, 26
	v_readlane_b32 s21, v3, 26
	v_fma_f32 v6, v58, s16, v6
	v_fma_f32 v7, v58, s17, v7
	v_readlane_b32 s22, v0, 27
	v_readlane_b32 s23, v3, 27
	v_fma_f32 v6, v59, s18, v6
	v_fma_f32 v7, v59, s19, v7
	v_readlane_b32 s16, v0, 28
	v_readlane_b32 s17, v3, 28
	v_fma_f32 v6, v60, s20, v6
	v_fma_f32 v7, v60, s21, v7
	v_readlane_b32 s18, v0, 29
	v_readlane_b32 s19, v3, 29
	v_fma_f32 v6, v61, s22, v6
	v_fma_f32 v7, v61, s23, v7
	v_readlane_b32 s20, v0, 30
	v_readlane_b32 s21, v3, 30
	v_fma_f32 v6, v62, s16, v6
	v_fma_f32 v7, v62, s17, v7
	v_readlane_b32 s22, v0, 31
	v_readlane_b32 s23, v3, 31
	v_fma_f32 v6, v63, s18, v6
	v_fma_f32 v7, v63, s19, v7
	v_readlane_b32 s16, v0, 32
	v_readlane_b32 s17, v3, 32
	v_fma_f32 v6, v64, s20, v6
	v_fma_f32 v7, v64, s21, v7
	v_readlane_b32 s18, v0, 33
	v_readlane_b32 s19, v3, 33
	v_fma_f32 v6, v65, s22, v6
	v_fma_f32 v7, v65, s23, v7
	v_readlane_b32 s20, v0, 34
	v_readlane_b32 s21, v3, 34
	v_fma_f32 v6, v66, s16, v6
	v_fma_f32 v7, v66, s17, v7
	v_readlane_b32 s22, v0, 35
	v_readlane_b32 s23, v3, 35
	v_fma_f32 v6, v67, s18, v6
	v_fma_f32 v7, v67, s19, v7
	v_readlane_b32 s16, v0, 36
	v_readlane_b32 s17, v3, 36
	v_fma_f32 v6, v68, s20, v6
	v_fma_f32 v7, v68, s21, v7
	v_readlane_b32 s18, v0, 37
	v_readlane_b32 s19, v3, 37
	v_fma_f32 v6, v69, s22, v6
	v_fma_f32 v7, v69, s23, v7
	v_readlane_b32 s20, v0, 38
	v_readlane_b32 s21, v3, 38
	v_fma_f32 v6, v70, s16, v6
	v_fma_f32 v7, v70, s17, v7
	v_readlane_b32 s22, v0, 39
	v_readlane_b32 s23, v3, 39
	v_fma_f32 v6, v71, s18, v6
	v_fma_f32 v7, v71, s19, v7
	v_readlane_b32 s16, v0, 40
	v_readlane_b32 s17, v3, 40
	v_fma_f32 v6, v72, s20, v6
	v_fma_f32 v7, v72, s21, v7
	v_readlane_b32 s18, v0, 41
	v_readlane_b32 s19, v3, 41
	v_fma_f32 v6, v73, s22, v6
	v_fma_f32 v7, v73, s23, v7
	v_readlane_b32 s20, v0, 42
	v_readlane_b32 s21, v3, 42
	v_fma_f32 v6, v74, s16, v6
	v_fma_f32 v7, v74, s17, v7
	v_readlane_b32 s22, v0, 43
	v_readlane_b32 s23, v3, 43
	v_fma_f32 v6, v75, s18, v6
	v_fma_f32 v7, v75, s19, v7
	v_readlane_b32 s16, v0, 44
	v_readlane_b32 s17, v3, 44
	v_fma_f32 v6, v76, s20, v6
	v_fma_f32 v7, v76, s21, v7
	v_readlane_b32 s18, v0, 45
	v_readlane_b32 s19, v3, 45
	v_fma_f32 v6, v77, s22, v6
	v_fma_f32 v7, v77, s23, v7
	v_readlane_b32 s20, v0, 46
	v_readlane_b32 s21, v3, 46
	v_fma_f32 v6, v78, s16, v6
	v_fma_f32 v7, v78, s17, v7
	v_readlane_b32 s22, v0, 47
	v_readlane_b32 s23, v3, 47
	v_fma_f32 v6, v79, s18, v6
	v_fma_f32 v7, v79, s19, v7
	v_readlane_b32 s16, v0, 48
	v_readlane_b32 s17, v3, 48
	v_fma_f32 v6, v80, s20, v6
	v_fma_f32 v7, v80, s21, v7
	v_readlane_b32 s18, v0, 49
	v_readlane_b32 s19, v3, 49
	v_fma_f32 v6, v81, s22, v6
	v_fma_f32 v7, v81, s23, v7
	v_readlane_b32 s20, v0, 50
	v_readlane_b32 s21, v3, 50
	v_fma_f32 v6, v82, s16, v6
	v_fma_f32 v7, v82, s17, v7
	v_readlane_b32 s22, v0, 51
	v_readlane_b32 s23, v3, 51
	v_fma_f32 v6, v83, s18, v6
	v_fma_f32 v7, v83, s19, v7
	v_readlane_b32 s16, v0, 52
	v_readlane_b32 s17, v3, 52
	v_fma_f32 v6, v84, s20, v6
	v_fma_f32 v7, v84, s21, v7
	v_readlane_b32 s18, v0, 53
	v_readlane_b32 s19, v3, 53
	v_fma_f32 v6, v85, s22, v6
	v_fma_f32 v7, v85, s23, v7
	v_readlane_b32 s20, v0, 54
	v_readlane_b32 s21, v3, 54
	v_fma_f32 v6, v86, s16, v6
	v_fma_f32 v7, v86, s17, v7
	v_readlane_b32 s22, v0, 55
	v_readlane_b32 s23, v3, 55
	v_fma_f32 v6, v87, s18, v6
	v_fma_f32 v7, v87, s19, v7
	v_readlane_b32 s16, v0, 56
	v_readlane_b32 s17, v3, 56
	v_fma_f32 v6, v88, s20, v6
	v_fma_f32 v7, v88, s21, v7
	v_readlane_b32 s18, v0, 57
	v_readlane_b32 s19, v3, 57
	v_fma_f32 v6, v89, s22, v6
	v_fma_f32 v7, v89, s23, v7
	v_readlane_b32 s20, v0, 58
	v_readlane_b32 s21, v3, 58
	v_fma_f32 v6, v90, s16, v6
	v_fma_f32 v7, v90, s17, v7
	v_readlane_b32 s22, v0, 59
	v_readlane_b32 s23, v3, 59
	v_fma_f32 v6, v91, s18, v6
	v_fma_f32 v7, v91, s19, v7
	v_readlane_b32 s16, v0, 60
	v_readlane_b32 s17, v3, 60
	v_fma_f32 v6, v92, s20, v6
	v_fma_f32 v7, v92, s21, v7
	v_readlane_b32 s18, v0, 61
	v_readlane_b32 s19, v3, 61
	v_fma_f32 v6, v93, s22, v6
	v_fma_f32 v7, v93, s23, v7
	v_readlane_b32 s20, v0, 62
	v_readlane_b32 s21, v3, 62
	v_fma_f32 v6, v94, s16, v6
	v_fma_f32 v7, v94, s17, v7
	v_readlane_b32 s22, v0, 63
	v_readlane_b32 s23, v3, 63
	v_fma_f32 v6, v95, s18, v6
	v_fma_f32 v7, v95, s19, v7
	v_readlane_b32 s16, v28, 0
	v_readlane_b32 s17, v29, 0
	v_fma_f32 v6, v96, s20, v6
	v_fma_f32 v7, v96, s21, v7
	v_readlane_b32 s18, v28, 1
	v_readlane_b32 s19, v29, 1
	v_fma_f32 v6, v97, s22, v6
	v_fma_f32 v7, v97, s23, v7
	v_readlane_b32 s20, v28, 2
	v_readlane_b32 s21, v29, 2
	v_fma_f32 v6, v98, s16, v6
	v_fma_f32 v7, v98, s17, v7
	v_readlane_b32 s22, v28, 3
	v_readlane_b32 s23, v29, 3
	s_waitcnt vmcnt(62)
	v_fma_f32 v6, v99, s18, v6
	v_fma_f32 v7, v99, s19, v7
	v_readlane_b32 s16, v28, 4
	v_readlane_b32 s17, v29, 4
	s_waitcnt vmcnt(61)
	v_fma_f32 v6, v100, s20, v6
	v_fma_f32 v7, v100, s21, v7
	v_readlane_b32 s18, v28, 5
	v_readlane_b32 s19, v29, 5
	s_waitcnt vmcnt(60)
	v_fma_f32 v6, v101, s22, v6
	v_fma_f32 v7, v101, s23, v7
	v_readlane_b32 s20, v28, 6
	v_readlane_b32 s21, v29, 6
	s_waitcnt vmcnt(59)
	v_fma_f32 v6, v102, s16, v6
	v_fma_f32 v7, v102, s17, v7
	v_readlane_b32 s22, v28, 7
	v_readlane_b32 s23, v29, 7
	s_waitcnt vmcnt(58)
	v_fma_f32 v6, v103, s18, v6
	v_fma_f32 v7, v103, s19, v7
	v_readlane_b32 s16, v28, 8
	v_readlane_b32 s17, v29, 8
	s_waitcnt vmcnt(57)
	v_fma_f32 v6, v104, s20, v6
	v_fma_f32 v7, v104, s21, v7
	v_readlane_b32 s18, v28, 9
	v_readlane_b32 s19, v29, 9
	s_waitcnt vmcnt(56)
	v_fma_f32 v6, v105, s22, v6
	v_fma_f32 v7, v105, s23, v7
	v_readlane_b32 s20, v28, 10
	v_readlane_b32 s21, v29, 10
	s_waitcnt vmcnt(55)
	v_fma_f32 v6, v106, s16, v6
	v_fma_f32 v7, v106, s17, v7
	v_readlane_b32 s22, v28, 11
	v_readlane_b32 s23, v29, 11
	s_waitcnt vmcnt(54)
	v_fma_f32 v6, v107, s18, v6
	v_fma_f32 v7, v107, s19, v7
	v_readlane_b32 s16, v28, 12
	v_readlane_b32 s17, v29, 12
	s_waitcnt vmcnt(53)
	v_fma_f32 v6, v108, s20, v6
	v_fma_f32 v7, v108, s21, v7
	v_readlane_b32 s18, v28, 13
	v_readlane_b32 s19, v29, 13
	s_waitcnt vmcnt(52)
	v_fma_f32 v6, v109, s22, v6
	v_fma_f32 v7, v109, s23, v7
	v_readlane_b32 s20, v28, 14
	v_readlane_b32 s21, v29, 14
	s_waitcnt vmcnt(51)
	v_fma_f32 v6, v110, s16, v6
	v_fma_f32 v7, v110, s17, v7
	v_readlane_b32 s22, v28, 15
	v_readlane_b32 s23, v29, 15
	s_waitcnt vmcnt(50)
	v_fma_f32 v6, v111, s18, v6
	v_fma_f32 v7, v111, s19, v7
	v_readlane_b32 s16, v28, 16
	v_readlane_b32 s17, v29, 16
	s_waitcnt vmcnt(49)
	v_fma_f32 v6, v112, s20, v6
	v_fma_f32 v7, v112, s21, v7
	v_readlane_b32 s18, v28, 17
	v_readlane_b32 s19, v29, 17
	s_waitcnt vmcnt(48)
	v_fma_f32 v6, v113, s22, v6
	v_fma_f32 v7, v113, s23, v7
	v_readlane_b32 s20, v28, 18
	v_readlane_b32 s21, v29, 18
	s_waitcnt vmcnt(47)
	v_fma_f32 v6, v114, s16, v6
	v_fma_f32 v7, v114, s17, v7
	v_readlane_b32 s22, v28, 19
	v_readlane_b32 s23, v29, 19
	s_waitcnt vmcnt(46)
	v_fma_f32 v6, v115, s18, v6
	v_fma_f32 v7, v115, s19, v7
	v_readlane_b32 s16, v28, 20
	v_readlane_b32 s17, v29, 20
	s_waitcnt vmcnt(45)
	v_fma_f32 v6, v116, s20, v6
	v_fma_f32 v7, v116, s21, v7
	v_readlane_b32 s18, v28, 21
	v_readlane_b32 s19, v29, 21
	s_waitcnt vmcnt(44)
	v_fma_f32 v6, v117, s22, v6
	v_fma_f32 v7, v117, s23, v7
	v_readlane_b32 s20, v28, 22
	v_readlane_b32 s21, v29, 22
	s_waitcnt vmcnt(43)
	v_fma_f32 v6, v118, s16, v6
	v_fma_f32 v7, v118, s17, v7
	v_readlane_b32 s22, v28, 23
	v_readlane_b32 s23, v29, 23
	s_waitcnt vmcnt(42)
	v_fma_f32 v6, v119, s18, v6
	v_fma_f32 v7, v119, s19, v7
	v_readlane_b32 s16, v28, 24
	v_readlane_b32 s17, v29, 24
	s_waitcnt vmcnt(41)
	v_fma_f32 v6, v120, s20, v6
	v_fma_f32 v7, v120, s21, v7
	v_readlane_b32 s18, v28, 25
	v_readlane_b32 s19, v29, 25
	s_waitcnt vmcnt(40)
	v_fma_f32 v6, v121, s22, v6
	v_fma_f32 v7, v121, s23, v7
	v_readlane_b32 s20, v28, 26
	v_readlane_b32 s21, v29, 26
	s_waitcnt vmcnt(39)
	v_fma_f32 v6, v122, s16, v6
	v_fma_f32 v7, v122, s17, v7
	v_readlane_b32 s22, v28, 27
	v_readlane_b32 s23, v29, 27
	s_waitcnt vmcnt(38)
	v_fma_f32 v6, v123, s18, v6
	v_fma_f32 v7, v123, s19, v7
	v_readlane_b32 s16, v28, 28
	v_readlane_b32 s17, v29, 28
	s_waitcnt vmcnt(37)
	v_fma_f32 v6, v124, s20, v6
	v_fma_f32 v7, v124, s21, v7
	v_readlane_b32 s18, v28, 29
	v_readlane_b32 s19, v29, 29
	s_waitcnt vmcnt(36)
	v_fma_f32 v6, v125, s22, v6
	v_fma_f32 v7, v125, s23, v7
	v_readlane_b32 s20, v28, 30
	v_readlane_b32 s21, v29, 30
	s_waitcnt vmcnt(35)
	v_fma_f32 v6, v126, s16, v6
	v_fma_f32 v7, v126, s17, v7
	v_readlane_b32 s22, v28, 31
	v_readlane_b32 s23, v29, 31
	s_waitcnt vmcnt(34)
	v_fma_f32 v6, v127, s18, v6
	v_fma_f32 v7, v127, s19, v7
	v_readlane_b32 s16, v28, 32
	v_readlane_b32 s17, v29, 32
	s_waitcnt vmcnt(33)
	v_fma_f32 v6, v128, s20, v6
	v_fma_f32 v7, v128, s21, v7
	v_readlane_b32 s18, v28, 33
	v_readlane_b32 s19, v29, 33
	s_waitcnt vmcnt(32)
	v_fma_f32 v6, v129, s22, v6
	v_fma_f32 v7, v129, s23, v7
	v_readlane_b32 s20, v28, 34
	v_readlane_b32 s21, v29, 34
	s_waitcnt vmcnt(31)
	v_fma_f32 v6, v130, s16, v6
	v_fma_f32 v7, v130, s17, v7
	v_readlane_b32 s22, v28, 35
	v_readlane_b32 s23, v29, 35
	s_waitcnt vmcnt(30)
	v_fma_f32 v6, v131, s18, v6
	v_fma_f32 v7, v131, s19, v7
	v_readlane_b32 s16, v28, 36
	v_readlane_b32 s17, v29, 36
	s_waitcnt vmcnt(29)
	v_fma_f32 v6, v132, s20, v6
	v_fma_f32 v7, v132, s21, v7
	v_readlane_b32 s18, v28, 37
	v_readlane_b32 s19, v29, 37
	s_waitcnt vmcnt(28)
	v_fma_f32 v6, v133, s22, v6
	v_fma_f32 v7, v133, s23, v7
	v_readlane_b32 s20, v28, 38
	v_readlane_b32 s21, v29, 38
	s_waitcnt vmcnt(27)
	v_fma_f32 v6, v134, s16, v6
	v_fma_f32 v7, v134, s17, v7
	v_readlane_b32 s22, v28, 39
	v_readlane_b32 s23, v29, 39
	s_waitcnt vmcnt(26)
	v_fma_f32 v6, v135, s18, v6
	v_fma_f32 v7, v135, s19, v7
	v_readlane_b32 s16, v28, 40
	v_readlane_b32 s17, v29, 40
	s_waitcnt vmcnt(25)
	v_fma_f32 v6, v136, s20, v6
	v_fma_f32 v7, v136, s21, v7
	v_readlane_b32 s18, v28, 41
	v_readlane_b32 s19, v29, 41
	s_waitcnt vmcnt(24)
	v_fma_f32 v6, v137, s22, v6
	v_fma_f32 v7, v137, s23, v7
	v_readlane_b32 s20, v28, 42
	v_readlane_b32 s21, v29, 42
	s_waitcnt vmcnt(23)
	v_fma_f32 v6, v138, s16, v6
	v_fma_f32 v7, v138, s17, v7
	v_readlane_b32 s22, v28, 43
	v_readlane_b32 s23, v29, 43
	s_waitcnt vmcnt(22)
	v_fma_f32 v6, v139, s18, v6
	v_fma_f32 v7, v139, s19, v7
	v_readlane_b32 s16, v28, 44
	v_readlane_b32 s17, v29, 44
	s_waitcnt vmcnt(21)
	v_fma_f32 v6, v140, s20, v6
	v_fma_f32 v7, v140, s21, v7
	v_readlane_b32 s18, v28, 45
	v_readlane_b32 s19, v29, 45
	s_waitcnt vmcnt(20)
	v_fma_f32 v6, v141, s22, v6
	v_fma_f32 v7, v141, s23, v7
	v_readlane_b32 s20, v28, 46
	v_readlane_b32 s21, v29, 46
	s_waitcnt vmcnt(19)
	v_fma_f32 v6, v142, s16, v6
	v_fma_f32 v7, v142, s17, v7
	v_readlane_b32 s22, v28, 47
	v_readlane_b32 s23, v29, 47
	s_waitcnt vmcnt(18)
	v_fma_f32 v6, v143, s18, v6
	v_fma_f32 v7, v143, s19, v7
	v_readlane_b32 s16, v28, 48
	v_readlane_b32 s17, v29, 48
	s_waitcnt vmcnt(17)
	v_fma_f32 v6, v144, s20, v6
	v_fma_f32 v7, v144, s21, v7
	v_readlane_b32 s18, v28, 49
	v_readlane_b32 s19, v29, 49
	s_waitcnt vmcnt(16)
	v_fma_f32 v6, v145, s22, v6
	v_fma_f32 v7, v145, s23, v7
	v_readlane_b32 s20, v28, 50
	v_readlane_b32 s21, v29, 50
	s_waitcnt vmcnt(15)
	v_fma_f32 v6, v146, s16, v6
	v_fma_f32 v7, v146, s17, v7
	v_readlane_b32 s22, v28, 51
	v_readlane_b32 s23, v29, 51
	s_waitcnt vmcnt(14)
	v_fma_f32 v6, v147, s18, v6
	v_fma_f32 v7, v147, s19, v7
	v_readlane_b32 s16, v28, 52
	v_readlane_b32 s17, v29, 52
	s_waitcnt vmcnt(13)
	v_fma_f32 v6, v148, s20, v6
	v_fma_f32 v7, v148, s21, v7
	v_readlane_b32 s18, v28, 53
	v_readlane_b32 s19, v29, 53
	s_waitcnt vmcnt(12)
	v_fma_f32 v6, v149, s22, v6
	v_fma_f32 v7, v149, s23, v7
	v_readlane_b32 s20, v28, 54
	v_readlane_b32 s21, v29, 54
	s_waitcnt vmcnt(11)
	v_fma_f32 v6, v150, s16, v6
	v_fma_f32 v7, v150, s17, v7
	v_readlane_b32 s22, v28, 55
	v_readlane_b32 s23, v29, 55
	s_waitcnt vmcnt(10)
	v_fma_f32 v6, v151, s18, v6
	v_fma_f32 v7, v151, s19, v7
	v_readlane_b32 s16, v28, 56
	v_readlane_b32 s17, v29, 56
	s_waitcnt vmcnt(9)
	v_fma_f32 v6, v152, s20, v6
	v_fma_f32 v7, v152, s21, v7
	v_readlane_b32 s18, v28, 57
	v_readlane_b32 s19, v29, 57
	s_waitcnt vmcnt(8)
	v_fma_f32 v6, v153, s22, v6
	v_fma_f32 v7, v153, s23, v7
	v_readlane_b32 s20, v28, 58
	v_readlane_b32 s21, v29, 58
	s_waitcnt vmcnt(7)
	v_fma_f32 v6, v154, s16, v6
	v_fma_f32 v7, v154, s17, v7
	v_readlane_b32 s22, v28, 59
	v_readlane_b32 s23, v29, 59
	s_waitcnt vmcnt(6)
	v_fma_f32 v6, v155, s18, v6
	v_fma_f32 v7, v155, s19, v7
	v_readlane_b32 s16, v28, 60
	v_readlane_b32 s17, v29, 60
	s_waitcnt vmcnt(5)
	v_fma_f32 v6, v156, s20, v6
	v_fma_f32 v7, v156, s21, v7
	v_readlane_b32 s18, v28, 61
	v_readlane_b32 s19, v29, 61
	s_waitcnt vmcnt(4)
	v_fma_f32 v6, v157, s22, v6
	v_fma_f32 v7, v157, s23, v7
	v_readlane_b32 s20, v28, 62
	v_readlane_b32 s21, v29, 62
	s_waitcnt vmcnt(3)
	v_fma_f32 v6, v158, s16, v6
	v_fma_f32 v7, v158, s17, v7
	v_readlane_b32 s22, v28, 63
	v_readlane_b32 s23, v29, 63
	s_waitcnt vmcnt(2)
	v_fma_f32 v6, v159, s18, v6
	v_fma_f32 v7, v159, s19, v7
	s_waitcnt vmcnt(1)
	v_fma_f32 v6, v164, s20, v6
	v_fma_f32 v7, v164, s21, v7
	s_waitcnt vmcnt(0)
	v_fma_f32 v6, v165, s22, v6
	v_fma_f32 v7, v165, s23, v7
	s_mov_b64 s[0:1], 0
	s_and_saveexec_b64 s[0:1], s[6:7]
	s_cbranch_execz .LBB0_696
	v_ashrrev_i32_e32 v3, 31, v2
	v_readlane_b32 s2, v250, 54
	v_lshlrev_b64 v[2:3], 2, v[2:3]
	v_readlane_b32 s3, v250, 55
	s_nop 1
	v_lshl_add_u64 v[4:5], s[2:3], 0, v[2:3]
	v_readlane_b32 s2, v250, 42
	v_readlane_b32 s3, v250, 43
	s_nop 1
	v_lshl_add_u64 v[2:3], s[2:3], 0, v[2:3]
	global_atomic_add_f32 v[2:3], v6, off
	global_atomic_add_f32 v[4:5], v7, off
	s_branch .LBB0_696

.LBB0_722:
	v_cndmask_b32_e64 v0, 0, 1, s[0:1]
	v_cmp_ne_u32_e32 vcc, 1, v0
	v_or_b32_e32 v0, s11, v10
	v_lshlrev_b64 v[8:9], 2, v[0:1]
	s_lshl_b32 s90, s11, 10
	v_lshl_add_u64 v[12:13], s[2:3], 0, v[8:9]
	v_lshl_add_u64 v[8:9], s[4:5], 0, v[8:9]
	global_load_dword v3, v[12:13], off
	global_load_dword v11, v[8:9], off
	global_load_dword v28, v[12:13], off offset:256
	global_load_dword v29, v[8:9], off offset:256
	v_lshl_add_u64 v[8:9], s[90:91], 2, v[4:5]
	s_mov_b32 s14, 0x1000
	s_mov_b32 s15, 0
	global_load_dword v32, v[8:9], off
	v_lshl_add_u64 v[8:9], v[8:9], 0, s[14:15]
	global_load_dword v33, v[8:9], off
	v_lshl_add_u64 v[8:9], v[8:9], 0, s[14:15]
	global_load_dword v34, v[8:9], off
	v_lshl_add_u64 v[8:9], v[8:9], 0, s[14:15]
	global_load_dword v35, v[8:9], off
	v_lshl_add_u64 v[8:9], v[8:9], 0, s[14:15]
	global_load_dword v36, v[8:9], off
	v_lshl_add_u64 v[8:9], v[8:9], 0, s[14:15]
	global_load_dword v37, v[8:9], off
	v_lshl_add_u64 v[8:9], v[8:9], 0, s[14:15]
	global_load_dword v38, v[8:9], off
	v_lshl_add_u64 v[8:9], v[8:9], 0, s[14:15]
	global_load_dword v39, v[8:9], off
	v_lshl_add_u64 v[8:9], v[8:9], 0, s[14:15]
	global_load_dword v40, v[8:9], off
	v_lshl_add_u64 v[8:9], v[8:9], 0, s[14:15]
	global_load_dword v41, v[8:9], off
	v_lshl_add_u64 v[8:9], v[8:9], 0, s[14:15]
	global_load_dword v42, v[8:9], off
	v_lshl_add_u64 v[8:9], v[8:9], 0, s[14:15]
	global_load_dword v43, v[8:9], off
	v_lshl_add_u64 v[8:9], v[8:9], 0, s[14:15]
	global_load_dword v44, v[8:9], off
	v_lshl_add_u64 v[8:9], v[8:9], 0, s[14:15]
	global_load_dword v45, v[8:9], off
	v_lshl_add_u64 v[8:9], v[8:9], 0, s[14:15]
	global_load_dword v46, v[8:9], off
	v_lshl_add_u64 v[8:9], v[8:9], 0, s[14:15]
	global_load_dword v47, v[8:9], off
	v_lshl_add_u64 v[8:9], v[8:9], 0, s[14:15]
	global_load_dword v48, v[8:9], off
	v_lshl_add_u64 v[8:9], v[8:9], 0, s[14:15]
	global_load_dword v49, v[8:9], off
	v_lshl_add_u64 v[8:9], v[8:9], 0, s[14:15]
	global_load_dword v50, v[8:9], off
	v_lshl_add_u64 v[8:9], v[8:9], 0, s[14:15]
	global_load_dword v51, v[8:9], off
	v_lshl_add_u64 v[8:9], v[8:9], 0, s[14:15]
	global_load_dword v52, v[8:9], off
	v_lshl_add_u64 v[8:9], v[8:9], 0, s[14:15]
	global_load_dword v53, v[8:9], off
	v_lshl_add_u64 v[8:9], v[8:9], 0, s[14:15]
	global_load_dword v54, v[8:9], off
	v_lshl_add_u64 v[8:9], v[8:9], 0, s[14:15]
	global_load_dword v55, v[8:9], off
	v_lshl_add_u64 v[8:9], v[8:9], 0, s[14:15]
	global_load_dword v58, v[8:9], off
	v_lshl_add_u64 v[8:9], v[8:9], 0, s[14:15]
	global_load_dword v59, v[8:9], off
	v_lshl_add_u64 v[8:9], v[8:9], 0, s[14:15]
	global_load_dword v60, v[8:9], off
	v_lshl_add_u64 v[8:9], v[8:9], 0, s[14:15]
	global_load_dword v61, v[8:9], off
	v_lshl_add_u64 v[8:9], v[8:9], 0, s[14:15]
	global_load_dword v62, v[8:9], off
	v_lshl_add_u64 v[8:9], v[8:9], 0, s[14:15]
	global_load_dword v63, v[8:9], off
	v_lshl_add_u64 v[8:9], v[8:9], 0, s[14:15]
	global_load_dword v64, v[8:9], off
	v_lshl_add_u64 v[8:9], v[8:9], 0, s[14:15]
	global_load_dword v65, v[8:9], off
	v_lshl_add_u64 v[8:9], v[8:9], 0, s[14:15]
	global_load_dword v66, v[8:9], off
	v_lshl_add_u64 v[8:9], v[8:9], 0, s[14:15]
	global_load_dword v67, v[8:9], off
	v_lshl_add_u64 v[8:9], v[8:9], 0, s[14:15]
	global_load_dword v68, v[8:9], off
	v_lshl_add_u64 v[8:9], v[8:9], 0, s[14:15]
	global_load_dword v69, v[8:9], off
	v_lshl_add_u64 v[8:9], v[8:9], 0, s[14:15]
	global_load_dword v70, v[8:9], off
	v_lshl_add_u64 v[8:9], v[8:9], 0, s[14:15]
	global_load_dword v71, v[8:9], off
	v_lshl_add_u64 v[8:9], v[8:9], 0, s[14:15]
	global_load_dword v72, v[8:9], off
	v_lshl_add_u64 v[8:9], v[8:9], 0, s[14:15]
	global_load_dword v73, v[8:9], off
	v_lshl_add_u64 v[8:9], v[8:9], 0, s[14:15]
	global_load_dword v74, v[8:9], off
	v_lshl_add_u64 v[8:9], v[8:9], 0, s[14:15]
	global_load_dword v75, v[8:9], off
	v_lshl_add_u64 v[8:9], v[8:9], 0, s[14:15]
	global_load_dword v76, v[8:9], off
	v_lshl_add_u64 v[8:9], v[8:9], 0, s[14:15]
	global_load_dword v77, v[8:9], off
	v_lshl_add_u64 v[8:9], v[8:9], 0, s[14:15]
	global_load_dword v78, v[8:9], off
	v_lshl_add_u64 v[8:9], v[8:9], 0, s[14:15]
	global_load_dword v79, v[8:9], off
	v_lshl_add_u64 v[8:9], v[8:9], 0, s[14:15]
	global_load_dword v80, v[8:9], off
	v_lshl_add_u64 v[8:9], v[8:9], 0, s[14:15]
	global_load_dword v81, v[8:9], off
	v_lshl_add_u64 v[8:9], v[8:9], 0, s[14:15]
	global_load_dword v82, v[8:9], off
	v_lshl_add_u64 v[8:9], v[8:9], 0, s[14:15]
	global_load_dword v83, v[8:9], off
	v_lshl_add_u64 v[8:9], v[8:9], 0, s[14:15]
	global_load_dword v84, v[8:9], off
	v_lshl_add_u64 v[8:9], v[8:9], 0, s[14:15]
	global_load_dword v85, v[8:9], off
	v_lshl_add_u64 v[8:9], v[8:9], 0, s[14:15]
	global_load_dword v86, v[8:9], off
	v_lshl_add_u64 v[8:9], v[8:9], 0, s[14:15]
	global_load_dword v87, v[8:9], off
	v_lshl_add_u64 v[8:9], v[8:9], 0, s[14:15]
	global_load_dword v88, v[8:9], off
	v_lshl_add_u64 v[8:9], v[8:9], 0, s[14:15]
	global_load_dword v89, v[8:9], off
	v_lshl_add_u64 v[8:9], v[8:9], 0, s[14:15]
	global_load_dword v90, v[8:9], off
	v_lshl_add_u64 v[8:9], v[8:9], 0, s[14:15]
	global_load_dword v91, v[8:9], off
	v_lshl_add_u64 v[8:9], v[8:9], 0, s[14:15]
	global_load_dword v92, v[8:9], off
	v_lshl_add_u64 v[8:9], v[8:9], 0, s[14:15]
	global_load_dword v93, v[8:9], off
	v_lshl_add_u64 v[8:9], v[8:9], 0, s[14:15]
	global_load_dword v94, v[8:9], off
	v_lshl_add_u64 v[8:9], v[8:9], 0, s[14:15]
	global_load_dword v95, v[8:9], off
	v_lshl_add_u64 v[8:9], v[8:9], 0, s[14:15]
	global_load_dword v96, v[8:9], off
	v_lshl_add_u64 v[8:9], v[8:9], 0, s[14:15]
	global_load_dword v97, v[8:9], off
	v_lshl_add_u64 v[8:9], v[8:9], 0, s[14:15]
	global_load_dword v98, v[8:9], off
	v_lshl_add_u64 v[8:9], v[8:9], 0, s[14:15]
	global_load_dword v99, v[8:9], off
	v_lshl_add_u64 v[8:9], v[8:9], 0, s[14:15]
	global_load_dword v100, v[8:9], off
	v_lshl_add_u64 v[8:9], v[8:9], 0, s[14:15]
	global_load_dword v101, v[8:9], off
	v_lshl_add_u64 v[8:9], v[8:9], 0, s[14:15]
	global_load_dword v102, v[8:9], off
	v_lshl_add_u64 v[8:9], v[8:9], 0, s[14:15]
	global_load_dword v103, v[8:9], off
	v_lshl_add_u64 v[8:9], v[8:9], 0, s[14:15]
	global_load_dword v104, v[8:9], off
	v_lshl_add_u64 v[8:9], v[8:9], 0, s[14:15]
	global_load_dword v105, v[8:9], off
	v_lshl_add_u64 v[8:9], v[8:9], 0, s[14:15]
	global_load_dword v106, v[8:9], off
	v_lshl_add_u64 v[8:9], v[8:9], 0, s[14:15]
	global_load_dword v107, v[8:9], off
	v_lshl_add_u64 v[8:9], v[8:9], 0, s[14:15]
	global_load_dword v108, v[8:9], off
	v_lshl_add_u64 v[8:9], v[8:9], 0, s[14:15]
	global_load_dword v109, v[8:9], off
	v_lshl_add_u64 v[8:9], v[8:9], 0, s[14:15]
	global_load_dword v110, v[8:9], off
	v_lshl_add_u64 v[8:9], v[8:9], 0, s[14:15]
	global_load_dword v111, v[8:9], off
	v_lshl_add_u64 v[8:9], v[8:9], 0, s[14:15]
	global_load_dword v112, v[8:9], off
	v_lshl_add_u64 v[8:9], v[8:9], 0, s[14:15]
	global_load_dword v113, v[8:9], off
	v_lshl_add_u64 v[8:9], v[8:9], 0, s[14:15]
	global_load_dword v114, v[8:9], off
	v_lshl_add_u64 v[8:9], v[8:9], 0, s[14:15]
	global_load_dword v115, v[8:9], off
	v_lshl_add_u64 v[8:9], v[8:9], 0, s[14:15]
	global_load_dword v116, v[8:9], off
	v_lshl_add_u64 v[8:9], v[8:9], 0, s[14:15]
	global_load_dword v117, v[8:9], off
	v_lshl_add_u64 v[8:9], v[8:9], 0, s[14:15]
	global_load_dword v118, v[8:9], off
	v_lshl_add_u64 v[8:9], v[8:9], 0, s[14:15]
	global_load_dword v119, v[8:9], off
	v_lshl_add_u64 v[8:9], v[8:9], 0, s[14:15]
	global_load_dword v120, v[8:9], off
	v_lshl_add_u64 v[8:9], v[8:9], 0, s[14:15]
	global_load_dword v121, v[8:9], off
	v_lshl_add_u64 v[8:9], v[8:9], 0, s[14:15]
	global_load_dword v122, v[8:9], off
	v_lshl_add_u64 v[8:9], v[8:9], 0, s[14:15]
	global_load_dword v123, v[8:9], off
	v_lshl_add_u64 v[8:9], v[8:9], 0, s[14:15]
	global_load_dword v124, v[8:9], off
	v_lshl_add_u64 v[8:9], v[8:9], 0, s[14:15]
	global_load_dword v125, v[8:9], off
	v_lshl_add_u64 v[8:9], v[8:9], 0, s[14:15]
	global_load_dword v126, v[8:9], off
	v_lshl_add_u64 v[8:9], v[8:9], 0, s[14:15]
	global_load_dword v127, v[8:9], off
	v_lshl_add_u64 v[8:9], v[8:9], 0, s[14:15]
	global_load_dword v128, v[8:9], off
	v_lshl_add_u64 v[8:9], v[8:9], 0, s[14:15]
	global_load_dword v129, v[8:9], off
	v_lshl_add_u64 v[8:9], v[8:9], 0, s[14:15]
	global_load_dword v130, v[8:9], off
	v_lshl_add_u64 v[8:9], v[8:9], 0, s[14:15]
	global_load_dword v131, v[8:9], off
	v_lshl_add_u64 v[8:9], v[8:9], 0, s[14:15]
	global_load_dword v132, v[8:9], off
	v_lshl_add_u64 v[8:9], v[8:9], 0, s[14:15]
	global_load_dword v133, v[8:9], off
	v_lshl_add_u64 v[8:9], v[8:9], 0, s[14:15]
	global_load_dword v134, v[8:9], off
	v_lshl_add_u64 v[8:9], v[8:9], 0, s[14:15]
	global_load_dword v135, v[8:9], off
	v_lshl_add_u64 v[8:9], v[8:9], 0, s[14:15]
	global_load_dword v136, v[8:9], off
	v_lshl_add_u64 v[8:9], v[8:9], 0, s[14:15]
	global_load_dword v137, v[8:9], off
	v_lshl_add_u64 v[8:9], v[8:9], 0, s[14:15]
	global_load_dword v138, v[8:9], off
	v_lshl_add_u64 v[8:9], v[8:9], 0, s[14:15]
	global_load_dword v139, v[8:9], off
	v_lshl_add_u64 v[8:9], v[8:9], 0, s[14:15]
	global_load_dword v140, v[8:9], off
	v_lshl_add_u64 v[8:9], v[8:9], 0, s[14:15]
	global_load_dword v141, v[8:9], off
	v_lshl_add_u64 v[8:9], v[8:9], 0, s[14:15]
	global_load_dword v142, v[8:9], off
	v_lshl_add_u64 v[8:9], v[8:9], 0, s[14:15]
	global_load_dword v143, v[8:9], off
	v_lshl_add_u64 v[8:9], v[8:9], 0, s[14:15]
	global_load_dword v144, v[8:9], off
	v_lshl_add_u64 v[8:9], v[8:9], 0, s[14:15]
	global_load_dword v145, v[8:9], off
	v_lshl_add_u64 v[8:9], v[8:9], 0, s[14:15]
	global_load_dword v146, v[8:9], off
	v_lshl_add_u64 v[8:9], v[8:9], 0, s[14:15]
	global_load_dword v147, v[8:9], off
	v_lshl_add_u64 v[8:9], v[8:9], 0, s[14:15]
	global_load_dword v148, v[8:9], off
	v_lshl_add_u64 v[8:9], v[8:9], 0, s[14:15]
	global_load_dword v149, v[8:9], off
	v_lshl_add_u64 v[8:9], v[8:9], 0, s[14:15]
	global_load_dword v150, v[8:9], off
	v_lshl_add_u64 v[8:9], v[8:9], 0, s[14:15]
	global_load_dword v151, v[8:9], off
	v_lshl_add_u64 v[8:9], v[8:9], 0, s[14:15]
	global_load_dword v152, v[8:9], off
	v_lshl_add_u64 v[8:9], v[8:9], 0, s[14:15]
	global_load_dword v153, v[8:9], off
	v_lshl_add_u64 v[8:9], v[8:9], 0, s[14:15]
	global_load_dword v154, v[8:9], off
	v_lshl_add_u64 v[8:9], v[8:9], 0, s[14:15]
	global_load_dword v155, v[8:9], off
	v_lshl_add_u64 v[8:9], v[8:9], 0, s[14:15]
	global_load_dword v156, v[8:9], off
	v_lshl_add_u64 v[8:9], v[8:9], 0, s[14:15]
	global_load_dword v157, v[8:9], off
	v_lshl_add_u64 v[8:9], v[8:9], 0, s[14:15]
	global_load_dword v158, v[8:9], off
	v_lshl_add_u64 v[8:9], v[8:9], 0, s[14:15]
	global_load_dword v159, v[8:9], off
	v_lshl_add_u64 v[8:9], v[8:9], 0, s[14:15]
	global_load_dword v164, v[8:9], off
	v_lshl_add_u64 v[8:9], v[8:9], 0, s[14:15]
	global_load_dword v165, v[8:9], off
	s_mov_b32 s11, 64
	s_and_b64 vcc, exec, vcc
	s_waitcnt vmcnt(63)
	v_readlane_b32 s16, v3, 0
	v_readlane_b32 s17, v11, 0
	v_readlane_b32 s18, v3, 1
	v_readlane_b32 s19, v11, 1
	v_readlane_b32 s20, v3, 2
	v_readlane_b32 s21, v11, 2
	v_fma_f32 v6, v32, s16, v6
	v_fma_f32 v7, v32, s17, v7
	v_readlane_b32 s22, v3, 3
	v_readlane_b32 s23, v11, 3
	v_fma_f32 v6, v33, s18, v6
	v_fma_f32 v7, v33, s19, v7
	v_readlane_b32 s16, v3, 4
	v_readlane_b32 s17, v11, 4
	v_fma_f32 v6, v34, s20, v6
	v_fma_f32 v7, v34, s21, v7
	v_readlane_b32 s18, v3, 5
	v_readlane_b32 s19, v11, 5
	v_fma_f32 v6, v35, s22, v6
	v_fma_f32 v7, v35, s23, v7
	v_readlane_b32 s20, v3, 6
	v_readlane_b32 s21, v11, 6
	v_fma_f32 v6, v36, s16, v6
	v_fma_f32 v7, v36, s17, v7
	v_readlane_b32 s22, v3, 7
	v_readlane_b32 s23, v11, 7
	v_fma_f32 v6, v37, s18, v6
	v_fma_f32 v7, v37, s19, v7
	v_readlane_b32 s16, v3, 8
	v_readlane_b32 s17, v11, 8
	v_fma_f32 v6, v38, s20, v6
	v_fma_f32 v7, v38, s21, v7
	v_readlane_b32 s18, v3, 9
	v_readlane_b32 s19, v11, 9
	v_fma_f32 v6, v39, s22, v6
	v_fma_f32 v7, v39, s23, v7
	v_readlane_b32 s20, v3, 10
	v_readlane_b32 s21, v11, 10
	v_fma_f32 v6, v40, s16, v6
	v_fma_f32 v7, v40, s17, v7
	v_readlane_b32 s22, v3, 11
	v_readlane_b32 s23, v11, 11
	v_fma_f32 v6, v41, s18, v6
	v_fma_f32 v7, v41, s19, v7
	v_readlane_b32 s16, v3, 12
	v_readlane_b32 s17, v11, 12
	v_fma_f32 v6, v42, s20, v6
	v_fma_f32 v7, v42, s21, v7
	v_readlane_b32 s18, v3, 13
	v_readlane_b32 s19, v11, 13
	v_fma_f32 v6, v43, s22, v6
	v_fma_f32 v7, v43, s23, v7
	v_readlane_b32 s20, v3, 14
	v_readlane_b32 s21, v11, 14
	v_fma_f32 v6, v44, s16, v6
	v_fma_f32 v7, v44, s17, v7
	v_readlane_b32 s22, v3, 15
	v_readlane_b32 s23, v11, 15
	v_fma_f32 v6, v45, s18, v6
	v_fma_f32 v7, v45, s19, v7
	v_readlane_b32 s16, v3, 16
	v_readlane_b32 s17, v11, 16
	v_fma_f32 v6, v46, s20, v6
	v_fma_f32 v7, v46, s21, v7
	v_readlane_b32 s18, v3, 17
	v_readlane_b32 s19, v11, 17
	v_fma_f32 v6, v47, s22, v6
	v_fma_f32 v7, v47, s23, v7
	v_readlane_b32 s20, v3, 18
	v_readlane_b32 s21, v11, 18
	v_fma_f32 v6, v48, s16, v6
	v_fma_f32 v7, v48, s17, v7
	v_readlane_b32 s22, v3, 19
	v_readlane_b32 s23, v11, 19
	v_fma_f32 v6, v49, s18, v6
	v_fma_f32 v7, v49, s19, v7
	v_readlane_b32 s16, v3, 20
	v_readlane_b32 s17, v11, 20
	v_fma_f32 v6, v50, s20, v6
	v_fma_f32 v7, v50, s21, v7
	v_readlane_b32 s18, v3, 21
	v_readlane_b32 s19, v11, 21
	v_fma_f32 v6, v51, s22, v6
	v_fma_f32 v7, v51, s23, v7
	v_readlane_b32 s20, v3, 22
	v_readlane_b32 s21, v11, 22
	v_fma_f32 v6, v52, s16, v6
	v_fma_f32 v7, v52, s17, v7
	v_readlane_b32 s22, v3, 23
	v_readlane_b32 s23, v11, 23
	v_fma_f32 v6, v53, s18, v6
	v_fma_f32 v7, v53, s19, v7
	v_readlane_b32 s16, v3, 24
	v_readlane_b32 s17, v11, 24
	v_fma_f32 v6, v54, s20, v6
	v_fma_f32 v7, v54, s21, v7
	v_readlane_b32 s18, v3, 25
	v_readlane_b32 s19, v11, 25
	v_fma_f32 v6, v55, s22, v6
	v_fma_f32 v7, v55, s23, v7
	v_readlane_b32 s20, v3, 26
	v_readlane_b32 s21, v11, 26
	v_fma_f32 v6, v58, s16, v6
	v_fma_f32 v7, v58, s17, v7
	v_readlane_b32 s22, v3, 27
	v_readlane_b32 s23, v11, 27
	v_fma_f32 v6, v59, s18, v6
	v_fma_f32 v7, v59, s19, v7
	v_readlane_b32 s16, v3, 28
	v_readlane_b32 s17, v11, 28
	v_fma_f32 v6, v60, s20, v6
	v_fma_f32 v7, v60, s21, v7
	v_readlane_b32 s18, v3, 29
	v_readlane_b32 s19, v11, 29
	v_fma_f32 v6, v61, s22, v6
	v_fma_f32 v7, v61, s23, v7
	v_readlane_b32 s20, v3, 30
	v_readlane_b32 s21, v11, 30
	v_fma_f32 v6, v62, s16, v6
	v_fma_f32 v7, v62, s17, v7
	v_readlane_b32 s22, v3, 31
	v_readlane_b32 s23, v11, 31
	v_fma_f32 v6, v63, s18, v6
	v_fma_f32 v7, v63, s19, v7
	v_readlane_b32 s16, v3, 32
	v_readlane_b32 s17, v11, 32
	v_fma_f32 v6, v64, s20, v6
	v_fma_f32 v7, v64, s21, v7
	v_readlane_b32 s18, v3, 33
	v_readlane_b32 s19, v11, 33
	v_fma_f32 v6, v65, s22, v6
	v_fma_f32 v7, v65, s23, v7
	v_readlane_b32 s20, v3, 34
	v_readlane_b32 s21, v11, 34
	v_fma_f32 v6, v66, s16, v6
	v_fma_f32 v7, v66, s17, v7
	v_readlane_b32 s22, v3, 35
	v_readlane_b32 s23, v11, 35
	v_fma_f32 v6, v67, s18, v6
	v_fma_f32 v7, v67, s19, v7
	v_readlane_b32 s16, v3, 36
	v_readlane_b32 s17, v11, 36
	v_fma_f32 v6, v68, s20, v6
	v_fma_f32 v7, v68, s21, v7
	v_readlane_b32 s18, v3, 37
	v_readlane_b32 s19, v11, 37
	v_fma_f32 v6, v69, s22, v6
	v_fma_f32 v7, v69, s23, v7
	v_readlane_b32 s20, v3, 38
	v_readlane_b32 s21, v11, 38
	v_fma_f32 v6, v70, s16, v6
	v_fma_f32 v7, v70, s17, v7
	v_readlane_b32 s22, v3, 39
	v_readlane_b32 s23, v11, 39
	v_fma_f32 v6, v71, s18, v6
	v_fma_f32 v7, v71, s19, v7
	v_readlane_b32 s16, v3, 40
	v_readlane_b32 s17, v11, 40
	v_fma_f32 v6, v72, s20, v6
	v_fma_f32 v7, v72, s21, v7
	v_readlane_b32 s18, v3, 41
	v_readlane_b32 s19, v11, 41
	v_fma_f32 v6, v73, s22, v6
	v_fma_f32 v7, v73, s23, v7
	v_readlane_b32 s20, v3, 42
	v_readlane_b32 s21, v11, 42
	v_fma_f32 v6, v74, s16, v6
	v_fma_f32 v7, v74, s17, v7
	v_readlane_b32 s22, v3, 43
	v_readlane_b32 s23, v11, 43
	v_fma_f32 v6, v75, s18, v6
	v_fma_f32 v7, v75, s19, v7
	v_readlane_b32 s16, v3, 44
	v_readlane_b32 s17, v11, 44
	v_fma_f32 v6, v76, s20, v6
	v_fma_f32 v7, v76, s21, v7
	v_readlane_b32 s18, v3, 45
	v_readlane_b32 s19, v11, 45
	v_fma_f32 v6, v77, s22, v6
	v_fma_f32 v7, v77, s23, v7
	v_readlane_b32 s20, v3, 46
	v_readlane_b32 s21, v11, 46
	v_fma_f32 v6, v78, s16, v6
	v_fma_f32 v7, v78, s17, v7
	v_readlane_b32 s22, v3, 47
	v_readlane_b32 s23, v11, 47
	v_fma_f32 v6, v79, s18, v6
	v_fma_f32 v7, v79, s19, v7
	v_readlane_b32 s16, v3, 48
	v_readlane_b32 s17, v11, 48
	v_fma_f32 v6, v80, s20, v6
	v_fma_f32 v7, v80, s21, v7
	v_readlane_b32 s18, v3, 49
	v_readlane_b32 s19, v11, 49
	v_fma_f32 v6, v81, s22, v6
	v_fma_f32 v7, v81, s23, v7
	v_readlane_b32 s20, v3, 50
	v_readlane_b32 s21, v11, 50
	v_fma_f32 v6, v82, s16, v6
	v_fma_f32 v7, v82, s17, v7
	v_readlane_b32 s22, v3, 51
	v_readlane_b32 s23, v11, 51
	v_fma_f32 v6, v83, s18, v6
	v_fma_f32 v7, v83, s19, v7
	v_readlane_b32 s16, v3, 52
	v_readlane_b32 s17, v11, 52
	v_fma_f32 v6, v84, s20, v6
	v_fma_f32 v7, v84, s21, v7
	v_readlane_b32 s18, v3, 53
	v_readlane_b32 s19, v11, 53
	v_fma_f32 v6, v85, s22, v6
	v_fma_f32 v7, v85, s23, v7
	v_readlane_b32 s20, v3, 54
	v_readlane_b32 s21, v11, 54
	v_fma_f32 v6, v86, s16, v6
	v_fma_f32 v7, v86, s17, v7
	v_readlane_b32 s22, v3, 55
	v_readlane_b32 s23, v11, 55
	v_fma_f32 v6, v87, s18, v6
	v_fma_f32 v7, v87, s19, v7
	v_readlane_b32 s16, v3, 56
	v_readlane_b32 s17, v11, 56
	v_fma_f32 v6, v88, s20, v6
	v_fma_f32 v7, v88, s21, v7
	v_readlane_b32 s18, v3, 57
	v_readlane_b32 s19, v11, 57
	v_fma_f32 v6, v89, s22, v6
	v_fma_f32 v7, v89, s23, v7
	v_readlane_b32 s20, v3, 58
	v_readlane_b32 s21, v11, 58
	v_fma_f32 v6, v90, s16, v6
	v_fma_f32 v7, v90, s17, v7
	v_readlane_b32 s22, v3, 59
	v_readlane_b32 s23, v11, 59
	v_fma_f32 v6, v91, s18, v6
	v_fma_f32 v7, v91, s19, v7
	v_readlane_b32 s16, v3, 60
	v_readlane_b32 s17, v11, 60
	v_fma_f32 v6, v92, s20, v6
	v_fma_f32 v7, v92, s21, v7
	v_readlane_b32 s18, v3, 61
	v_readlane_b32 s19, v11, 61
	v_fma_f32 v6, v93, s22, v6
	v_fma_f32 v7, v93, s23, v7
	v_readlane_b32 s20, v3, 62
	v_readlane_b32 s21, v11, 62
	v_fma_f32 v6, v94, s16, v6
	v_fma_f32 v7, v94, s17, v7
	v_readlane_b32 s22, v3, 63
	v_readlane_b32 s23, v11, 63
	v_fma_f32 v6, v95, s18, v6
	v_fma_f32 v7, v95, s19, v7
	v_readlane_b32 s16, v28, 0
	v_readlane_b32 s17, v29, 0
	v_fma_f32 v6, v96, s20, v6
	v_fma_f32 v7, v96, s21, v7
	v_readlane_b32 s18, v28, 1
	v_readlane_b32 s19, v29, 1
	v_fma_f32 v6, v97, s22, v6
	v_fma_f32 v7, v97, s23, v7
	v_readlane_b32 s20, v28, 2
	v_readlane_b32 s21, v29, 2
	v_fma_f32 v6, v98, s16, v6
	v_fma_f32 v7, v98, s17, v7
	v_readlane_b32 s22, v28, 3
	v_readlane_b32 s23, v29, 3
	s_waitcnt vmcnt(62)
	v_fma_f32 v6, v99, s18, v6
	v_fma_f32 v7, v99, s19, v7
	v_readlane_b32 s16, v28, 4
	v_readlane_b32 s17, v29, 4
	s_waitcnt vmcnt(61)
	v_fma_f32 v6, v100, s20, v6
	v_fma_f32 v7, v100, s21, v7
	v_readlane_b32 s18, v28, 5
	v_readlane_b32 s19, v29, 5
	s_waitcnt vmcnt(60)
	v_fma_f32 v6, v101, s22, v6
	v_fma_f32 v7, v101, s23, v7
	v_readlane_b32 s20, v28, 6
	v_readlane_b32 s21, v29, 6
	s_waitcnt vmcnt(59)
	v_fma_f32 v6, v102, s16, v6
	v_fma_f32 v7, v102, s17, v7
	v_readlane_b32 s22, v28, 7
	v_readlane_b32 s23, v29, 7
	s_waitcnt vmcnt(58)
	v_fma_f32 v6, v103, s18, v6
	v_fma_f32 v7, v103, s19, v7
	v_readlane_b32 s16, v28, 8
	v_readlane_b32 s17, v29, 8
	s_waitcnt vmcnt(57)
	v_fma_f32 v6, v104, s20, v6
	v_fma_f32 v7, v104, s21, v7
	v_readlane_b32 s18, v28, 9
	v_readlane_b32 s19, v29, 9
	s_waitcnt vmcnt(56)
	v_fma_f32 v6, v105, s22, v6
	v_fma_f32 v7, v105, s23, v7
	v_readlane_b32 s20, v28, 10
	v_readlane_b32 s21, v29, 10
	s_waitcnt vmcnt(55)
	v_fma_f32 v6, v106, s16, v6
	v_fma_f32 v7, v106, s17, v7
	v_readlane_b32 s22, v28, 11
	v_readlane_b32 s23, v29, 11
	s_waitcnt vmcnt(54)
	v_fma_f32 v6, v107, s18, v6
	v_fma_f32 v7, v107, s19, v7
	v_readlane_b32 s16, v28, 12
	v_readlane_b32 s17, v29, 12
	s_waitcnt vmcnt(53)
	v_fma_f32 v6, v108, s20, v6
	v_fma_f32 v7, v108, s21, v7
	v_readlane_b32 s18, v28, 13
	v_readlane_b32 s19, v29, 13
	s_waitcnt vmcnt(52)
	v_fma_f32 v6, v109, s22, v6
	v_fma_f32 v7, v109, s23, v7
	v_readlane_b32 s20, v28, 14
	v_readlane_b32 s21, v29, 14
	s_waitcnt vmcnt(51)
	v_fma_f32 v6, v110, s16, v6
	v_fma_f32 v7, v110, s17, v7
	v_readlane_b32 s22, v28, 15
	v_readlane_b32 s23, v29, 15
	s_waitcnt vmcnt(50)
	v_fma_f32 v6, v111, s18, v6
	v_fma_f32 v7, v111, s19, v7
	v_readlane_b32 s16, v28, 16
	v_readlane_b32 s17, v29, 16
	s_waitcnt vmcnt(49)
	v_fma_f32 v6, v112, s20, v6
	v_fma_f32 v7, v112, s21, v7
	v_readlane_b32 s18, v28, 17
	v_readlane_b32 s19, v29, 17
	s_waitcnt vmcnt(48)
	v_fma_f32 v6, v113, s22, v6
	v_fma_f32 v7, v113, s23, v7
	v_readlane_b32 s20, v28, 18
	v_readlane_b32 s21, v29, 18
	s_waitcnt vmcnt(47)
	v_fma_f32 v6, v114, s16, v6
	v_fma_f32 v7, v114, s17, v7
	v_readlane_b32 s22, v28, 19
	v_readlane_b32 s23, v29, 19
	s_waitcnt vmcnt(46)
	v_fma_f32 v6, v115, s18, v6
	v_fma_f32 v7, v115, s19, v7
	v_readlane_b32 s16, v28, 20
	v_readlane_b32 s17, v29, 20
	s_waitcnt vmcnt(45)
	v_fma_f32 v6, v116, s20, v6
	v_fma_f32 v7, v116, s21, v7
	v_readlane_b32 s18, v28, 21
	v_readlane_b32 s19, v29, 21
	s_waitcnt vmcnt(44)
	v_fma_f32 v6, v117, s22, v6
	v_fma_f32 v7, v117, s23, v7
	v_readlane_b32 s20, v28, 22
	v_readlane_b32 s21, v29, 22
	s_waitcnt vmcnt(43)
	v_fma_f32 v6, v118, s16, v6
	v_fma_f32 v7, v118, s17, v7
	v_readlane_b32 s22, v28, 23
	v_readlane_b32 s23, v29, 23
	s_waitcnt vmcnt(42)
	v_fma_f32 v6, v119, s18, v6
	v_fma_f32 v7, v119, s19, v7
	v_readlane_b32 s16, v28, 24
	v_readlane_b32 s17, v29, 24
	s_waitcnt vmcnt(41)
	v_fma_f32 v6, v120, s20, v6
	v_fma_f32 v7, v120, s21, v7
	v_readlane_b32 s18, v28, 25
	v_readlane_b32 s19, v29, 25
	s_waitcnt vmcnt(40)
	v_fma_f32 v6, v121, s22, v6
	v_fma_f32 v7, v121, s23, v7
	v_readlane_b32 s20, v28, 26
	v_readlane_b32 s21, v29, 26
	s_waitcnt vmcnt(39)
	v_fma_f32 v6, v122, s16, v6
	v_fma_f32 v7, v122, s17, v7
	v_readlane_b32 s22, v28, 27
	v_readlane_b32 s23, v29, 27
	s_waitcnt vmcnt(38)
	v_fma_f32 v6, v123, s18, v6
	v_fma_f32 v7, v123, s19, v7
	v_readlane_b32 s16, v28, 28
	v_readlane_b32 s17, v29, 28
	s_waitcnt vmcnt(37)
	v_fma_f32 v6, v124, s20, v6
	v_fma_f32 v7, v124, s21, v7
	v_readlane_b32 s18, v28, 29
	v_readlane_b32 s19, v29, 29
	s_waitcnt vmcnt(36)
	v_fma_f32 v6, v125, s22, v6
	v_fma_f32 v7, v125, s23, v7
	v_readlane_b32 s20, v28, 30
	v_readlane_b32 s21, v29, 30
	s_waitcnt vmcnt(35)
	v_fma_f32 v6, v126, s16, v6
	v_fma_f32 v7, v126, s17, v7
	v_readlane_b32 s22, v28, 31
	v_readlane_b32 s23, v29, 31
	s_waitcnt vmcnt(34)
	v_fma_f32 v6, v127, s18, v6
	v_fma_f32 v7, v127, s19, v7
	v_readlane_b32 s16, v28, 32
	v_readlane_b32 s17, v29, 32
	s_waitcnt vmcnt(33)
	v_fma_f32 v6, v128, s20, v6
	v_fma_f32 v7, v128, s21, v7
	v_readlane_b32 s18, v28, 33
	v_readlane_b32 s19, v29, 33
	s_waitcnt vmcnt(32)
	v_fma_f32 v6, v129, s22, v6
	v_fma_f32 v7, v129, s23, v7
	v_readlane_b32 s20, v28, 34
	v_readlane_b32 s21, v29, 34
	s_waitcnt vmcnt(31)
	v_fma_f32 v6, v130, s16, v6
	v_fma_f32 v7, v130, s17, v7
	v_readlane_b32 s22, v28, 35
	v_readlane_b32 s23, v29, 35
	s_waitcnt vmcnt(30)
	v_fma_f32 v6, v131, s18, v6
	v_fma_f32 v7, v131, s19, v7
	v_readlane_b32 s16, v28, 36
	v_readlane_b32 s17, v29, 36
	s_waitcnt vmcnt(29)
	v_fma_f32 v6, v132, s20, v6
	v_fma_f32 v7, v132, s21, v7
	v_readlane_b32 s18, v28, 37
	v_readlane_b32 s19, v29, 37
	s_waitcnt vmcnt(28)
	v_fma_f32 v6, v133, s22, v6
	v_fma_f32 v7, v133, s23, v7
	v_readlane_b32 s20, v28, 38
	v_readlane_b32 s21, v29, 38
	s_waitcnt vmcnt(27)
	v_fma_f32 v6, v134, s16, v6
	v_fma_f32 v7, v134, s17, v7
	v_readlane_b32 s22, v28, 39
	v_readlane_b32 s23, v29, 39
	s_waitcnt vmcnt(26)
	v_fma_f32 v6, v135, s18, v6
	v_fma_f32 v7, v135, s19, v7
	v_readlane_b32 s16, v28, 40
	v_readlane_b32 s17, v29, 40
	s_waitcnt vmcnt(25)
	v_fma_f32 v6, v136, s20, v6
	v_fma_f32 v7, v136, s21, v7
	v_readlane_b32 s18, v28, 41
	v_readlane_b32 s19, v29, 41
	s_waitcnt vmcnt(24)
	v_fma_f32 v6, v137, s22, v6
	v_fma_f32 v7, v137, s23, v7
	v_readlane_b32 s20, v28, 42
	v_readlane_b32 s21, v29, 42
	s_waitcnt vmcnt(23)
	v_fma_f32 v6, v138, s16, v6
	v_fma_f32 v7, v138, s17, v7
	v_readlane_b32 s22, v28, 43
	v_readlane_b32 s23, v29, 43
	s_waitcnt vmcnt(22)
	v_fma_f32 v6, v139, s18, v6
	v_fma_f32 v7, v139, s19, v7
	v_readlane_b32 s16, v28, 44
	v_readlane_b32 s17, v29, 44
	s_waitcnt vmcnt(21)
	v_fma_f32 v6, v140, s20, v6
	v_fma_f32 v7, v140, s21, v7
	v_readlane_b32 s18, v28, 45
	v_readlane_b32 s19, v29, 45
	s_waitcnt vmcnt(20)
	v_fma_f32 v6, v141, s22, v6
	v_fma_f32 v7, v141, s23, v7
	v_readlane_b32 s20, v28, 46
	v_readlane_b32 s21, v29, 46
	s_waitcnt vmcnt(19)
	v_fma_f32 v6, v142, s16, v6
	v_fma_f32 v7, v142, s17, v7
	v_readlane_b32 s22, v28, 47
	v_readlane_b32 s23, v29, 47
	s_waitcnt vmcnt(18)
	v_fma_f32 v6, v143, s18, v6
	v_fma_f32 v7, v143, s19, v7
	v_readlane_b32 s16, v28, 48
	v_readlane_b32 s17, v29, 48
	s_waitcnt vmcnt(17)
	v_fma_f32 v6, v144, s20, v6
	v_fma_f32 v7, v144, s21, v7
	v_readlane_b32 s18, v28, 49
	v_readlane_b32 s19, v29, 49
	s_waitcnt vmcnt(16)
	v_fma_f32 v6, v145, s22, v6
	v_fma_f32 v7, v145, s23, v7
	v_readlane_b32 s20, v28, 50
	v_readlane_b32 s21, v29, 50
	s_waitcnt vmcnt(15)
	v_fma_f32 v6, v146, s16, v6
	v_fma_f32 v7, v146, s17, v7
	v_readlane_b32 s22, v28, 51
	v_readlane_b32 s23, v29, 51
	s_waitcnt vmcnt(14)
	v_fma_f32 v6, v147, s18, v6
	v_fma_f32 v7, v147, s19, v7
	v_readlane_b32 s16, v28, 52
	v_readlane_b32 s17, v29, 52
	s_waitcnt vmcnt(13)
	v_fma_f32 v6, v148, s20, v6
	v_fma_f32 v7, v148, s21, v7
	v_readlane_b32 s18, v28, 53
	v_readlane_b32 s19, v29, 53
	s_waitcnt vmcnt(12)
	v_fma_f32 v6, v149, s22, v6
	v_fma_f32 v7, v149, s23, v7
	v_readlane_b32 s20, v28, 54
	v_readlane_b32 s21, v29, 54
	s_waitcnt vmcnt(11)
	v_fma_f32 v6, v150, s16, v6
	v_fma_f32 v7, v150, s17, v7
	v_readlane_b32 s22, v28, 55
	v_readlane_b32 s23, v29, 55
	s_waitcnt vmcnt(10)
	v_fma_f32 v6, v151, s18, v6
	v_fma_f32 v7, v151, s19, v7
	v_readlane_b32 s16, v28, 56
	v_readlane_b32 s17, v29, 56
	s_waitcnt vmcnt(9)
	v_fma_f32 v6, v152, s20, v6
	v_fma_f32 v7, v152, s21, v7
	v_readlane_b32 s18, v28, 57
	v_readlane_b32 s19, v29, 57
	s_waitcnt vmcnt(8)
	v_fma_f32 v6, v153, s22, v6
	v_fma_f32 v7, v153, s23, v7
	v_readlane_b32 s20, v28, 58
	v_readlane_b32 s21, v29, 58
	s_waitcnt vmcnt(7)
	v_fma_f32 v6, v154, s16, v6
	v_fma_f32 v7, v154, s17, v7
	v_readlane_b32 s22, v28, 59
	v_readlane_b32 s23, v29, 59
	s_waitcnt vmcnt(6)
	v_fma_f32 v6, v155, s18, v6
	v_fma_f32 v7, v155, s19, v7
	v_readlane_b32 s16, v28, 60
	v_readlane_b32 s17, v29, 60
	s_waitcnt vmcnt(5)
	v_fma_f32 v6, v156, s20, v6
	v_fma_f32 v7, v156, s21, v7
	v_readlane_b32 s18, v28, 61
	v_readlane_b32 s19, v29, 61
	s_waitcnt vmcnt(4)
	v_fma_f32 v6, v157, s22, v6
	v_fma_f32 v7, v157, s23, v7
	v_readlane_b32 s20, v28, 62
	v_readlane_b32 s21, v29, 62
	s_waitcnt vmcnt(3)
	v_fma_f32 v6, v158, s16, v6
	v_fma_f32 v7, v158, s17, v7
	v_readlane_b32 s22, v28, 63
	v_readlane_b32 s23, v29, 63
	s_waitcnt vmcnt(2)
	v_fma_f32 v6, v159, s18, v6
	v_fma_f32 v7, v159, s19, v7
	s_waitcnt vmcnt(1)
	v_fma_f32 v6, v164, s20, v6
	v_fma_f32 v7, v164, s21, v7
	s_waitcnt vmcnt(0)
	v_fma_f32 v6, v165, s22, v6
	v_fma_f32 v7, v165, s23, v7
	s_mov_b64 s[0:1], 0
	s_and_saveexec_b64 s[0:1], s[6:7]
	v_readlane_b32 s4, v250, 48
	v_readlane_b32 s5, v250, 49
	s_cbranch_execz .LBB0_720
	v_ashrrev_i32_e32 v3, 31, v2
	v_readlane_b32 s2, v250, 60
	v_lshlrev_b64 v[2:3], 2, v[2:3]
	v_readlane_b32 s3, v250, 61
	s_nop 1
	v_lshl_add_u64 v[4:5], s[2:3], 0, v[2:3]
	v_lshl_add_u64 v[2:3], s[4:5], 0, v[2:3]
	global_atomic_add_f32 v[2:3], v6, off
	global_atomic_add_f32 v[4:5], v7, off
	s_branch .LBB0_720

.LBB0_742:
	v_cndmask_b32_e64 v0, 0, 1, s[0:1]
	v_cmp_ne_u32_e32 vcc, 1, v0
	v_or_b32_e32 v0, s11, v10
	v_lshlrev_b64 v[8:9], 2, v[0:1]
	s_lshl_b32 s90, s11, 10
	v_lshl_add_u64 v[12:13], s[2:3], 0, v[8:9]
	v_lshl_add_u64 v[8:9], s[4:5], 0, v[8:9]
	global_load_dword v3, v[12:13], off
	global_load_dword v11, v[8:9], off
	global_load_dword v28, v[12:13], off offset:256
	global_load_dword v29, v[8:9], off offset:256
	v_lshl_add_u64 v[8:9], s[90:91], 2, v[4:5]
	s_mov_b32 s14, 0x1000
	s_mov_b32 s15, 0
	global_load_dword v32, v[8:9], off
	v_lshl_add_u64 v[8:9], v[8:9], 0, s[14:15]
	global_load_dword v33, v[8:9], off
	v_lshl_add_u64 v[8:9], v[8:9], 0, s[14:15]
	global_load_dword v34, v[8:9], off
	v_lshl_add_u64 v[8:9], v[8:9], 0, s[14:15]
	global_load_dword v35, v[8:9], off
	v_lshl_add_u64 v[8:9], v[8:9], 0, s[14:15]
	global_load_dword v36, v[8:9], off
	v_lshl_add_u64 v[8:9], v[8:9], 0, s[14:15]
	global_load_dword v37, v[8:9], off
	v_lshl_add_u64 v[8:9], v[8:9], 0, s[14:15]
	global_load_dword v38, v[8:9], off
	v_lshl_add_u64 v[8:9], v[8:9], 0, s[14:15]
	global_load_dword v39, v[8:9], off
	v_lshl_add_u64 v[8:9], v[8:9], 0, s[14:15]
	global_load_dword v40, v[8:9], off
	v_lshl_add_u64 v[8:9], v[8:9], 0, s[14:15]
	global_load_dword v41, v[8:9], off
	v_lshl_add_u64 v[8:9], v[8:9], 0, s[14:15]
	global_load_dword v42, v[8:9], off
	v_lshl_add_u64 v[8:9], v[8:9], 0, s[14:15]
	global_load_dword v43, v[8:9], off
	v_lshl_add_u64 v[8:9], v[8:9], 0, s[14:15]
	global_load_dword v44, v[8:9], off
	v_lshl_add_u64 v[8:9], v[8:9], 0, s[14:15]
	global_load_dword v45, v[8:9], off
	v_lshl_add_u64 v[8:9], v[8:9], 0, s[14:15]
	global_load_dword v46, v[8:9], off
	v_lshl_add_u64 v[8:9], v[8:9], 0, s[14:15]
	global_load_dword v47, v[8:9], off
	v_lshl_add_u64 v[8:9], v[8:9], 0, s[14:15]
	global_load_dword v48, v[8:9], off
	v_lshl_add_u64 v[8:9], v[8:9], 0, s[14:15]
	global_load_dword v49, v[8:9], off
	v_lshl_add_u64 v[8:9], v[8:9], 0, s[14:15]
	global_load_dword v50, v[8:9], off
	v_lshl_add_u64 v[8:9], v[8:9], 0, s[14:15]
	global_load_dword v51, v[8:9], off
	v_lshl_add_u64 v[8:9], v[8:9], 0, s[14:15]
	global_load_dword v52, v[8:9], off
	v_lshl_add_u64 v[8:9], v[8:9], 0, s[14:15]
	global_load_dword v53, v[8:9], off
	v_lshl_add_u64 v[8:9], v[8:9], 0, s[14:15]
	global_load_dword v54, v[8:9], off
	v_lshl_add_u64 v[8:9], v[8:9], 0, s[14:15]
	global_load_dword v55, v[8:9], off
	v_lshl_add_u64 v[8:9], v[8:9], 0, s[14:15]
	global_load_dword v58, v[8:9], off
	v_lshl_add_u64 v[8:9], v[8:9], 0, s[14:15]
	global_load_dword v59, v[8:9], off
	v_lshl_add_u64 v[8:9], v[8:9], 0, s[14:15]
	global_load_dword v60, v[8:9], off
	v_lshl_add_u64 v[8:9], v[8:9], 0, s[14:15]
	global_load_dword v61, v[8:9], off
	v_lshl_add_u64 v[8:9], v[8:9], 0, s[14:15]
	global_load_dword v62, v[8:9], off
	v_lshl_add_u64 v[8:9], v[8:9], 0, s[14:15]
	global_load_dword v63, v[8:9], off
	v_lshl_add_u64 v[8:9], v[8:9], 0, s[14:15]
	global_load_dword v64, v[8:9], off
	v_lshl_add_u64 v[8:9], v[8:9], 0, s[14:15]
	global_load_dword v65, v[8:9], off
	v_lshl_add_u64 v[8:9], v[8:9], 0, s[14:15]
	global_load_dword v66, v[8:9], off
	v_lshl_add_u64 v[8:9], v[8:9], 0, s[14:15]
	global_load_dword v67, v[8:9], off
	v_lshl_add_u64 v[8:9], v[8:9], 0, s[14:15]
	global_load_dword v68, v[8:9], off
	v_lshl_add_u64 v[8:9], v[8:9], 0, s[14:15]
	global_load_dword v69, v[8:9], off
	v_lshl_add_u64 v[8:9], v[8:9], 0, s[14:15]
	global_load_dword v70, v[8:9], off
	v_lshl_add_u64 v[8:9], v[8:9], 0, s[14:15]
	global_load_dword v71, v[8:9], off
	v_lshl_add_u64 v[8:9], v[8:9], 0, s[14:15]
	global_load_dword v72, v[8:9], off
	v_lshl_add_u64 v[8:9], v[8:9], 0, s[14:15]
	global_load_dword v73, v[8:9], off
	v_lshl_add_u64 v[8:9], v[8:9], 0, s[14:15]
	global_load_dword v74, v[8:9], off
	v_lshl_add_u64 v[8:9], v[8:9], 0, s[14:15]
	global_load_dword v75, v[8:9], off
	v_lshl_add_u64 v[8:9], v[8:9], 0, s[14:15]
	global_load_dword v76, v[8:9], off
	v_lshl_add_u64 v[8:9], v[8:9], 0, s[14:15]
	global_load_dword v77, v[8:9], off
	v_lshl_add_u64 v[8:9], v[8:9], 0, s[14:15]
	global_load_dword v78, v[8:9], off
	v_lshl_add_u64 v[8:9], v[8:9], 0, s[14:15]
	global_load_dword v79, v[8:9], off
	v_lshl_add_u64 v[8:9], v[8:9], 0, s[14:15]
	global_load_dword v80, v[8:9], off
	v_lshl_add_u64 v[8:9], v[8:9], 0, s[14:15]
	global_load_dword v81, v[8:9], off
	v_lshl_add_u64 v[8:9], v[8:9], 0, s[14:15]
	global_load_dword v82, v[8:9], off
	v_lshl_add_u64 v[8:9], v[8:9], 0, s[14:15]
	global_load_dword v83, v[8:9], off
	v_lshl_add_u64 v[8:9], v[8:9], 0, s[14:15]
	global_load_dword v84, v[8:9], off
	v_lshl_add_u64 v[8:9], v[8:9], 0, s[14:15]
	global_load_dword v85, v[8:9], off
	v_lshl_add_u64 v[8:9], v[8:9], 0, s[14:15]
	global_load_dword v86, v[8:9], off
	v_lshl_add_u64 v[8:9], v[8:9], 0, s[14:15]
	global_load_dword v87, v[8:9], off
	v_lshl_add_u64 v[8:9], v[8:9], 0, s[14:15]
	global_load_dword v88, v[8:9], off
	v_lshl_add_u64 v[8:9], v[8:9], 0, s[14:15]
	global_load_dword v89, v[8:9], off
	v_lshl_add_u64 v[8:9], v[8:9], 0, s[14:15]
	global_load_dword v90, v[8:9], off
	v_lshl_add_u64 v[8:9], v[8:9], 0, s[14:15]
	global_load_dword v91, v[8:9], off
	v_lshl_add_u64 v[8:9], v[8:9], 0, s[14:15]
	global_load_dword v92, v[8:9], off
	v_lshl_add_u64 v[8:9], v[8:9], 0, s[14:15]
	global_load_dword v93, v[8:9], off
	v_lshl_add_u64 v[8:9], v[8:9], 0, s[14:15]
	global_load_dword v94, v[8:9], off
	v_lshl_add_u64 v[8:9], v[8:9], 0, s[14:15]
	global_load_dword v95, v[8:9], off
	v_lshl_add_u64 v[8:9], v[8:9], 0, s[14:15]
	global_load_dword v96, v[8:9], off
	v_lshl_add_u64 v[8:9], v[8:9], 0, s[14:15]
	global_load_dword v97, v[8:9], off
	v_lshl_add_u64 v[8:9], v[8:9], 0, s[14:15]
	global_load_dword v98, v[8:9], off
	v_lshl_add_u64 v[8:9], v[8:9], 0, s[14:15]
	global_load_dword v99, v[8:9], off
	v_lshl_add_u64 v[8:9], v[8:9], 0, s[14:15]
	global_load_dword v100, v[8:9], off
	v_lshl_add_u64 v[8:9], v[8:9], 0, s[14:15]
	global_load_dword v101, v[8:9], off
	v_lshl_add_u64 v[8:9], v[8:9], 0, s[14:15]
	global_load_dword v102, v[8:9], off
	v_lshl_add_u64 v[8:9], v[8:9], 0, s[14:15]
	global_load_dword v103, v[8:9], off
	v_lshl_add_u64 v[8:9], v[8:9], 0, s[14:15]
	global_load_dword v104, v[8:9], off
	v_lshl_add_u64 v[8:9], v[8:9], 0, s[14:15]
	global_load_dword v105, v[8:9], off
	v_lshl_add_u64 v[8:9], v[8:9], 0, s[14:15]
	global_load_dword v106, v[8:9], off
	v_lshl_add_u64 v[8:9], v[8:9], 0, s[14:15]
	global_load_dword v107, v[8:9], off
	v_lshl_add_u64 v[8:9], v[8:9], 0, s[14:15]
	global_load_dword v108, v[8:9], off
	v_lshl_add_u64 v[8:9], v[8:9], 0, s[14:15]
	global_load_dword v109, v[8:9], off
	v_lshl_add_u64 v[8:9], v[8:9], 0, s[14:15]
	global_load_dword v110, v[8:9], off
	v_lshl_add_u64 v[8:9], v[8:9], 0, s[14:15]
	global_load_dword v111, v[8:9], off
	v_lshl_add_u64 v[8:9], v[8:9], 0, s[14:15]
	global_load_dword v112, v[8:9], off
	v_lshl_add_u64 v[8:9], v[8:9], 0, s[14:15]
	global_load_dword v113, v[8:9], off
	v_lshl_add_u64 v[8:9], v[8:9], 0, s[14:15]
	global_load_dword v114, v[8:9], off
	v_lshl_add_u64 v[8:9], v[8:9], 0, s[14:15]
	global_load_dword v115, v[8:9], off
	v_lshl_add_u64 v[8:9], v[8:9], 0, s[14:15]
	global_load_dword v116, v[8:9], off
	v_lshl_add_u64 v[8:9], v[8:9], 0, s[14:15]
	global_load_dword v117, v[8:9], off
	v_lshl_add_u64 v[8:9], v[8:9], 0, s[14:15]
	global_load_dword v118, v[8:9], off
	v_lshl_add_u64 v[8:9], v[8:9], 0, s[14:15]
	global_load_dword v119, v[8:9], off
	v_lshl_add_u64 v[8:9], v[8:9], 0, s[14:15]
	global_load_dword v120, v[8:9], off
	v_lshl_add_u64 v[8:9], v[8:9], 0, s[14:15]
	global_load_dword v121, v[8:9], off
	v_lshl_add_u64 v[8:9], v[8:9], 0, s[14:15]
	global_load_dword v122, v[8:9], off
	v_lshl_add_u64 v[8:9], v[8:9], 0, s[14:15]
	global_load_dword v123, v[8:9], off
	v_lshl_add_u64 v[8:9], v[8:9], 0, s[14:15]
	global_load_dword v124, v[8:9], off
	v_lshl_add_u64 v[8:9], v[8:9], 0, s[14:15]
	global_load_dword v125, v[8:9], off
	v_lshl_add_u64 v[8:9], v[8:9], 0, s[14:15]
	global_load_dword v126, v[8:9], off
	v_lshl_add_u64 v[8:9], v[8:9], 0, s[14:15]
	global_load_dword v127, v[8:9], off
	v_lshl_add_u64 v[8:9], v[8:9], 0, s[14:15]
	global_load_dword v128, v[8:9], off
	v_lshl_add_u64 v[8:9], v[8:9], 0, s[14:15]
	global_load_dword v129, v[8:9], off
	v_lshl_add_u64 v[8:9], v[8:9], 0, s[14:15]
	global_load_dword v130, v[8:9], off
	v_lshl_add_u64 v[8:9], v[8:9], 0, s[14:15]
	global_load_dword v131, v[8:9], off
	v_lshl_add_u64 v[8:9], v[8:9], 0, s[14:15]
	global_load_dword v132, v[8:9], off
	v_lshl_add_u64 v[8:9], v[8:9], 0, s[14:15]
	global_load_dword v133, v[8:9], off
	v_lshl_add_u64 v[8:9], v[8:9], 0, s[14:15]
	global_load_dword v134, v[8:9], off
	v_lshl_add_u64 v[8:9], v[8:9], 0, s[14:15]
	global_load_dword v135, v[8:9], off
	v_lshl_add_u64 v[8:9], v[8:9], 0, s[14:15]
	global_load_dword v136, v[8:9], off
	v_lshl_add_u64 v[8:9], v[8:9], 0, s[14:15]
	global_load_dword v137, v[8:9], off
	v_lshl_add_u64 v[8:9], v[8:9], 0, s[14:15]
	global_load_dword v138, v[8:9], off
	v_lshl_add_u64 v[8:9], v[8:9], 0, s[14:15]
	global_load_dword v139, v[8:9], off
	v_lshl_add_u64 v[8:9], v[8:9], 0, s[14:15]
	global_load_dword v140, v[8:9], off
	v_lshl_add_u64 v[8:9], v[8:9], 0, s[14:15]
	global_load_dword v141, v[8:9], off
	v_lshl_add_u64 v[8:9], v[8:9], 0, s[14:15]
	global_load_dword v142, v[8:9], off
	v_lshl_add_u64 v[8:9], v[8:9], 0, s[14:15]
	global_load_dword v143, v[8:9], off
	v_lshl_add_u64 v[8:9], v[8:9], 0, s[14:15]
	global_load_dword v144, v[8:9], off
	v_lshl_add_u64 v[8:9], v[8:9], 0, s[14:15]
	global_load_dword v145, v[8:9], off
	v_lshl_add_u64 v[8:9], v[8:9], 0, s[14:15]
	global_load_dword v146, v[8:9], off
	v_lshl_add_u64 v[8:9], v[8:9], 0, s[14:15]
	global_load_dword v147, v[8:9], off
	v_lshl_add_u64 v[8:9], v[8:9], 0, s[14:15]
	global_load_dword v148, v[8:9], off
	v_lshl_add_u64 v[8:9], v[8:9], 0, s[14:15]
	global_load_dword v149, v[8:9], off
	v_lshl_add_u64 v[8:9], v[8:9], 0, s[14:15]
	global_load_dword v150, v[8:9], off
	v_lshl_add_u64 v[8:9], v[8:9], 0, s[14:15]
	global_load_dword v151, v[8:9], off
	v_lshl_add_u64 v[8:9], v[8:9], 0, s[14:15]
	global_load_dword v152, v[8:9], off
	v_lshl_add_u64 v[8:9], v[8:9], 0, s[14:15]
	global_load_dword v153, v[8:9], off
	v_lshl_add_u64 v[8:9], v[8:9], 0, s[14:15]
	global_load_dword v154, v[8:9], off
	v_lshl_add_u64 v[8:9], v[8:9], 0, s[14:15]
	global_load_dword v155, v[8:9], off
	v_lshl_add_u64 v[8:9], v[8:9], 0, s[14:15]
	global_load_dword v156, v[8:9], off
	v_lshl_add_u64 v[8:9], v[8:9], 0, s[14:15]
	global_load_dword v157, v[8:9], off
	v_lshl_add_u64 v[8:9], v[8:9], 0, s[14:15]
	global_load_dword v158, v[8:9], off
	v_lshl_add_u64 v[8:9], v[8:9], 0, s[14:15]
	global_load_dword v159, v[8:9], off
	v_lshl_add_u64 v[8:9], v[8:9], 0, s[14:15]
	global_load_dword v164, v[8:9], off
	v_lshl_add_u64 v[8:9], v[8:9], 0, s[14:15]
	global_load_dword v165, v[8:9], off
	s_mov_b32 s11, 64
	s_and_b64 vcc, exec, vcc
	s_waitcnt vmcnt(63)
	v_readlane_b32 s16, v3, 0
	v_readlane_b32 s17, v11, 0
	v_readlane_b32 s18, v3, 1
	v_readlane_b32 s19, v11, 1
	v_readlane_b32 s20, v3, 2
	v_readlane_b32 s21, v11, 2
	v_fma_f32 v6, v32, s16, v6
	v_fma_f32 v7, v32, s17, v7
	v_readlane_b32 s22, v3, 3
	v_readlane_b32 s23, v11, 3
	v_fma_f32 v6, v33, s18, v6
	v_fma_f32 v7, v33, s19, v7
	v_readlane_b32 s16, v3, 4
	v_readlane_b32 s17, v11, 4
	v_fma_f32 v6, v34, s20, v6
	v_fma_f32 v7, v34, s21, v7
	v_readlane_b32 s18, v3, 5
	v_readlane_b32 s19, v11, 5
	v_fma_f32 v6, v35, s22, v6
	v_fma_f32 v7, v35, s23, v7
	v_readlane_b32 s20, v3, 6
	v_readlane_b32 s21, v11, 6
	v_fma_f32 v6, v36, s16, v6
	v_fma_f32 v7, v36, s17, v7
	v_readlane_b32 s22, v3, 7
	v_readlane_b32 s23, v11, 7
	v_fma_f32 v6, v37, s18, v6
	v_fma_f32 v7, v37, s19, v7
	v_readlane_b32 s16, v3, 8
	v_readlane_b32 s17, v11, 8
	v_fma_f32 v6, v38, s20, v6
	v_fma_f32 v7, v38, s21, v7
	v_readlane_b32 s18, v3, 9
	v_readlane_b32 s19, v11, 9
	v_fma_f32 v6, v39, s22, v6
	v_fma_f32 v7, v39, s23, v7
	v_readlane_b32 s20, v3, 10
	v_readlane_b32 s21, v11, 10
	v_fma_f32 v6, v40, s16, v6
	v_fma_f32 v7, v40, s17, v7
	v_readlane_b32 s22, v3, 11
	v_readlane_b32 s23, v11, 11
	v_fma_f32 v6, v41, s18, v6
	v_fma_f32 v7, v41, s19, v7
	v_readlane_b32 s16, v3, 12
	v_readlane_b32 s17, v11, 12
	v_fma_f32 v6, v42, s20, v6
	v_fma_f32 v7, v42, s21, v7
	v_readlane_b32 s18, v3, 13
	v_readlane_b32 s19, v11, 13
	v_fma_f32 v6, v43, s22, v6
	v_fma_f32 v7, v43, s23, v7
	v_readlane_b32 s20, v3, 14
	v_readlane_b32 s21, v11, 14
	v_fma_f32 v6, v44, s16, v6
	v_fma_f32 v7, v44, s17, v7
	v_readlane_b32 s22, v3, 15
	v_readlane_b32 s23, v11, 15
	v_fma_f32 v6, v45, s18, v6
	v_fma_f32 v7, v45, s19, v7
	v_readlane_b32 s16, v3, 16
	v_readlane_b32 s17, v11, 16
	v_fma_f32 v6, v46, s20, v6
	v_fma_f32 v7, v46, s21, v7
	v_readlane_b32 s18, v3, 17
	v_readlane_b32 s19, v11, 17
	v_fma_f32 v6, v47, s22, v6
	v_fma_f32 v7, v47, s23, v7
	v_readlane_b32 s20, v3, 18
	v_readlane_b32 s21, v11, 18
	v_fma_f32 v6, v48, s16, v6
	v_fma_f32 v7, v48, s17, v7
	v_readlane_b32 s22, v3, 19
	v_readlane_b32 s23, v11, 19
	v_fma_f32 v6, v49, s18, v6
	v_fma_f32 v7, v49, s19, v7
	v_readlane_b32 s16, v3, 20
	v_readlane_b32 s17, v11, 20
	v_fma_f32 v6, v50, s20, v6
	v_fma_f32 v7, v50, s21, v7
	v_readlane_b32 s18, v3, 21
	v_readlane_b32 s19, v11, 21
	v_fma_f32 v6, v51, s22, v6
	v_fma_f32 v7, v51, s23, v7
	v_readlane_b32 s20, v3, 22
	v_readlane_b32 s21, v11, 22
	v_fma_f32 v6, v52, s16, v6
	v_fma_f32 v7, v52, s17, v7
	v_readlane_b32 s22, v3, 23
	v_readlane_b32 s23, v11, 23
	v_fma_f32 v6, v53, s18, v6
	v_fma_f32 v7, v53, s19, v7
	v_readlane_b32 s16, v3, 24
	v_readlane_b32 s17, v11, 24
	v_fma_f32 v6, v54, s20, v6
	v_fma_f32 v7, v54, s21, v7
	v_readlane_b32 s18, v3, 25
	v_readlane_b32 s19, v11, 25
	v_fma_f32 v6, v55, s22, v6
	v_fma_f32 v7, v55, s23, v7
	v_readlane_b32 s20, v3, 26
	v_readlane_b32 s21, v11, 26
	v_fma_f32 v6, v58, s16, v6
	v_fma_f32 v7, v58, s17, v7
	v_readlane_b32 s22, v3, 27
	v_readlane_b32 s23, v11, 27
	v_fma_f32 v6, v59, s18, v6
	v_fma_f32 v7, v59, s19, v7
	v_readlane_b32 s16, v3, 28
	v_readlane_b32 s17, v11, 28
	v_fma_f32 v6, v60, s20, v6
	v_fma_f32 v7, v60, s21, v7
	v_readlane_b32 s18, v3, 29
	v_readlane_b32 s19, v11, 29
	v_fma_f32 v6, v61, s22, v6
	v_fma_f32 v7, v61, s23, v7
	v_readlane_b32 s20, v3, 30
	v_readlane_b32 s21, v11, 30
	v_fma_f32 v6, v62, s16, v6
	v_fma_f32 v7, v62, s17, v7
	v_readlane_b32 s22, v3, 31
	v_readlane_b32 s23, v11, 31
	v_fma_f32 v6, v63, s18, v6
	v_fma_f32 v7, v63, s19, v7
	v_readlane_b32 s16, v3, 32
	v_readlane_b32 s17, v11, 32
	v_fma_f32 v6, v64, s20, v6
	v_fma_f32 v7, v64, s21, v7
	v_readlane_b32 s18, v3, 33
	v_readlane_b32 s19, v11, 33
	v_fma_f32 v6, v65, s22, v6
	v_fma_f32 v7, v65, s23, v7
	v_readlane_b32 s20, v3, 34
	v_readlane_b32 s21, v11, 34
	v_fma_f32 v6, v66, s16, v6
	v_fma_f32 v7, v66, s17, v7
	v_readlane_b32 s22, v3, 35
	v_readlane_b32 s23, v11, 35
	v_fma_f32 v6, v67, s18, v6
	v_fma_f32 v7, v67, s19, v7
	v_readlane_b32 s16, v3, 36
	v_readlane_b32 s17, v11, 36
	v_fma_f32 v6, v68, s20, v6
	v_fma_f32 v7, v68, s21, v7
	v_readlane_b32 s18, v3, 37
	v_readlane_b32 s19, v11, 37
	v_fma_f32 v6, v69, s22, v6
	v_fma_f32 v7, v69, s23, v7
	v_readlane_b32 s20, v3, 38
	v_readlane_b32 s21, v11, 38
	v_fma_f32 v6, v70, s16, v6
	v_fma_f32 v7, v70, s17, v7
	v_readlane_b32 s22, v3, 39
	v_readlane_b32 s23, v11, 39
	v_fma_f32 v6, v71, s18, v6
	v_fma_f32 v7, v71, s19, v7
	v_readlane_b32 s16, v3, 40
	v_readlane_b32 s17, v11, 40
	v_fma_f32 v6, v72, s20, v6
	v_fma_f32 v7, v72, s21, v7
	v_readlane_b32 s18, v3, 41
	v_readlane_b32 s19, v11, 41
	v_fma_f32 v6, v73, s22, v6
	v_fma_f32 v7, v73, s23, v7
	v_readlane_b32 s20, v3, 42
	v_readlane_b32 s21, v11, 42
	v_fma_f32 v6, v74, s16, v6
	v_fma_f32 v7, v74, s17, v7
	v_readlane_b32 s22, v3, 43
	v_readlane_b32 s23, v11, 43
	v_fma_f32 v6, v75, s18, v6
	v_fma_f32 v7, v75, s19, v7
	v_readlane_b32 s16, v3, 44
	v_readlane_b32 s17, v11, 44
	v_fma_f32 v6, v76, s20, v6
	v_fma_f32 v7, v76, s21, v7
	v_readlane_b32 s18, v3, 45
	v_readlane_b32 s19, v11, 45
	v_fma_f32 v6, v77, s22, v6
	v_fma_f32 v7, v77, s23, v7
	v_readlane_b32 s20, v3, 46
	v_readlane_b32 s21, v11, 46
	v_fma_f32 v6, v78, s16, v6
	v_fma_f32 v7, v78, s17, v7
	v_readlane_b32 s22, v3, 47
	v_readlane_b32 s23, v11, 47
	v_fma_f32 v6, v79, s18, v6
	v_fma_f32 v7, v79, s19, v7
	v_readlane_b32 s16, v3, 48
	v_readlane_b32 s17, v11, 48
	v_fma_f32 v6, v80, s20, v6
	v_fma_f32 v7, v80, s21, v7
	v_readlane_b32 s18, v3, 49
	v_readlane_b32 s19, v11, 49
	v_fma_f32 v6, v81, s22, v6
	v_fma_f32 v7, v81, s23, v7
	v_readlane_b32 s20, v3, 50
	v_readlane_b32 s21, v11, 50
	v_fma_f32 v6, v82, s16, v6
	v_fma_f32 v7, v82, s17, v7
	v_readlane_b32 s22, v3, 51
	v_readlane_b32 s23, v11, 51
	v_fma_f32 v6, v83, s18, v6
	v_fma_f32 v7, v83, s19, v7
	v_readlane_b32 s16, v3, 52
	v_readlane_b32 s17, v11, 52
	v_fma_f32 v6, v84, s20, v6
	v_fma_f32 v7, v84, s21, v7
	v_readlane_b32 s18, v3, 53
	v_readlane_b32 s19, v11, 53
	v_fma_f32 v6, v85, s22, v6
	v_fma_f32 v7, v85, s23, v7
	v_readlane_b32 s20, v3, 54
	v_readlane_b32 s21, v11, 54
	v_fma_f32 v6, v86, s16, v6
	v_fma_f32 v7, v86, s17, v7
	v_readlane_b32 s22, v3, 55
	v_readlane_b32 s23, v11, 55
	v_fma_f32 v6, v87, s18, v6
	v_fma_f32 v7, v87, s19, v7
	v_readlane_b32 s16, v3, 56
	v_readlane_b32 s17, v11, 56
	v_fma_f32 v6, v88, s20, v6
	v_fma_f32 v7, v88, s21, v7
	v_readlane_b32 s18, v3, 57
	v_readlane_b32 s19, v11, 57
	v_fma_f32 v6, v89, s22, v6
	v_fma_f32 v7, v89, s23, v7
	v_readlane_b32 s20, v3, 58
	v_readlane_b32 s21, v11, 58
	v_fma_f32 v6, v90, s16, v6
	v_fma_f32 v7, v90, s17, v7
	v_readlane_b32 s22, v3, 59
	v_readlane_b32 s23, v11, 59
	v_fma_f32 v6, v91, s18, v6
	v_fma_f32 v7, v91, s19, v7
	v_readlane_b32 s16, v3, 60
	v_readlane_b32 s17, v11, 60
	v_fma_f32 v6, v92, s20, v6
	v_fma_f32 v7, v92, s21, v7
	v_readlane_b32 s18, v3, 61
	v_readlane_b32 s19, v11, 61
	v_fma_f32 v6, v93, s22, v6
	v_fma_f32 v7, v93, s23, v7
	v_readlane_b32 s20, v3, 62
	v_readlane_b32 s21, v11, 62
	v_fma_f32 v6, v94, s16, v6
	v_fma_f32 v7, v94, s17, v7
	v_readlane_b32 s22, v3, 63
	v_readlane_b32 s23, v11, 63
	v_fma_f32 v6, v95, s18, v6
	v_fma_f32 v7, v95, s19, v7
	v_readlane_b32 s16, v28, 0
	v_readlane_b32 s17, v29, 0
	v_fma_f32 v6, v96, s20, v6
	v_fma_f32 v7, v96, s21, v7
	v_readlane_b32 s18, v28, 1
	v_readlane_b32 s19, v29, 1
	v_fma_f32 v6, v97, s22, v6
	v_fma_f32 v7, v97, s23, v7
	v_readlane_b32 s20, v28, 2
	v_readlane_b32 s21, v29, 2
	v_fma_f32 v6, v98, s16, v6
	v_fma_f32 v7, v98, s17, v7
	v_readlane_b32 s22, v28, 3
	v_readlane_b32 s23, v29, 3
	s_waitcnt vmcnt(62)
	v_fma_f32 v6, v99, s18, v6
	v_fma_f32 v7, v99, s19, v7
	v_readlane_b32 s16, v28, 4
	v_readlane_b32 s17, v29, 4
	s_waitcnt vmcnt(61)
	v_fma_f32 v6, v100, s20, v6
	v_fma_f32 v7, v100, s21, v7
	v_readlane_b32 s18, v28, 5
	v_readlane_b32 s19, v29, 5
	s_waitcnt vmcnt(60)
	v_fma_f32 v6, v101, s22, v6
	v_fma_f32 v7, v101, s23, v7
	v_readlane_b32 s20, v28, 6
	v_readlane_b32 s21, v29, 6
	s_waitcnt vmcnt(59)
	v_fma_f32 v6, v102, s16, v6
	v_fma_f32 v7, v102, s17, v7
	v_readlane_b32 s22, v28, 7
	v_readlane_b32 s23, v29, 7
	s_waitcnt vmcnt(58)
	v_fma_f32 v6, v103, s18, v6
	v_fma_f32 v7, v103, s19, v7
	v_readlane_b32 s16, v28, 8
	v_readlane_b32 s17, v29, 8
	s_waitcnt vmcnt(57)
	v_fma_f32 v6, v104, s20, v6
	v_fma_f32 v7, v104, s21, v7
	v_readlane_b32 s18, v28, 9
	v_readlane_b32 s19, v29, 9
	s_waitcnt vmcnt(56)
	v_fma_f32 v6, v105, s22, v6
	v_fma_f32 v7, v105, s23, v7
	v_readlane_b32 s20, v28, 10
	v_readlane_b32 s21, v29, 10
	s_waitcnt vmcnt(55)
	v_fma_f32 v6, v106, s16, v6
	v_fma_f32 v7, v106, s17, v7
	v_readlane_b32 s22, v28, 11
	v_readlane_b32 s23, v29, 11
	s_waitcnt vmcnt(54)
	v_fma_f32 v6, v107, s18, v6
	v_fma_f32 v7, v107, s19, v7
	v_readlane_b32 s16, v28, 12
	v_readlane_b32 s17, v29, 12
	s_waitcnt vmcnt(53)
	v_fma_f32 v6, v108, s20, v6
	v_fma_f32 v7, v108, s21, v7
	v_readlane_b32 s18, v28, 13
	v_readlane_b32 s19, v29, 13
	s_waitcnt vmcnt(52)
	v_fma_f32 v6, v109, s22, v6
	v_fma_f32 v7, v109, s23, v7
	v_readlane_b32 s20, v28, 14
	v_readlane_b32 s21, v29, 14
	s_waitcnt vmcnt(51)
	v_fma_f32 v6, v110, s16, v6
	v_fma_f32 v7, v110, s17, v7
	v_readlane_b32 s22, v28, 15
	v_readlane_b32 s23, v29, 15
	s_waitcnt vmcnt(50)
	v_fma_f32 v6, v111, s18, v6
	v_fma_f32 v7, v111, s19, v7
	v_readlane_b32 s16, v28, 16
	v_readlane_b32 s17, v29, 16
	s_waitcnt vmcnt(49)
	v_fma_f32 v6, v112, s20, v6
	v_fma_f32 v7, v112, s21, v7
	v_readlane_b32 s18, v28, 17
	v_readlane_b32 s19, v29, 17
	s_waitcnt vmcnt(48)
	v_fma_f32 v6, v113, s22, v6
	v_fma_f32 v7, v113, s23, v7
	v_readlane_b32 s20, v28, 18
	v_readlane_b32 s21, v29, 18
	s_waitcnt vmcnt(47)
	v_fma_f32 v6, v114, s16, v6
	v_fma_f32 v7, v114, s17, v7
	v_readlane_b32 s22, v28, 19
	v_readlane_b32 s23, v29, 19
	s_waitcnt vmcnt(46)
	v_fma_f32 v6, v115, s18, v6
	v_fma_f32 v7, v115, s19, v7
	v_readlane_b32 s16, v28, 20
	v_readlane_b32 s17, v29, 20
	s_waitcnt vmcnt(45)
	v_fma_f32 v6, v116, s20, v6
	v_fma_f32 v7, v116, s21, v7
	v_readlane_b32 s18, v28, 21
	v_readlane_b32 s19, v29, 21
	s_waitcnt vmcnt(44)
	v_fma_f32 v6, v117, s22, v6
	v_fma_f32 v7, v117, s23, v7
	v_readlane_b32 s20, v28, 22
	v_readlane_b32 s21, v29, 22
	s_waitcnt vmcnt(43)
	v_fma_f32 v6, v118, s16, v6
	v_fma_f32 v7, v118, s17, v7
	v_readlane_b32 s22, v28, 23
	v_readlane_b32 s23, v29, 23
	s_waitcnt vmcnt(42)
	v_fma_f32 v6, v119, s18, v6
	v_fma_f32 v7, v119, s19, v7
	v_readlane_b32 s16, v28, 24
	v_readlane_b32 s17, v29, 24
	s_waitcnt vmcnt(41)
	v_fma_f32 v6, v120, s20, v6
	v_fma_f32 v7, v120, s21, v7
	v_readlane_b32 s18, v28, 25
	v_readlane_b32 s19, v29, 25
	s_waitcnt vmcnt(40)
	v_fma_f32 v6, v121, s22, v6
	v_fma_f32 v7, v121, s23, v7
	v_readlane_b32 s20, v28, 26
	v_readlane_b32 s21, v29, 26
	s_waitcnt vmcnt(39)
	v_fma_f32 v6, v122, s16, v6
	v_fma_f32 v7, v122, s17, v7
	v_readlane_b32 s22, v28, 27
	v_readlane_b32 s23, v29, 27
	s_waitcnt vmcnt(38)
	v_fma_f32 v6, v123, s18, v6
	v_fma_f32 v7, v123, s19, v7
	v_readlane_b32 s16, v28, 28
	v_readlane_b32 s17, v29, 28
	s_waitcnt vmcnt(37)
	v_fma_f32 v6, v124, s20, v6
	v_fma_f32 v7, v124, s21, v7
	v_readlane_b32 s18, v28, 29
	v_readlane_b32 s19, v29, 29
	s_waitcnt vmcnt(36)
	v_fma_f32 v6, v125, s22, v6
	v_fma_f32 v7, v125, s23, v7
	v_readlane_b32 s20, v28, 30
	v_readlane_b32 s21, v29, 30
	s_waitcnt vmcnt(35)
	v_fma_f32 v6, v126, s16, v6
	v_fma_f32 v7, v126, s17, v7
	v_readlane_b32 s22, v28, 31
	v_readlane_b32 s23, v29, 31
	s_waitcnt vmcnt(34)
	v_fma_f32 v6, v127, s18, v6
	v_fma_f32 v7, v127, s19, v7
	v_readlane_b32 s16, v28, 32
	v_readlane_b32 s17, v29, 32
	s_waitcnt vmcnt(33)
	v_fma_f32 v6, v128, s20, v6
	v_fma_f32 v7, v128, s21, v7
	v_readlane_b32 s18, v28, 33
	v_readlane_b32 s19, v29, 33
	s_waitcnt vmcnt(32)
	v_fma_f32 v6, v129, s22, v6
	v_fma_f32 v7, v129, s23, v7
	v_readlane_b32 s20, v28, 34
	v_readlane_b32 s21, v29, 34
	s_waitcnt vmcnt(31)
	v_fma_f32 v6, v130, s16, v6
	v_fma_f32 v7, v130, s17, v7
	v_readlane_b32 s22, v28, 35
	v_readlane_b32 s23, v29, 35
	s_waitcnt vmcnt(30)
	v_fma_f32 v6, v131, s18, v6
	v_fma_f32 v7, v131, s19, v7
	v_readlane_b32 s16, v28, 36
	v_readlane_b32 s17, v29, 36
	s_waitcnt vmcnt(29)
	v_fma_f32 v6, v132, s20, v6
	v_fma_f32 v7, v132, s21, v7
	v_readlane_b32 s18, v28, 37
	v_readlane_b32 s19, v29, 37
	s_waitcnt vmcnt(28)
	v_fma_f32 v6, v133, s22, v6
	v_fma_f32 v7, v133, s23, v7
	v_readlane_b32 s20, v28, 38
	v_readlane_b32 s21, v29, 38
	s_waitcnt vmcnt(27)
	v_fma_f32 v6, v134, s16, v6
	v_fma_f32 v7, v134, s17, v7
	v_readlane_b32 s22, v28, 39
	v_readlane_b32 s23, v29, 39
	s_waitcnt vmcnt(26)
	v_fma_f32 v6, v135, s18, v6
	v_fma_f32 v7, v135, s19, v7
	v_readlane_b32 s16, v28, 40
	v_readlane_b32 s17, v29, 40
	s_waitcnt vmcnt(25)
	v_fma_f32 v6, v136, s20, v6
	v_fma_f32 v7, v136, s21, v7
	v_readlane_b32 s18, v28, 41
	v_readlane_b32 s19, v29, 41
	s_waitcnt vmcnt(24)
	v_fma_f32 v6, v137, s22, v6
	v_fma_f32 v7, v137, s23, v7
	v_readlane_b32 s20, v28, 42
	v_readlane_b32 s21, v29, 42
	s_waitcnt vmcnt(23)
	v_fma_f32 v6, v138, s16, v6
	v_fma_f32 v7, v138, s17, v7
	v_readlane_b32 s22, v28, 43
	v_readlane_b32 s23, v29, 43
	s_waitcnt vmcnt(22)
	v_fma_f32 v6, v139, s18, v6
	v_fma_f32 v7, v139, s19, v7
	v_readlane_b32 s16, v28, 44
	v_readlane_b32 s17, v29, 44
	s_waitcnt vmcnt(21)
	v_fma_f32 v6, v140, s20, v6
	v_fma_f32 v7, v140, s21, v7
	v_readlane_b32 s18, v28, 45
	v_readlane_b32 s19, v29, 45
	s_waitcnt vmcnt(20)
	v_fma_f32 v6, v141, s22, v6
	v_fma_f32 v7, v141, s23, v7
	v_readlane_b32 s20, v28, 46
	v_readlane_b32 s21, v29, 46
	s_waitcnt vmcnt(19)
	v_fma_f32 v6, v142, s16, v6
	v_fma_f32 v7, v142, s17, v7
	v_readlane_b32 s22, v28, 47
	v_readlane_b32 s23, v29, 47
	s_waitcnt vmcnt(18)
	v_fma_f32 v6, v143, s18, v6
	v_fma_f32 v7, v143, s19, v7
	v_readlane_b32 s16, v28, 48
	v_readlane_b32 s17, v29, 48
	s_waitcnt vmcnt(17)
	v_fma_f32 v6, v144, s20, v6
	v_fma_f32 v7, v144, s21, v7
	v_readlane_b32 s18, v28, 49
	v_readlane_b32 s19, v29, 49
	s_waitcnt vmcnt(16)
	v_fma_f32 v6, v145, s22, v6
	v_fma_f32 v7, v145, s23, v7
	v_readlane_b32 s20, v28, 50
	v_readlane_b32 s21, v29, 50
	s_waitcnt vmcnt(15)
	v_fma_f32 v6, v146, s16, v6
	v_fma_f32 v7, v146, s17, v7
	v_readlane_b32 s22, v28, 51
	v_readlane_b32 s23, v29, 51
	s_waitcnt vmcnt(14)
	v_fma_f32 v6, v147, s18, v6
	v_fma_f32 v7, v147, s19, v7
	v_readlane_b32 s16, v28, 52
	v_readlane_b32 s17, v29, 52
	s_waitcnt vmcnt(13)
	v_fma_f32 v6, v148, s20, v6
	v_fma_f32 v7, v148, s21, v7
	v_readlane_b32 s18, v28, 53
	v_readlane_b32 s19, v29, 53
	s_waitcnt vmcnt(12)
	v_fma_f32 v6, v149, s22, v6
	v_fma_f32 v7, v149, s23, v7
	v_readlane_b32 s20, v28, 54
	v_readlane_b32 s21, v29, 54
	s_waitcnt vmcnt(11)
	v_fma_f32 v6, v150, s16, v6
	v_fma_f32 v7, v150, s17, v7
	v_readlane_b32 s22, v28, 55
	v_readlane_b32 s23, v29, 55
	s_waitcnt vmcnt(10)
	v_fma_f32 v6, v151, s18, v6
	v_fma_f32 v7, v151, s19, v7
	v_readlane_b32 s16, v28, 56
	v_readlane_b32 s17, v29, 56
	s_waitcnt vmcnt(9)
	v_fma_f32 v6, v152, s20, v6
	v_fma_f32 v7, v152, s21, v7
	v_readlane_b32 s18, v28, 57
	v_readlane_b32 s19, v29, 57
	s_waitcnt vmcnt(8)
	v_fma_f32 v6, v153, s22, v6
	v_fma_f32 v7, v153, s23, v7
	v_readlane_b32 s20, v28, 58
	v_readlane_b32 s21, v29, 58
	s_waitcnt vmcnt(7)
	v_fma_f32 v6, v154, s16, v6
	v_fma_f32 v7, v154, s17, v7
	v_readlane_b32 s22, v28, 59
	v_readlane_b32 s23, v29, 59
	s_waitcnt vmcnt(6)
	v_fma_f32 v6, v155, s18, v6
	v_fma_f32 v7, v155, s19, v7
	v_readlane_b32 s16, v28, 60
	v_readlane_b32 s17, v29, 60
	s_waitcnt vmcnt(5)
	v_fma_f32 v6, v156, s20, v6
	v_fma_f32 v7, v156, s21, v7
	v_readlane_b32 s18, v28, 61
	v_readlane_b32 s19, v29, 61
	s_waitcnt vmcnt(4)
	v_fma_f32 v6, v157, s22, v6
	v_fma_f32 v7, v157, s23, v7
	v_readlane_b32 s20, v28, 62
	v_readlane_b32 s21, v29, 62
	s_waitcnt vmcnt(3)
	v_fma_f32 v6, v158, s16, v6
	v_fma_f32 v7, v158, s17, v7
	v_readlane_b32 s22, v28, 63
	v_readlane_b32 s23, v29, 63
	s_waitcnt vmcnt(2)
	v_fma_f32 v6, v159, s18, v6
	v_fma_f32 v7, v159, s19, v7
	s_waitcnt vmcnt(1)
	v_fma_f32 v6, v164, s20, v6
	v_fma_f32 v7, v164, s21, v7
	s_waitcnt vmcnt(0)
	v_fma_f32 v6, v165, s22, v6
	v_fma_f32 v7, v165, s23, v7
	s_mov_b64 s[0:1], 0
	s_and_saveexec_b64 s[0:1], s[6:7]
	s_cbranch_execz .LBB0_740
	v_ashrrev_i32_e32 v3, 31, v2
	v_readlane_b32 s2, v251, 4
	v_lshlrev_b64 v[2:3], 2, v[2:3]
	v_readlane_b32 s3, v251, 5
	s_nop 1
	v_lshl_add_u64 v[4:5], s[2:3], 0, v[2:3]
	v_readlane_b32 s2, v250, 62
	v_readlane_b32 s3, v250, 63
	s_nop 1
	v_lshl_add_u64 v[2:3], s[2:3], 0, v[2:3]
	global_atomic_add_f32 v[2:3], v6, off
	global_atomic_add_f32 v[4:5], v7, off
	s_branch .LBB0_740

.LBB0_749:
	v_cndmask_b32_e64 v0, 0, 1, s[0:1]
	v_cmp_ne_u32_e32 vcc, 1, v0
	v_or_b32_e32 v0, s11, v10
	v_lshlrev_b64 v[8:9], 2, v[0:1]
	s_lshl_b32 s90, s11, 10
	v_lshl_add_u64 v[12:13], s[2:3], 0, v[8:9]
	v_lshl_add_u64 v[8:9], s[4:5], 0, v[8:9]
	global_load_dword v3, v[12:13], off
	global_load_dword v11, v[8:9], off
	global_load_dword v28, v[12:13], off offset:256
	global_load_dword v29, v[8:9], off offset:256
	v_lshl_add_u64 v[8:9], s[90:91], 2, v[4:5]
	s_mov_b32 s14, 0x1000
	s_mov_b32 s15, 0
	global_load_dword v32, v[8:9], off
	v_lshl_add_u64 v[8:9], v[8:9], 0, s[14:15]
	global_load_dword v33, v[8:9], off
	v_lshl_add_u64 v[8:9], v[8:9], 0, s[14:15]
	global_load_dword v34, v[8:9], off
	v_lshl_add_u64 v[8:9], v[8:9], 0, s[14:15]
	global_load_dword v35, v[8:9], off
	v_lshl_add_u64 v[8:9], v[8:9], 0, s[14:15]
	global_load_dword v36, v[8:9], off
	v_lshl_add_u64 v[8:9], v[8:9], 0, s[14:15]
	global_load_dword v37, v[8:9], off
	v_lshl_add_u64 v[8:9], v[8:9], 0, s[14:15]
	global_load_dword v38, v[8:9], off
	v_lshl_add_u64 v[8:9], v[8:9], 0, s[14:15]
	global_load_dword v39, v[8:9], off
	v_lshl_add_u64 v[8:9], v[8:9], 0, s[14:15]
	global_load_dword v40, v[8:9], off
	v_lshl_add_u64 v[8:9], v[8:9], 0, s[14:15]
	global_load_dword v41, v[8:9], off
	v_lshl_add_u64 v[8:9], v[8:9], 0, s[14:15]
	global_load_dword v42, v[8:9], off
	v_lshl_add_u64 v[8:9], v[8:9], 0, s[14:15]
	global_load_dword v43, v[8:9], off
	v_lshl_add_u64 v[8:9], v[8:9], 0, s[14:15]
	global_load_dword v44, v[8:9], off
	v_lshl_add_u64 v[8:9], v[8:9], 0, s[14:15]
	global_load_dword v45, v[8:9], off
	v_lshl_add_u64 v[8:9], v[8:9], 0, s[14:15]
	global_load_dword v46, v[8:9], off
	v_lshl_add_u64 v[8:9], v[8:9], 0, s[14:15]
	global_load_dword v47, v[8:9], off
	v_lshl_add_u64 v[8:9], v[8:9], 0, s[14:15]
	global_load_dword v48, v[8:9], off
	v_lshl_add_u64 v[8:9], v[8:9], 0, s[14:15]
	global_load_dword v49, v[8:9], off
	v_lshl_add_u64 v[8:9], v[8:9], 0, s[14:15]
	global_load_dword v50, v[8:9], off
	v_lshl_add_u64 v[8:9], v[8:9], 0, s[14:15]
	global_load_dword v51, v[8:9], off
	v_lshl_add_u64 v[8:9], v[8:9], 0, s[14:15]
	global_load_dword v52, v[8:9], off
	v_lshl_add_u64 v[8:9], v[8:9], 0, s[14:15]
	global_load_dword v53, v[8:9], off
	v_lshl_add_u64 v[8:9], v[8:9], 0, s[14:15]
	global_load_dword v54, v[8:9], off
	v_lshl_add_u64 v[8:9], v[8:9], 0, s[14:15]
	global_load_dword v55, v[8:9], off
	v_lshl_add_u64 v[8:9], v[8:9], 0, s[14:15]
	global_load_dword v58, v[8:9], off
	v_lshl_add_u64 v[8:9], v[8:9], 0, s[14:15]
	global_load_dword v59, v[8:9], off
	v_lshl_add_u64 v[8:9], v[8:9], 0, s[14:15]
	global_load_dword v60, v[8:9], off
	v_lshl_add_u64 v[8:9], v[8:9], 0, s[14:15]
	global_load_dword v61, v[8:9], off
	v_lshl_add_u64 v[8:9], v[8:9], 0, s[14:15]
	global_load_dword v62, v[8:9], off
	v_lshl_add_u64 v[8:9], v[8:9], 0, s[14:15]
	global_load_dword v63, v[8:9], off
	v_lshl_add_u64 v[8:9], v[8:9], 0, s[14:15]
	global_load_dword v64, v[8:9], off
	v_lshl_add_u64 v[8:9], v[8:9], 0, s[14:15]
	global_load_dword v65, v[8:9], off
	v_lshl_add_u64 v[8:9], v[8:9], 0, s[14:15]
	global_load_dword v66, v[8:9], off
	v_lshl_add_u64 v[8:9], v[8:9], 0, s[14:15]
	global_load_dword v67, v[8:9], off
	v_lshl_add_u64 v[8:9], v[8:9], 0, s[14:15]
	global_load_dword v68, v[8:9], off
	v_lshl_add_u64 v[8:9], v[8:9], 0, s[14:15]
	global_load_dword v69, v[8:9], off
	v_lshl_add_u64 v[8:9], v[8:9], 0, s[14:15]
	global_load_dword v70, v[8:9], off
	v_lshl_add_u64 v[8:9], v[8:9], 0, s[14:15]
	global_load_dword v71, v[8:9], off
	v_lshl_add_u64 v[8:9], v[8:9], 0, s[14:15]
	global_load_dword v72, v[8:9], off
	v_lshl_add_u64 v[8:9], v[8:9], 0, s[14:15]
	global_load_dword v73, v[8:9], off
	v_lshl_add_u64 v[8:9], v[8:9], 0, s[14:15]
	global_load_dword v74, v[8:9], off
	v_lshl_add_u64 v[8:9], v[8:9], 0, s[14:15]
	global_load_dword v75, v[8:9], off
	v_lshl_add_u64 v[8:9], v[8:9], 0, s[14:15]
	global_load_dword v76, v[8:9], off
	v_lshl_add_u64 v[8:9], v[8:9], 0, s[14:15]
	global_load_dword v77, v[8:9], off
	v_lshl_add_u64 v[8:9], v[8:9], 0, s[14:15]
	global_load_dword v78, v[8:9], off
	v_lshl_add_u64 v[8:9], v[8:9], 0, s[14:15]
	global_load_dword v79, v[8:9], off
	v_lshl_add_u64 v[8:9], v[8:9], 0, s[14:15]
	global_load_dword v80, v[8:9], off
	v_lshl_add_u64 v[8:9], v[8:9], 0, s[14:15]
	global_load_dword v81, v[8:9], off
	v_lshl_add_u64 v[8:9], v[8:9], 0, s[14:15]
	global_load_dword v82, v[8:9], off
	v_lshl_add_u64 v[8:9], v[8:9], 0, s[14:15]
	global_load_dword v83, v[8:9], off
	v_lshl_add_u64 v[8:9], v[8:9], 0, s[14:15]
	global_load_dword v84, v[8:9], off
	v_lshl_add_u64 v[8:9], v[8:9], 0, s[14:15]
	global_load_dword v85, v[8:9], off
	v_lshl_add_u64 v[8:9], v[8:9], 0, s[14:15]
	global_load_dword v86, v[8:9], off
	v_lshl_add_u64 v[8:9], v[8:9], 0, s[14:15]
	global_load_dword v87, v[8:9], off
	v_lshl_add_u64 v[8:9], v[8:9], 0, s[14:15]
	global_load_dword v88, v[8:9], off
	v_lshl_add_u64 v[8:9], v[8:9], 0, s[14:15]
	global_load_dword v89, v[8:9], off
	v_lshl_add_u64 v[8:9], v[8:9], 0, s[14:15]
	global_load_dword v90, v[8:9], off
	v_lshl_add_u64 v[8:9], v[8:9], 0, s[14:15]
	global_load_dword v91, v[8:9], off
	v_lshl_add_u64 v[8:9], v[8:9], 0, s[14:15]
	global_load_dword v92, v[8:9], off
	v_lshl_add_u64 v[8:9], v[8:9], 0, s[14:15]
	global_load_dword v93, v[8:9], off
	v_lshl_add_u64 v[8:9], v[8:9], 0, s[14:15]
	global_load_dword v94, v[8:9], off
	v_lshl_add_u64 v[8:9], v[8:9], 0, s[14:15]
	global_load_dword v95, v[8:9], off
	v_lshl_add_u64 v[8:9], v[8:9], 0, s[14:15]
	global_load_dword v96, v[8:9], off
	v_lshl_add_u64 v[8:9], v[8:9], 0, s[14:15]
	global_load_dword v97, v[8:9], off
	v_lshl_add_u64 v[8:9], v[8:9], 0, s[14:15]
	global_load_dword v98, v[8:9], off
	v_lshl_add_u64 v[8:9], v[8:9], 0, s[14:15]
	global_load_dword v99, v[8:9], off
	v_lshl_add_u64 v[8:9], v[8:9], 0, s[14:15]
	global_load_dword v100, v[8:9], off
	v_lshl_add_u64 v[8:9], v[8:9], 0, s[14:15]
	global_load_dword v101, v[8:9], off
	v_lshl_add_u64 v[8:9], v[8:9], 0, s[14:15]
	global_load_dword v102, v[8:9], off
	v_lshl_add_u64 v[8:9], v[8:9], 0, s[14:15]
	global_load_dword v103, v[8:9], off
	v_lshl_add_u64 v[8:9], v[8:9], 0, s[14:15]
	global_load_dword v104, v[8:9], off
	v_lshl_add_u64 v[8:9], v[8:9], 0, s[14:15]
	global_load_dword v105, v[8:9], off
	v_lshl_add_u64 v[8:9], v[8:9], 0, s[14:15]
	global_load_dword v106, v[8:9], off
	v_lshl_add_u64 v[8:9], v[8:9], 0, s[14:15]
	global_load_dword v107, v[8:9], off
	v_lshl_add_u64 v[8:9], v[8:9], 0, s[14:15]
	global_load_dword v108, v[8:9], off
	v_lshl_add_u64 v[8:9], v[8:9], 0, s[14:15]
	global_load_dword v109, v[8:9], off
	v_lshl_add_u64 v[8:9], v[8:9], 0, s[14:15]
	global_load_dword v110, v[8:9], off
	v_lshl_add_u64 v[8:9], v[8:9], 0, s[14:15]
	global_load_dword v111, v[8:9], off
	v_lshl_add_u64 v[8:9], v[8:9], 0, s[14:15]
	global_load_dword v112, v[8:9], off
	v_lshl_add_u64 v[8:9], v[8:9], 0, s[14:15]
	global_load_dword v113, v[8:9], off
	v_lshl_add_u64 v[8:9], v[8:9], 0, s[14:15]
	global_load_dword v114, v[8:9], off
	v_lshl_add_u64 v[8:9], v[8:9], 0, s[14:15]
	global_load_dword v115, v[8:9], off
	v_lshl_add_u64 v[8:9], v[8:9], 0, s[14:15]
	global_load_dword v116, v[8:9], off
	v_lshl_add_u64 v[8:9], v[8:9], 0, s[14:15]
	global_load_dword v117, v[8:9], off
	v_lshl_add_u64 v[8:9], v[8:9], 0, s[14:15]
	global_load_dword v118, v[8:9], off
	v_lshl_add_u64 v[8:9], v[8:9], 0, s[14:15]
	global_load_dword v119, v[8:9], off
	v_lshl_add_u64 v[8:9], v[8:9], 0, s[14:15]
	global_load_dword v120, v[8:9], off
	v_lshl_add_u64 v[8:9], v[8:9], 0, s[14:15]
	global_load_dword v121, v[8:9], off
	v_lshl_add_u64 v[8:9], v[8:9], 0, s[14:15]
	global_load_dword v122, v[8:9], off
	v_lshl_add_u64 v[8:9], v[8:9], 0, s[14:15]
	global_load_dword v123, v[8:9], off
	v_lshl_add_u64 v[8:9], v[8:9], 0, s[14:15]
	global_load_dword v124, v[8:9], off
	v_lshl_add_u64 v[8:9], v[8:9], 0, s[14:15]
	global_load_dword v125, v[8:9], off
	v_lshl_add_u64 v[8:9], v[8:9], 0, s[14:15]
	global_load_dword v126, v[8:9], off
	v_lshl_add_u64 v[8:9], v[8:9], 0, s[14:15]
	global_load_dword v127, v[8:9], off
	v_lshl_add_u64 v[8:9], v[8:9], 0, s[14:15]
	global_load_dword v128, v[8:9], off
	v_lshl_add_u64 v[8:9], v[8:9], 0, s[14:15]
	global_load_dword v129, v[8:9], off
	v_lshl_add_u64 v[8:9], v[8:9], 0, s[14:15]
	global_load_dword v130, v[8:9], off
	v_lshl_add_u64 v[8:9], v[8:9], 0, s[14:15]
	global_load_dword v131, v[8:9], off
	v_lshl_add_u64 v[8:9], v[8:9], 0, s[14:15]
	global_load_dword v132, v[8:9], off
	v_lshl_add_u64 v[8:9], v[8:9], 0, s[14:15]
	global_load_dword v133, v[8:9], off
	v_lshl_add_u64 v[8:9], v[8:9], 0, s[14:15]
	global_load_dword v134, v[8:9], off
	v_lshl_add_u64 v[8:9], v[8:9], 0, s[14:15]
	global_load_dword v135, v[8:9], off
	v_lshl_add_u64 v[8:9], v[8:9], 0, s[14:15]
	global_load_dword v136, v[8:9], off
	v_lshl_add_u64 v[8:9], v[8:9], 0, s[14:15]
	global_load_dword v137, v[8:9], off
	v_lshl_add_u64 v[8:9], v[8:9], 0, s[14:15]
	global_load_dword v138, v[8:9], off
	v_lshl_add_u64 v[8:9], v[8:9], 0, s[14:15]
	global_load_dword v139, v[8:9], off
	v_lshl_add_u64 v[8:9], v[8:9], 0, s[14:15]
	global_load_dword v140, v[8:9], off
	v_lshl_add_u64 v[8:9], v[8:9], 0, s[14:15]
	global_load_dword v141, v[8:9], off
	v_lshl_add_u64 v[8:9], v[8:9], 0, s[14:15]
	global_load_dword v142, v[8:9], off
	v_lshl_add_u64 v[8:9], v[8:9], 0, s[14:15]
	global_load_dword v143, v[8:9], off
	v_lshl_add_u64 v[8:9], v[8:9], 0, s[14:15]
	global_load_dword v144, v[8:9], off
	v_lshl_add_u64 v[8:9], v[8:9], 0, s[14:15]
	global_load_dword v145, v[8:9], off
	v_lshl_add_u64 v[8:9], v[8:9], 0, s[14:15]
	global_load_dword v146, v[8:9], off
	v_lshl_add_u64 v[8:9], v[8:9], 0, s[14:15]
	global_load_dword v147, v[8:9], off
	v_lshl_add_u64 v[8:9], v[8:9], 0, s[14:15]
	global_load_dword v148, v[8:9], off
	v_lshl_add_u64 v[8:9], v[8:9], 0, s[14:15]
	global_load_dword v149, v[8:9], off
	v_lshl_add_u64 v[8:9], v[8:9], 0, s[14:15]
	global_load_dword v150, v[8:9], off
	v_lshl_add_u64 v[8:9], v[8:9], 0, s[14:15]
	global_load_dword v151, v[8:9], off
	v_lshl_add_u64 v[8:9], v[8:9], 0, s[14:15]
	global_load_dword v152, v[8:9], off
	v_lshl_add_u64 v[8:9], v[8:9], 0, s[14:15]
	global_load_dword v153, v[8:9], off
	v_lshl_add_u64 v[8:9], v[8:9], 0, s[14:15]
	global_load_dword v154, v[8:9], off
	v_lshl_add_u64 v[8:9], v[8:9], 0, s[14:15]
	global_load_dword v155, v[8:9], off
	v_lshl_add_u64 v[8:9], v[8:9], 0, s[14:15]
	global_load_dword v156, v[8:9], off
	v_lshl_add_u64 v[8:9], v[8:9], 0, s[14:15]
	global_load_dword v157, v[8:9], off
	v_lshl_add_u64 v[8:9], v[8:9], 0, s[14:15]
	global_load_dword v158, v[8:9], off
	v_lshl_add_u64 v[8:9], v[8:9], 0, s[14:15]
	global_load_dword v159, v[8:9], off
	v_lshl_add_u64 v[8:9], v[8:9], 0, s[14:15]
	global_load_dword v164, v[8:9], off
	v_lshl_add_u64 v[8:9], v[8:9], 0, s[14:15]
	global_load_dword v165, v[8:9], off
	s_mov_b32 s11, 64
	s_and_b64 vcc, exec, vcc
	s_waitcnt vmcnt(63)
	v_readlane_b32 s16, v3, 0
	v_readlane_b32 s17, v11, 0
	v_readlane_b32 s18, v3, 1
	v_readlane_b32 s19, v11, 1
	v_readlane_b32 s20, v3, 2
	v_readlane_b32 s21, v11, 2
	v_fma_f32 v6, v32, s16, v6
	v_fma_f32 v7, v32, s17, v7
	v_readlane_b32 s22, v3, 3
	v_readlane_b32 s23, v11, 3
	v_fma_f32 v6, v33, s18, v6
	v_fma_f32 v7, v33, s19, v7
	v_readlane_b32 s16, v3, 4
	v_readlane_b32 s17, v11, 4
	v_fma_f32 v6, v34, s20, v6
	v_fma_f32 v7, v34, s21, v7
	v_readlane_b32 s18, v3, 5
	v_readlane_b32 s19, v11, 5
	v_fma_f32 v6, v35, s22, v6
	v_fma_f32 v7, v35, s23, v7
	v_readlane_b32 s20, v3, 6
	v_readlane_b32 s21, v11, 6
	v_fma_f32 v6, v36, s16, v6
	v_fma_f32 v7, v36, s17, v7
	v_readlane_b32 s22, v3, 7
	v_readlane_b32 s23, v11, 7
	v_fma_f32 v6, v37, s18, v6
	v_fma_f32 v7, v37, s19, v7
	v_readlane_b32 s16, v3, 8
	v_readlane_b32 s17, v11, 8
	v_fma_f32 v6, v38, s20, v6
	v_fma_f32 v7, v38, s21, v7
	v_readlane_b32 s18, v3, 9
	v_readlane_b32 s19, v11, 9
	v_fma_f32 v6, v39, s22, v6
	v_fma_f32 v7, v39, s23, v7
	v_readlane_b32 s20, v3, 10
	v_readlane_b32 s21, v11, 10
	v_fma_f32 v6, v40, s16, v6
	v_fma_f32 v7, v40, s17, v7
	v_readlane_b32 s22, v3, 11
	v_readlane_b32 s23, v11, 11
	v_fma_f32 v6, v41, s18, v6
	v_fma_f32 v7, v41, s19, v7
	v_readlane_b32 s16, v3, 12
	v_readlane_b32 s17, v11, 12
	v_fma_f32 v6, v42, s20, v6
	v_fma_f32 v7, v42, s21, v7
	v_readlane_b32 s18, v3, 13
	v_readlane_b32 s19, v11, 13
	v_fma_f32 v6, v43, s22, v6
	v_fma_f32 v7, v43, s23, v7
	v_readlane_b32 s20, v3, 14
	v_readlane_b32 s21, v11, 14
	v_fma_f32 v6, v44, s16, v6
	v_fma_f32 v7, v44, s17, v7
	v_readlane_b32 s22, v3, 15
	v_readlane_b32 s23, v11, 15
	v_fma_f32 v6, v45, s18, v6
	v_fma_f32 v7, v45, s19, v7
	v_readlane_b32 s16, v3, 16
	v_readlane_b32 s17, v11, 16
	v_fma_f32 v6, v46, s20, v6
	v_fma_f32 v7, v46, s21, v7
	v_readlane_b32 s18, v3, 17
	v_readlane_b32 s19, v11, 17
	v_fma_f32 v6, v47, s22, v6
	v_fma_f32 v7, v47, s23, v7
	v_readlane_b32 s20, v3, 18
	v_readlane_b32 s21, v11, 18
	v_fma_f32 v6, v48, s16, v6
	v_fma_f32 v7, v48, s17, v7
	v_readlane_b32 s22, v3, 19
	v_readlane_b32 s23, v11, 19
	v_fma_f32 v6, v49, s18, v6
	v_fma_f32 v7, v49, s19, v7
	v_readlane_b32 s16, v3, 20
	v_readlane_b32 s17, v11, 20
	v_fma_f32 v6, v50, s20, v6
	v_fma_f32 v7, v50, s21, v7
	v_readlane_b32 s18, v3, 21
	v_readlane_b32 s19, v11, 21
	v_fma_f32 v6, v51, s22, v6
	v_fma_f32 v7, v51, s23, v7
	v_readlane_b32 s20, v3, 22
	v_readlane_b32 s21, v11, 22
	v_fma_f32 v6, v52, s16, v6
	v_fma_f32 v7, v52, s17, v7
	v_readlane_b32 s22, v3, 23
	v_readlane_b32 s23, v11, 23
	v_fma_f32 v6, v53, s18, v6
	v_fma_f32 v7, v53, s19, v7
	v_readlane_b32 s16, v3, 24
	v_readlane_b32 s17, v11, 24
	v_fma_f32 v6, v54, s20, v6
	v_fma_f32 v7, v54, s21, v7
	v_readlane_b32 s18, v3, 25
	v_readlane_b32 s19, v11, 25
	v_fma_f32 v6, v55, s22, v6
	v_fma_f32 v7, v55, s23, v7
	v_readlane_b32 s20, v3, 26
	v_readlane_b32 s21, v11, 26
	v_fma_f32 v6, v58, s16, v6
	v_fma_f32 v7, v58, s17, v7
	v_readlane_b32 s22, v3, 27
	v_readlane_b32 s23, v11, 27
	v_fma_f32 v6, v59, s18, v6
	v_fma_f32 v7, v59, s19, v7
	v_readlane_b32 s16, v3, 28
	v_readlane_b32 s17, v11, 28
	v_fma_f32 v6, v60, s20, v6
	v_fma_f32 v7, v60, s21, v7
	v_readlane_b32 s18, v3, 29
	v_readlane_b32 s19, v11, 29
	v_fma_f32 v6, v61, s22, v6
	v_fma_f32 v7, v61, s23, v7
	v_readlane_b32 s20, v3, 30
	v_readlane_b32 s21, v11, 30
	v_fma_f32 v6, v62, s16, v6
	v_fma_f32 v7, v62, s17, v7
	v_readlane_b32 s22, v3, 31
	v_readlane_b32 s23, v11, 31
	v_fma_f32 v6, v63, s18, v6
	v_fma_f32 v7, v63, s19, v7
	v_readlane_b32 s16, v3, 32
	v_readlane_b32 s17, v11, 32
	v_fma_f32 v6, v64, s20, v6
	v_fma_f32 v7, v64, s21, v7
	v_readlane_b32 s18, v3, 33
	v_readlane_b32 s19, v11, 33
	v_fma_f32 v6, v65, s22, v6
	v_fma_f32 v7, v65, s23, v7
	v_readlane_b32 s20, v3, 34
	v_readlane_b32 s21, v11, 34
	v_fma_f32 v6, v66, s16, v6
	v_fma_f32 v7, v66, s17, v7
	v_readlane_b32 s22, v3, 35
	v_readlane_b32 s23, v11, 35
	v_fma_f32 v6, v67, s18, v6
	v_fma_f32 v7, v67, s19, v7
	v_readlane_b32 s16, v3, 36
	v_readlane_b32 s17, v11, 36
	v_fma_f32 v6, v68, s20, v6
	v_fma_f32 v7, v68, s21, v7
	v_readlane_b32 s18, v3, 37
	v_readlane_b32 s19, v11, 37
	v_fma_f32 v6, v69, s22, v6
	v_fma_f32 v7, v69, s23, v7
	v_readlane_b32 s20, v3, 38
	v_readlane_b32 s21, v11, 38
	v_fma_f32 v6, v70, s16, v6
	v_fma_f32 v7, v70, s17, v7
	v_readlane_b32 s22, v3, 39
	v_readlane_b32 s23, v11, 39
	v_fma_f32 v6, v71, s18, v6
	v_fma_f32 v7, v71, s19, v7
	v_readlane_b32 s16, v3, 40
	v_readlane_b32 s17, v11, 40
	v_fma_f32 v6, v72, s20, v6
	v_fma_f32 v7, v72, s21, v7
	v_readlane_b32 s18, v3, 41
	v_readlane_b32 s19, v11, 41
	v_fma_f32 v6, v73, s22, v6
	v_fma_f32 v7, v73, s23, v7
	v_readlane_b32 s20, v3, 42
	v_readlane_b32 s21, v11, 42
	v_fma_f32 v6, v74, s16, v6
	v_fma_f32 v7, v74, s17, v7
	v_readlane_b32 s22, v3, 43
	v_readlane_b32 s23, v11, 43
	v_fma_f32 v6, v75, s18, v6
	v_fma_f32 v7, v75, s19, v7
	v_readlane_b32 s16, v3, 44
	v_readlane_b32 s17, v11, 44
	v_fma_f32 v6, v76, s20, v6
	v_fma_f32 v7, v76, s21, v7
	v_readlane_b32 s18, v3, 45
	v_readlane_b32 s19, v11, 45
	v_fma_f32 v6, v77, s22, v6
	v_fma_f32 v7, v77, s23, v7
	v_readlane_b32 s20, v3, 46
	v_readlane_b32 s21, v11, 46
	v_fma_f32 v6, v78, s16, v6
	v_fma_f32 v7, v78, s17, v7
	v_readlane_b32 s22, v3, 47
	v_readlane_b32 s23, v11, 47
	v_fma_f32 v6, v79, s18, v6
	v_fma_f32 v7, v79, s19, v7
	v_readlane_b32 s16, v3, 48
	v_readlane_b32 s17, v11, 48
	v_fma_f32 v6, v80, s20, v6
	v_fma_f32 v7, v80, s21, v7
	v_readlane_b32 s18, v3, 49
	v_readlane_b32 s19, v11, 49
	v_fma_f32 v6, v81, s22, v6
	v_fma_f32 v7, v81, s23, v7
	v_readlane_b32 s20, v3, 50
	v_readlane_b32 s21, v11, 50
	v_fma_f32 v6, v82, s16, v6
	v_fma_f32 v7, v82, s17, v7
	v_readlane_b32 s22, v3, 51
	v_readlane_b32 s23, v11, 51
	v_fma_f32 v6, v83, s18, v6
	v_fma_f32 v7, v83, s19, v7
	v_readlane_b32 s16, v3, 52
	v_readlane_b32 s17, v11, 52
	v_fma_f32 v6, v84, s20, v6
	v_fma_f32 v7, v84, s21, v7
	v_readlane_b32 s18, v3, 53
	v_readlane_b32 s19, v11, 53
	v_fma_f32 v6, v85, s22, v6
	v_fma_f32 v7, v85, s23, v7
	v_readlane_b32 s20, v3, 54
	v_readlane_b32 s21, v11, 54
	v_fma_f32 v6, v86, s16, v6
	v_fma_f32 v7, v86, s17, v7
	v_readlane_b32 s22, v3, 55
	v_readlane_b32 s23, v11, 55
	v_fma_f32 v6, v87, s18, v6
	v_fma_f32 v7, v87, s19, v7
	v_readlane_b32 s16, v3, 56
	v_readlane_b32 s17, v11, 56
	v_fma_f32 v6, v88, s20, v6
	v_fma_f32 v7, v88, s21, v7
	v_readlane_b32 s18, v3, 57
	v_readlane_b32 s19, v11, 57
	v_fma_f32 v6, v89, s22, v6
	v_fma_f32 v7, v89, s23, v7
	v_readlane_b32 s20, v3, 58
	v_readlane_b32 s21, v11, 58
	v_fma_f32 v6, v90, s16, v6
	v_fma_f32 v7, v90, s17, v7
	v_readlane_b32 s22, v3, 59
	v_readlane_b32 s23, v11, 59
	v_fma_f32 v6, v91, s18, v6
	v_fma_f32 v7, v91, s19, v7
	v_readlane_b32 s16, v3, 60
	v_readlane_b32 s17, v11, 60
	v_fma_f32 v6, v92, s20, v6
	v_fma_f32 v7, v92, s21, v7
	v_readlane_b32 s18, v3, 61
	v_readlane_b32 s19, v11, 61
	v_fma_f32 v6, v93, s22, v6
	v_fma_f32 v7, v93, s23, v7
	v_readlane_b32 s20, v3, 62
	v_readlane_b32 s21, v11, 62
	v_fma_f32 v6, v94, s16, v6
	v_fma_f32 v7, v94, s17, v7
	v_readlane_b32 s22, v3, 63
	v_readlane_b32 s23, v11, 63
	v_fma_f32 v6, v95, s18, v6
	v_fma_f32 v7, v95, s19, v7
	v_readlane_b32 s16, v28, 0
	v_readlane_b32 s17, v29, 0
	v_fma_f32 v6, v96, s20, v6
	v_fma_f32 v7, v96, s21, v7
	v_readlane_b32 s18, v28, 1
	v_readlane_b32 s19, v29, 1
	v_fma_f32 v6, v97, s22, v6
	v_fma_f32 v7, v97, s23, v7
	v_readlane_b32 s20, v28, 2
	v_readlane_b32 s21, v29, 2
	v_fma_f32 v6, v98, s16, v6
	v_fma_f32 v7, v98, s17, v7
	v_readlane_b32 s22, v28, 3
	v_readlane_b32 s23, v29, 3
	s_waitcnt vmcnt(62)
	v_fma_f32 v6, v99, s18, v6
	v_fma_f32 v7, v99, s19, v7
	v_readlane_b32 s16, v28, 4
	v_readlane_b32 s17, v29, 4
	s_waitcnt vmcnt(61)
	v_fma_f32 v6, v100, s20, v6
	v_fma_f32 v7, v100, s21, v7
	v_readlane_b32 s18, v28, 5
	v_readlane_b32 s19, v29, 5
	s_waitcnt vmcnt(60)
	v_fma_f32 v6, v101, s22, v6
	v_fma_f32 v7, v101, s23, v7
	v_readlane_b32 s20, v28, 6
	v_readlane_b32 s21, v29, 6
	s_waitcnt vmcnt(59)
	v_fma_f32 v6, v102, s16, v6
	v_fma_f32 v7, v102, s17, v7
	v_readlane_b32 s22, v28, 7
	v_readlane_b32 s23, v29, 7
	s_waitcnt vmcnt(58)
	v_fma_f32 v6, v103, s18, v6
	v_fma_f32 v7, v103, s19, v7
	v_readlane_b32 s16, v28, 8
	v_readlane_b32 s17, v29, 8
	s_waitcnt vmcnt(57)
	v_fma_f32 v6, v104, s20, v6
	v_fma_f32 v7, v104, s21, v7
	v_readlane_b32 s18, v28, 9
	v_readlane_b32 s19, v29, 9
	s_waitcnt vmcnt(56)
	v_fma_f32 v6, v105, s22, v6
	v_fma_f32 v7, v105, s23, v7
	v_readlane_b32 s20, v28, 10
	v_readlane_b32 s21, v29, 10
	s_waitcnt vmcnt(55)
	v_fma_f32 v6, v106, s16, v6
	v_fma_f32 v7, v106, s17, v7
	v_readlane_b32 s22, v28, 11
	v_readlane_b32 s23, v29, 11
	s_waitcnt vmcnt(54)
	v_fma_f32 v6, v107, s18, v6
	v_fma_f32 v7, v107, s19, v7
	v_readlane_b32 s16, v28, 12
	v_readlane_b32 s17, v29, 12
	s_waitcnt vmcnt(53)
	v_fma_f32 v6, v108, s20, v6
	v_fma_f32 v7, v108, s21, v7
	v_readlane_b32 s18, v28, 13
	v_readlane_b32 s19, v29, 13
	s_waitcnt vmcnt(52)
	v_fma_f32 v6, v109, s22, v6
	v_fma_f32 v7, v109, s23, v7
	v_readlane_b32 s20, v28, 14
	v_readlane_b32 s21, v29, 14
	s_waitcnt vmcnt(51)
	v_fma_f32 v6, v110, s16, v6
	v_fma_f32 v7, v110, s17, v7
	v_readlane_b32 s22, v28, 15
	v_readlane_b32 s23, v29, 15
	s_waitcnt vmcnt(50)
	v_fma_f32 v6, v111, s18, v6
	v_fma_f32 v7, v111, s19, v7
	v_readlane_b32 s16, v28, 16
	v_readlane_b32 s17, v29, 16
	s_waitcnt vmcnt(49)
	v_fma_f32 v6, v112, s20, v6
	v_fma_f32 v7, v112, s21, v7
	v_readlane_b32 s18, v28, 17
	v_readlane_b32 s19, v29, 17
	s_waitcnt vmcnt(48)
	v_fma_f32 v6, v113, s22, v6
	v_fma_f32 v7, v113, s23, v7
	v_readlane_b32 s20, v28, 18
	v_readlane_b32 s21, v29, 18
	s_waitcnt vmcnt(47)
	v_fma_f32 v6, v114, s16, v6
	v_fma_f32 v7, v114, s17, v7
	v_readlane_b32 s22, v28, 19
	v_readlane_b32 s23, v29, 19
	s_waitcnt vmcnt(46)
	v_fma_f32 v6, v115, s18, v6
	v_fma_f32 v7, v115, s19, v7
	v_readlane_b32 s16, v28, 20
	v_readlane_b32 s17, v29, 20
	s_waitcnt vmcnt(45)
	v_fma_f32 v6, v116, s20, v6
	v_fma_f32 v7, v116, s21, v7
	v_readlane_b32 s18, v28, 21
	v_readlane_b32 s19, v29, 21
	s_waitcnt vmcnt(44)
	v_fma_f32 v6, v117, s22, v6
	v_fma_f32 v7, v117, s23, v7
	v_readlane_b32 s20, v28, 22
	v_readlane_b32 s21, v29, 22
	s_waitcnt vmcnt(43)
	v_fma_f32 v6, v118, s16, v6
	v_fma_f32 v7, v118, s17, v7
	v_readlane_b32 s22, v28, 23
	v_readlane_b32 s23, v29, 23
	s_waitcnt vmcnt(42)
	v_fma_f32 v6, v119, s18, v6
	v_fma_f32 v7, v119, s19, v7
	v_readlane_b32 s16, v28, 24
	v_readlane_b32 s17, v29, 24
	s_waitcnt vmcnt(41)
	v_fma_f32 v6, v120, s20, v6
	v_fma_f32 v7, v120, s21, v7
	v_readlane_b32 s18, v28, 25
	v_readlane_b32 s19, v29, 25
	s_waitcnt vmcnt(40)
	v_fma_f32 v6, v121, s22, v6
	v_fma_f32 v7, v121, s23, v7
	v_readlane_b32 s20, v28, 26
	v_readlane_b32 s21, v29, 26
	s_waitcnt vmcnt(39)
	v_fma_f32 v6, v122, s16, v6
	v_fma_f32 v7, v122, s17, v7
	v_readlane_b32 s22, v28, 27
	v_readlane_b32 s23, v29, 27
	s_waitcnt vmcnt(38)
	v_fma_f32 v6, v123, s18, v6
	v_fma_f32 v7, v123, s19, v7
	v_readlane_b32 s16, v28, 28
	v_readlane_b32 s17, v29, 28
	s_waitcnt vmcnt(37)
	v_fma_f32 v6, v124, s20, v6
	v_fma_f32 v7, v124, s21, v7
	v_readlane_b32 s18, v28, 29
	v_readlane_b32 s19, v29, 29
	s_waitcnt vmcnt(36)
	v_fma_f32 v6, v125, s22, v6
	v_fma_f32 v7, v125, s23, v7
	v_readlane_b32 s20, v28, 30
	v_readlane_b32 s21, v29, 30
	s_waitcnt vmcnt(35)
	v_fma_f32 v6, v126, s16, v6
	v_fma_f32 v7, v126, s17, v7
	v_readlane_b32 s22, v28, 31
	v_readlane_b32 s23, v29, 31
	s_waitcnt vmcnt(34)
	v_fma_f32 v6, v127, s18, v6
	v_fma_f32 v7, v127, s19, v7
	v_readlane_b32 s16, v28, 32
	v_readlane_b32 s17, v29, 32
	s_waitcnt vmcnt(33)
	v_fma_f32 v6, v128, s20, v6
	v_fma_f32 v7, v128, s21, v7
	v_readlane_b32 s18, v28, 33
	v_readlane_b32 s19, v29, 33
	s_waitcnt vmcnt(32)
	v_fma_f32 v6, v129, s22, v6
	v_fma_f32 v7, v129, s23, v7
	v_readlane_b32 s20, v28, 34
	v_readlane_b32 s21, v29, 34
	s_waitcnt vmcnt(31)
	v_fma_f32 v6, v130, s16, v6
	v_fma_f32 v7, v130, s17, v7
	v_readlane_b32 s22, v28, 35
	v_readlane_b32 s23, v29, 35
	s_waitcnt vmcnt(30)
	v_fma_f32 v6, v131, s18, v6
	v_fma_f32 v7, v131, s19, v7
	v_readlane_b32 s16, v28, 36
	v_readlane_b32 s17, v29, 36
	s_waitcnt vmcnt(29)
	v_fma_f32 v6, v132, s20, v6
	v_fma_f32 v7, v132, s21, v7
	v_readlane_b32 s18, v28, 37
	v_readlane_b32 s19, v29, 37
	s_waitcnt vmcnt(28)
	v_fma_f32 v6, v133, s22, v6
	v_fma_f32 v7, v133, s23, v7
	v_readlane_b32 s20, v28, 38
	v_readlane_b32 s21, v29, 38
	s_waitcnt vmcnt(27)
	v_fma_f32 v6, v134, s16, v6
	v_fma_f32 v7, v134, s17, v7
	v_readlane_b32 s22, v28, 39
	v_readlane_b32 s23, v29, 39
	s_waitcnt vmcnt(26)
	v_fma_f32 v6, v135, s18, v6
	v_fma_f32 v7, v135, s19, v7
	v_readlane_b32 s16, v28, 40
	v_readlane_b32 s17, v29, 40
	s_waitcnt vmcnt(25)
	v_fma_f32 v6, v136, s20, v6
	v_fma_f32 v7, v136, s21, v7
	v_readlane_b32 s18, v28, 41
	v_readlane_b32 s19, v29, 41
	s_waitcnt vmcnt(24)
	v_fma_f32 v6, v137, s22, v6
	v_fma_f32 v7, v137, s23, v7
	v_readlane_b32 s20, v28, 42
	v_readlane_b32 s21, v29, 42
	s_waitcnt vmcnt(23)
	v_fma_f32 v6, v138, s16, v6
	v_fma_f32 v7, v138, s17, v7
	v_readlane_b32 s22, v28, 43
	v_readlane_b32 s23, v29, 43
	s_waitcnt vmcnt(22)
	v_fma_f32 v6, v139, s18, v6
	v_fma_f32 v7, v139, s19, v7
	v_readlane_b32 s16, v28, 44
	v_readlane_b32 s17, v29, 44
	s_waitcnt vmcnt(21)
	v_fma_f32 v6, v140, s20, v6
	v_fma_f32 v7, v140, s21, v7
	v_readlane_b32 s18, v28, 45
	v_readlane_b32 s19, v29, 45
	s_waitcnt vmcnt(20)
	v_fma_f32 v6, v141, s22, v6
	v_fma_f32 v7, v141, s23, v7
	v_readlane_b32 s20, v28, 46
	v_readlane_b32 s21, v29, 46
	s_waitcnt vmcnt(19)
	v_fma_f32 v6, v142, s16, v6
	v_fma_f32 v7, v142, s17, v7
	v_readlane_b32 s22, v28, 47
	v_readlane_b32 s23, v29, 47
	s_waitcnt vmcnt(18)
	v_fma_f32 v6, v143, s18, v6
	v_fma_f32 v7, v143, s19, v7
	v_readlane_b32 s16, v28, 48
	v_readlane_b32 s17, v29, 48
	s_waitcnt vmcnt(17)
	v_fma_f32 v6, v144, s20, v6
	v_fma_f32 v7, v144, s21, v7
	v_readlane_b32 s18, v28, 49
	v_readlane_b32 s19, v29, 49
	s_waitcnt vmcnt(16)
	v_fma_f32 v6, v145, s22, v6
	v_fma_f32 v7, v145, s23, v7
	v_readlane_b32 s20, v28, 50
	v_readlane_b32 s21, v29, 50
	s_waitcnt vmcnt(15)
	v_fma_f32 v6, v146, s16, v6
	v_fma_f32 v7, v146, s17, v7
	v_readlane_b32 s22, v28, 51
	v_readlane_b32 s23, v29, 51
	s_waitcnt vmcnt(14)
	v_fma_f32 v6, v147, s18, v6
	v_fma_f32 v7, v147, s19, v7
	v_readlane_b32 s16, v28, 52
	v_readlane_b32 s17, v29, 52
	s_waitcnt vmcnt(13)
	v_fma_f32 v6, v148, s20, v6
	v_fma_f32 v7, v148, s21, v7
	v_readlane_b32 s18, v28, 53
	v_readlane_b32 s19, v29, 53
	s_waitcnt vmcnt(12)
	v_fma_f32 v6, v149, s22, v6
	v_fma_f32 v7, v149, s23, v7
	v_readlane_b32 s20, v28, 54
	v_readlane_b32 s21, v29, 54
	s_waitcnt vmcnt(11)
	v_fma_f32 v6, v150, s16, v6
	v_fma_f32 v7, v150, s17, v7
	v_readlane_b32 s22, v28, 55
	v_readlane_b32 s23, v29, 55
	s_waitcnt vmcnt(10)
	v_fma_f32 v6, v151, s18, v6
	v_fma_f32 v7, v151, s19, v7
	v_readlane_b32 s16, v28, 56
	v_readlane_b32 s17, v29, 56
	s_waitcnt vmcnt(9)
	v_fma_f32 v6, v152, s20, v6
	v_fma_f32 v7, v152, s21, v7
	v_readlane_b32 s18, v28, 57
	v_readlane_b32 s19, v29, 57
	s_waitcnt vmcnt(8)
	v_fma_f32 v6, v153, s22, v6
	v_fma_f32 v7, v153, s23, v7
	v_readlane_b32 s20, v28, 58
	v_readlane_b32 s21, v29, 58
	s_waitcnt vmcnt(7)
	v_fma_f32 v6, v154, s16, v6
	v_fma_f32 v7, v154, s17, v7
	v_readlane_b32 s22, v28, 59
	v_readlane_b32 s23, v29, 59
	s_waitcnt vmcnt(6)
	v_fma_f32 v6, v155, s18, v6
	v_fma_f32 v7, v155, s19, v7
	v_readlane_b32 s16, v28, 60
	v_readlane_b32 s17, v29, 60
	s_waitcnt vmcnt(5)
	v_fma_f32 v6, v156, s20, v6
	v_fma_f32 v7, v156, s21, v7
	v_readlane_b32 s18, v28, 61
	v_readlane_b32 s19, v29, 61
	s_waitcnt vmcnt(4)
	v_fma_f32 v6, v157, s22, v6
	v_fma_f32 v7, v157, s23, v7
	v_readlane_b32 s20, v28, 62
	v_readlane_b32 s21, v29, 62
	s_waitcnt vmcnt(3)
	v_fma_f32 v6, v158, s16, v6
	v_fma_f32 v7, v158, s17, v7
	v_readlane_b32 s22, v28, 63
	v_readlane_b32 s23, v29, 63
	s_waitcnt vmcnt(2)
	v_fma_f32 v6, v159, s18, v6
	v_fma_f32 v7, v159, s19, v7
	s_waitcnt vmcnt(1)
	v_fma_f32 v6, v164, s20, v6
	v_fma_f32 v7, v164, s21, v7
	s_waitcnt vmcnt(0)
	v_fma_f32 v6, v165, s22, v6
	v_fma_f32 v7, v165, s23, v7
	s_mov_b64 s[0:1], 0
	s_and_saveexec_b64 s[0:1], s[6:7]
	s_cbranch_execz .LBB0_747
	v_ashrrev_i32_e32 v3, 31, v2
	v_readlane_b32 s2, v251, 12
	v_lshlrev_b64 v[2:3], 2, v[2:3]
	v_readlane_b32 s3, v251, 13
	s_nop 1
	v_lshl_add_u64 v[4:5], s[2:3], 0, v[2:3]
	v_readlane_b32 s2, v251, 6
	v_readlane_b32 s3, v251, 7
	s_nop 1
	v_lshl_add_u64 v[2:3], s[2:3], 0, v[2:3]
	global_atomic_add_f32 v[2:3], v6, off
	global_atomic_add_f32 v[4:5], v7, off
	s_branch .LBB0_747

.LBB0_756:
	v_cndmask_b32_e64 v0, 0, 1, s[0:1]
	v_cmp_ne_u32_e32 vcc, 1, v0
	v_or_b32_e32 v0, s11, v10
	v_lshlrev_b64 v[8:9], 2, v[0:1]
	s_lshl_b32 s90, s11, 10
	v_lshl_add_u64 v[12:13], s[2:3], 0, v[8:9]
	v_lshl_add_u64 v[8:9], s[4:5], 0, v[8:9]
	global_load_dword v3, v[12:13], off
	global_load_dword v11, v[8:9], off
	global_load_dword v28, v[12:13], off offset:256
	global_load_dword v29, v[8:9], off offset:256
	v_lshl_add_u64 v[8:9], s[90:91], 2, v[4:5]
	s_mov_b32 s14, 0x1000
	s_mov_b32 s15, 0
	global_load_dword v32, v[8:9], off
	v_lshl_add_u64 v[8:9], v[8:9], 0, s[14:15]
	global_load_dword v33, v[8:9], off
	v_lshl_add_u64 v[8:9], v[8:9], 0, s[14:15]
	global_load_dword v34, v[8:9], off
	v_lshl_add_u64 v[8:9], v[8:9], 0, s[14:15]
	global_load_dword v35, v[8:9], off
	v_lshl_add_u64 v[8:9], v[8:9], 0, s[14:15]
	global_load_dword v36, v[8:9], off
	v_lshl_add_u64 v[8:9], v[8:9], 0, s[14:15]
	global_load_dword v37, v[8:9], off
	v_lshl_add_u64 v[8:9], v[8:9], 0, s[14:15]
	global_load_dword v38, v[8:9], off
	v_lshl_add_u64 v[8:9], v[8:9], 0, s[14:15]
	global_load_dword v39, v[8:9], off
	v_lshl_add_u64 v[8:9], v[8:9], 0, s[14:15]
	global_load_dword v40, v[8:9], off
	v_lshl_add_u64 v[8:9], v[8:9], 0, s[14:15]
	global_load_dword v41, v[8:9], off
	v_lshl_add_u64 v[8:9], v[8:9], 0, s[14:15]
	global_load_dword v42, v[8:9], off
	v_lshl_add_u64 v[8:9], v[8:9], 0, s[14:15]
	global_load_dword v43, v[8:9], off
	v_lshl_add_u64 v[8:9], v[8:9], 0, s[14:15]
	global_load_dword v44, v[8:9], off
	v_lshl_add_u64 v[8:9], v[8:9], 0, s[14:15]
	global_load_dword v45, v[8:9], off
	v_lshl_add_u64 v[8:9], v[8:9], 0, s[14:15]
	global_load_dword v46, v[8:9], off
	v_lshl_add_u64 v[8:9], v[8:9], 0, s[14:15]
	global_load_dword v47, v[8:9], off
	v_lshl_add_u64 v[8:9], v[8:9], 0, s[14:15]
	global_load_dword v48, v[8:9], off
	v_lshl_add_u64 v[8:9], v[8:9], 0, s[14:15]
	global_load_dword v49, v[8:9], off
	v_lshl_add_u64 v[8:9], v[8:9], 0, s[14:15]
	global_load_dword v50, v[8:9], off
	v_lshl_add_u64 v[8:9], v[8:9], 0, s[14:15]
	global_load_dword v51, v[8:9], off
	v_lshl_add_u64 v[8:9], v[8:9], 0, s[14:15]
	global_load_dword v52, v[8:9], off
	v_lshl_add_u64 v[8:9], v[8:9], 0, s[14:15]
	global_load_dword v53, v[8:9], off
	v_lshl_add_u64 v[8:9], v[8:9], 0, s[14:15]
	global_load_dword v54, v[8:9], off
	v_lshl_add_u64 v[8:9], v[8:9], 0, s[14:15]
	global_load_dword v55, v[8:9], off
	v_lshl_add_u64 v[8:9], v[8:9], 0, s[14:15]
	global_load_dword v58, v[8:9], off
	v_lshl_add_u64 v[8:9], v[8:9], 0, s[14:15]
	global_load_dword v59, v[8:9], off
	v_lshl_add_u64 v[8:9], v[8:9], 0, s[14:15]
	global_load_dword v60, v[8:9], off
	v_lshl_add_u64 v[8:9], v[8:9], 0, s[14:15]
	global_load_dword v61, v[8:9], off
	v_lshl_add_u64 v[8:9], v[8:9], 0, s[14:15]
	global_load_dword v62, v[8:9], off
	v_lshl_add_u64 v[8:9], v[8:9], 0, s[14:15]
	global_load_dword v63, v[8:9], off
	v_lshl_add_u64 v[8:9], v[8:9], 0, s[14:15]
	global_load_dword v64, v[8:9], off
	v_lshl_add_u64 v[8:9], v[8:9], 0, s[14:15]
	global_load_dword v65, v[8:9], off
	v_lshl_add_u64 v[8:9], v[8:9], 0, s[14:15]
	global_load_dword v66, v[8:9], off
	v_lshl_add_u64 v[8:9], v[8:9], 0, s[14:15]
	global_load_dword v67, v[8:9], off
	v_lshl_add_u64 v[8:9], v[8:9], 0, s[14:15]
	global_load_dword v68, v[8:9], off
	v_lshl_add_u64 v[8:9], v[8:9], 0, s[14:15]
	global_load_dword v69, v[8:9], off
	v_lshl_add_u64 v[8:9], v[8:9], 0, s[14:15]
	global_load_dword v70, v[8:9], off
	v_lshl_add_u64 v[8:9], v[8:9], 0, s[14:15]
	global_load_dword v71, v[8:9], off
	v_lshl_add_u64 v[8:9], v[8:9], 0, s[14:15]
	global_load_dword v72, v[8:9], off
	v_lshl_add_u64 v[8:9], v[8:9], 0, s[14:15]
	global_load_dword v73, v[8:9], off
	v_lshl_add_u64 v[8:9], v[8:9], 0, s[14:15]
	global_load_dword v74, v[8:9], off
	v_lshl_add_u64 v[8:9], v[8:9], 0, s[14:15]
	global_load_dword v75, v[8:9], off
	v_lshl_add_u64 v[8:9], v[8:9], 0, s[14:15]
	global_load_dword v76, v[8:9], off
	v_lshl_add_u64 v[8:9], v[8:9], 0, s[14:15]
	global_load_dword v77, v[8:9], off
	v_lshl_add_u64 v[8:9], v[8:9], 0, s[14:15]
	global_load_dword v78, v[8:9], off
	v_lshl_add_u64 v[8:9], v[8:9], 0, s[14:15]
	global_load_dword v79, v[8:9], off
	v_lshl_add_u64 v[8:9], v[8:9], 0, s[14:15]
	global_load_dword v80, v[8:9], off
	v_lshl_add_u64 v[8:9], v[8:9], 0, s[14:15]
	global_load_dword v81, v[8:9], off
	v_lshl_add_u64 v[8:9], v[8:9], 0, s[14:15]
	global_load_dword v82, v[8:9], off
	v_lshl_add_u64 v[8:9], v[8:9], 0, s[14:15]
	global_load_dword v83, v[8:9], off
	v_lshl_add_u64 v[8:9], v[8:9], 0, s[14:15]
	global_load_dword v84, v[8:9], off
	v_lshl_add_u64 v[8:9], v[8:9], 0, s[14:15]
	global_load_dword v85, v[8:9], off
	v_lshl_add_u64 v[8:9], v[8:9], 0, s[14:15]
	global_load_dword v86, v[8:9], off
	v_lshl_add_u64 v[8:9], v[8:9], 0, s[14:15]
	global_load_dword v87, v[8:9], off
	v_lshl_add_u64 v[8:9], v[8:9], 0, s[14:15]
	global_load_dword v88, v[8:9], off
	v_lshl_add_u64 v[8:9], v[8:9], 0, s[14:15]
	global_load_dword v89, v[8:9], off
	v_lshl_add_u64 v[8:9], v[8:9], 0, s[14:15]
	global_load_dword v90, v[8:9], off
	v_lshl_add_u64 v[8:9], v[8:9], 0, s[14:15]
	global_load_dword v91, v[8:9], off
	v_lshl_add_u64 v[8:9], v[8:9], 0, s[14:15]
	global_load_dword v92, v[8:9], off
	v_lshl_add_u64 v[8:9], v[8:9], 0, s[14:15]
	global_load_dword v93, v[8:9], off
	v_lshl_add_u64 v[8:9], v[8:9], 0, s[14:15]
	global_load_dword v94, v[8:9], off
	v_lshl_add_u64 v[8:9], v[8:9], 0, s[14:15]
	global_load_dword v95, v[8:9], off
	v_lshl_add_u64 v[8:9], v[8:9], 0, s[14:15]
	global_load_dword v96, v[8:9], off
	v_lshl_add_u64 v[8:9], v[8:9], 0, s[14:15]
	global_load_dword v97, v[8:9], off
	v_lshl_add_u64 v[8:9], v[8:9], 0, s[14:15]
	global_load_dword v98, v[8:9], off
	v_lshl_add_u64 v[8:9], v[8:9], 0, s[14:15]
	global_load_dword v99, v[8:9], off
	v_lshl_add_u64 v[8:9], v[8:9], 0, s[14:15]
	global_load_dword v100, v[8:9], off
	v_lshl_add_u64 v[8:9], v[8:9], 0, s[14:15]
	global_load_dword v101, v[8:9], off
	v_lshl_add_u64 v[8:9], v[8:9], 0, s[14:15]
	global_load_dword v102, v[8:9], off
	v_lshl_add_u64 v[8:9], v[8:9], 0, s[14:15]
	global_load_dword v103, v[8:9], off
	v_lshl_add_u64 v[8:9], v[8:9], 0, s[14:15]
	global_load_dword v104, v[8:9], off
	v_lshl_add_u64 v[8:9], v[8:9], 0, s[14:15]
	global_load_dword v105, v[8:9], off
	v_lshl_add_u64 v[8:9], v[8:9], 0, s[14:15]
	global_load_dword v106, v[8:9], off
	v_lshl_add_u64 v[8:9], v[8:9], 0, s[14:15]
	global_load_dword v107, v[8:9], off
	v_lshl_add_u64 v[8:9], v[8:9], 0, s[14:15]
	global_load_dword v108, v[8:9], off
	v_lshl_add_u64 v[8:9], v[8:9], 0, s[14:15]
	global_load_dword v109, v[8:9], off
	v_lshl_add_u64 v[8:9], v[8:9], 0, s[14:15]
	global_load_dword v110, v[8:9], off
	v_lshl_add_u64 v[8:9], v[8:9], 0, s[14:15]
	global_load_dword v111, v[8:9], off
	v_lshl_add_u64 v[8:9], v[8:9], 0, s[14:15]
	global_load_dword v112, v[8:9], off
	v_lshl_add_u64 v[8:9], v[8:9], 0, s[14:15]
	global_load_dword v113, v[8:9], off
	v_lshl_add_u64 v[8:9], v[8:9], 0, s[14:15]
	global_load_dword v114, v[8:9], off
	v_lshl_add_u64 v[8:9], v[8:9], 0, s[14:15]
	global_load_dword v115, v[8:9], off
	v_lshl_add_u64 v[8:9], v[8:9], 0, s[14:15]
	global_load_dword v116, v[8:9], off
	v_lshl_add_u64 v[8:9], v[8:9], 0, s[14:15]
	global_load_dword v117, v[8:9], off
	v_lshl_add_u64 v[8:9], v[8:9], 0, s[14:15]
	global_load_dword v118, v[8:9], off
	v_lshl_add_u64 v[8:9], v[8:9], 0, s[14:15]
	global_load_dword v119, v[8:9], off
	v_lshl_add_u64 v[8:9], v[8:9], 0, s[14:15]
	global_load_dword v120, v[8:9], off
	v_lshl_add_u64 v[8:9], v[8:9], 0, s[14:15]
	global_load_dword v121, v[8:9], off
	v_lshl_add_u64 v[8:9], v[8:9], 0, s[14:15]
	global_load_dword v122, v[8:9], off
	v_lshl_add_u64 v[8:9], v[8:9], 0, s[14:15]
	global_load_dword v123, v[8:9], off
	v_lshl_add_u64 v[8:9], v[8:9], 0, s[14:15]
	global_load_dword v124, v[8:9], off
	v_lshl_add_u64 v[8:9], v[8:9], 0, s[14:15]
	global_load_dword v125, v[8:9], off
	v_lshl_add_u64 v[8:9], v[8:9], 0, s[14:15]
	global_load_dword v126, v[8:9], off
	v_lshl_add_u64 v[8:9], v[8:9], 0, s[14:15]
	global_load_dword v127, v[8:9], off
	v_lshl_add_u64 v[8:9], v[8:9], 0, s[14:15]
	global_load_dword v128, v[8:9], off
	v_lshl_add_u64 v[8:9], v[8:9], 0, s[14:15]
	global_load_dword v129, v[8:9], off
	v_lshl_add_u64 v[8:9], v[8:9], 0, s[14:15]
	global_load_dword v130, v[8:9], off
	v_lshl_add_u64 v[8:9], v[8:9], 0, s[14:15]
	global_load_dword v131, v[8:9], off
	v_lshl_add_u64 v[8:9], v[8:9], 0, s[14:15]
	global_load_dword v132, v[8:9], off
	v_lshl_add_u64 v[8:9], v[8:9], 0, s[14:15]
	global_load_dword v133, v[8:9], off
	v_lshl_add_u64 v[8:9], v[8:9], 0, s[14:15]
	global_load_dword v134, v[8:9], off
	v_lshl_add_u64 v[8:9], v[8:9], 0, s[14:15]
	global_load_dword v135, v[8:9], off
	v_lshl_add_u64 v[8:9], v[8:9], 0, s[14:15]
	global_load_dword v136, v[8:9], off
	v_lshl_add_u64 v[8:9], v[8:9], 0, s[14:15]
	global_load_dword v137, v[8:9], off
	v_lshl_add_u64 v[8:9], v[8:9], 0, s[14:15]
	global_load_dword v138, v[8:9], off
	v_lshl_add_u64 v[8:9], v[8:9], 0, s[14:15]
	global_load_dword v139, v[8:9], off
	v_lshl_add_u64 v[8:9], v[8:9], 0, s[14:15]
	global_load_dword v140, v[8:9], off
	v_lshl_add_u64 v[8:9], v[8:9], 0, s[14:15]
	global_load_dword v141, v[8:9], off
	v_lshl_add_u64 v[8:9], v[8:9], 0, s[14:15]
	global_load_dword v142, v[8:9], off
	v_lshl_add_u64 v[8:9], v[8:9], 0, s[14:15]
	global_load_dword v143, v[8:9], off
	v_lshl_add_u64 v[8:9], v[8:9], 0, s[14:15]
	global_load_dword v144, v[8:9], off
	v_lshl_add_u64 v[8:9], v[8:9], 0, s[14:15]
	global_load_dword v145, v[8:9], off
	v_lshl_add_u64 v[8:9], v[8:9], 0, s[14:15]
	global_load_dword v146, v[8:9], off
	v_lshl_add_u64 v[8:9], v[8:9], 0, s[14:15]
	global_load_dword v147, v[8:9], off
	v_lshl_add_u64 v[8:9], v[8:9], 0, s[14:15]
	global_load_dword v148, v[8:9], off
	v_lshl_add_u64 v[8:9], v[8:9], 0, s[14:15]
	global_load_dword v149, v[8:9], off
	v_lshl_add_u64 v[8:9], v[8:9], 0, s[14:15]
	global_load_dword v150, v[8:9], off
	v_lshl_add_u64 v[8:9], v[8:9], 0, s[14:15]
	global_load_dword v151, v[8:9], off
	v_lshl_add_u64 v[8:9], v[8:9], 0, s[14:15]
	global_load_dword v152, v[8:9], off
	v_lshl_add_u64 v[8:9], v[8:9], 0, s[14:15]
	global_load_dword v153, v[8:9], off
	v_lshl_add_u64 v[8:9], v[8:9], 0, s[14:15]
	global_load_dword v154, v[8:9], off
	v_lshl_add_u64 v[8:9], v[8:9], 0, s[14:15]
	global_load_dword v155, v[8:9], off
	v_lshl_add_u64 v[8:9], v[8:9], 0, s[14:15]
	global_load_dword v156, v[8:9], off
	v_lshl_add_u64 v[8:9], v[8:9], 0, s[14:15]
	global_load_dword v157, v[8:9], off
	v_lshl_add_u64 v[8:9], v[8:9], 0, s[14:15]
	global_load_dword v158, v[8:9], off
	v_lshl_add_u64 v[8:9], v[8:9], 0, s[14:15]
	global_load_dword v159, v[8:9], off
	v_lshl_add_u64 v[8:9], v[8:9], 0, s[14:15]
	global_load_dword v164, v[8:9], off
	v_lshl_add_u64 v[8:9], v[8:9], 0, s[14:15]
	global_load_dword v165, v[8:9], off
	s_mov_b32 s11, 64
	s_and_b64 vcc, exec, vcc
	s_waitcnt vmcnt(63)
	v_readlane_b32 s16, v3, 0
	v_readlane_b32 s17, v11, 0
	v_readlane_b32 s18, v3, 1
	v_readlane_b32 s19, v11, 1
	v_readlane_b32 s20, v3, 2
	v_readlane_b32 s21, v11, 2
	v_fma_f32 v6, v32, s16, v6
	v_fma_f32 v7, v32, s17, v7
	v_readlane_b32 s22, v3, 3
	v_readlane_b32 s23, v11, 3
	v_fma_f32 v6, v33, s18, v6
	v_fma_f32 v7, v33, s19, v7
	v_readlane_b32 s16, v3, 4
	v_readlane_b32 s17, v11, 4
	v_fma_f32 v6, v34, s20, v6
	v_fma_f32 v7, v34, s21, v7
	v_readlane_b32 s18, v3, 5
	v_readlane_b32 s19, v11, 5
	v_fma_f32 v6, v35, s22, v6
	v_fma_f32 v7, v35, s23, v7
	v_readlane_b32 s20, v3, 6
	v_readlane_b32 s21, v11, 6
	v_fma_f32 v6, v36, s16, v6
	v_fma_f32 v7, v36, s17, v7
	v_readlane_b32 s22, v3, 7
	v_readlane_b32 s23, v11, 7
	v_fma_f32 v6, v37, s18, v6
	v_fma_f32 v7, v37, s19, v7
	v_readlane_b32 s16, v3, 8
	v_readlane_b32 s17, v11, 8
	v_fma_f32 v6, v38, s20, v6
	v_fma_f32 v7, v38, s21, v7
	v_readlane_b32 s18, v3, 9
	v_readlane_b32 s19, v11, 9
	v_fma_f32 v6, v39, s22, v6
	v_fma_f32 v7, v39, s23, v7
	v_readlane_b32 s20, v3, 10
	v_readlane_b32 s21, v11, 10
	v_fma_f32 v6, v40, s16, v6
	v_fma_f32 v7, v40, s17, v7
	v_readlane_b32 s22, v3, 11
	v_readlane_b32 s23, v11, 11
	v_fma_f32 v6, v41, s18, v6
	v_fma_f32 v7, v41, s19, v7
	v_readlane_b32 s16, v3, 12
	v_readlane_b32 s17, v11, 12
	v_fma_f32 v6, v42, s20, v6
	v_fma_f32 v7, v42, s21, v7
	v_readlane_b32 s18, v3, 13
	v_readlane_b32 s19, v11, 13
	v_fma_f32 v6, v43, s22, v6
	v_fma_f32 v7, v43, s23, v7
	v_readlane_b32 s20, v3, 14
	v_readlane_b32 s21, v11, 14
	v_fma_f32 v6, v44, s16, v6
	v_fma_f32 v7, v44, s17, v7
	v_readlane_b32 s22, v3, 15
	v_readlane_b32 s23, v11, 15
	v_fma_f32 v6, v45, s18, v6
	v_fma_f32 v7, v45, s19, v7
	v_readlane_b32 s16, v3, 16
	v_readlane_b32 s17, v11, 16
	v_fma_f32 v6, v46, s20, v6
	v_fma_f32 v7, v46, s21, v7
	v_readlane_b32 s18, v3, 17
	v_readlane_b32 s19, v11, 17
	v_fma_f32 v6, v47, s22, v6
	v_fma_f32 v7, v47, s23, v7
	v_readlane_b32 s20, v3, 18
	v_readlane_b32 s21, v11, 18
	v_fma_f32 v6, v48, s16, v6
	v_fma_f32 v7, v48, s17, v7
	v_readlane_b32 s22, v3, 19
	v_readlane_b32 s23, v11, 19
	v_fma_f32 v6, v49, s18, v6
	v_fma_f32 v7, v49, s19, v7
	v_readlane_b32 s16, v3, 20
	v_readlane_b32 s17, v11, 20
	v_fma_f32 v6, v50, s20, v6
	v_fma_f32 v7, v50, s21, v7
	v_readlane_b32 s18, v3, 21
	v_readlane_b32 s19, v11, 21
	v_fma_f32 v6, v51, s22, v6
	v_fma_f32 v7, v51, s23, v7
	v_readlane_b32 s20, v3, 22
	v_readlane_b32 s21, v11, 22
	v_fma_f32 v6, v52, s16, v6
	v_fma_f32 v7, v52, s17, v7
	v_readlane_b32 s22, v3, 23
	v_readlane_b32 s23, v11, 23
	v_fma_f32 v6, v53, s18, v6
	v_fma_f32 v7, v53, s19, v7
	v_readlane_b32 s16, v3, 24
	v_readlane_b32 s17, v11, 24
	v_fma_f32 v6, v54, s20, v6
	v_fma_f32 v7, v54, s21, v7
	v_readlane_b32 s18, v3, 25
	v_readlane_b32 s19, v11, 25
	v_fma_f32 v6, v55, s22, v6
	v_fma_f32 v7, v55, s23, v7
	v_readlane_b32 s20, v3, 26
	v_readlane_b32 s21, v11, 26
	v_fma_f32 v6, v58, s16, v6
	v_fma_f32 v7, v58, s17, v7
	v_readlane_b32 s22, v3, 27
	v_readlane_b32 s23, v11, 27
	v_fma_f32 v6, v59, s18, v6
	v_fma_f32 v7, v59, s19, v7
	v_readlane_b32 s16, v3, 28
	v_readlane_b32 s17, v11, 28
	v_fma_f32 v6, v60, s20, v6
	v_fma_f32 v7, v60, s21, v7
	v_readlane_b32 s18, v3, 29
	v_readlane_b32 s19, v11, 29
	v_fma_f32 v6, v61, s22, v6
	v_fma_f32 v7, v61, s23, v7
	v_readlane_b32 s20, v3, 30
	v_readlane_b32 s21, v11, 30
	v_fma_f32 v6, v62, s16, v6
	v_fma_f32 v7, v62, s17, v7
	v_readlane_b32 s22, v3, 31
	v_readlane_b32 s23, v11, 31
	v_fma_f32 v6, v63, s18, v6
	v_fma_f32 v7, v63, s19, v7
	v_readlane_b32 s16, v3, 32
	v_readlane_b32 s17, v11, 32
	v_fma_f32 v6, v64, s20, v6
	v_fma_f32 v7, v64, s21, v7
	v_readlane_b32 s18, v3, 33
	v_readlane_b32 s19, v11, 33
	v_fma_f32 v6, v65, s22, v6
	v_fma_f32 v7, v65, s23, v7
	v_readlane_b32 s20, v3, 34
	v_readlane_b32 s21, v11, 34
	v_fma_f32 v6, v66, s16, v6
	v_fma_f32 v7, v66, s17, v7
	v_readlane_b32 s22, v3, 35
	v_readlane_b32 s23, v11, 35
	v_fma_f32 v6, v67, s18, v6
	v_fma_f32 v7, v67, s19, v7
	v_readlane_b32 s16, v3, 36
	v_readlane_b32 s17, v11, 36
	v_fma_f32 v6, v68, s20, v6
	v_fma_f32 v7, v68, s21, v7
	v_readlane_b32 s18, v3, 37
	v_readlane_b32 s19, v11, 37
	v_fma_f32 v6, v69, s22, v6
	v_fma_f32 v7, v69, s23, v7
	v_readlane_b32 s20, v3, 38
	v_readlane_b32 s21, v11, 38
	v_fma_f32 v6, v70, s16, v6
	v_fma_f32 v7, v70, s17, v7
	v_readlane_b32 s22, v3, 39
	v_readlane_b32 s23, v11, 39
	v_fma_f32 v6, v71, s18, v6
	v_fma_f32 v7, v71, s19, v7
	v_readlane_b32 s16, v3, 40
	v_readlane_b32 s17, v11, 40
	v_fma_f32 v6, v72, s20, v6
	v_fma_f32 v7, v72, s21, v7
	v_readlane_b32 s18, v3, 41
	v_readlane_b32 s19, v11, 41
	v_fma_f32 v6, v73, s22, v6
	v_fma_f32 v7, v73, s23, v7
	v_readlane_b32 s20, v3, 42
	v_readlane_b32 s21, v11, 42
	v_fma_f32 v6, v74, s16, v6
	v_fma_f32 v7, v74, s17, v7
	v_readlane_b32 s22, v3, 43
	v_readlane_b32 s23, v11, 43
	v_fma_f32 v6, v75, s18, v6
	v_fma_f32 v7, v75, s19, v7
	v_readlane_b32 s16, v3, 44
	v_readlane_b32 s17, v11, 44
	v_fma_f32 v6, v76, s20, v6
	v_fma_f32 v7, v76, s21, v7
	v_readlane_b32 s18, v3, 45
	v_readlane_b32 s19, v11, 45
	v_fma_f32 v6, v77, s22, v6
	v_fma_f32 v7, v77, s23, v7
	v_readlane_b32 s20, v3, 46
	v_readlane_b32 s21, v11, 46
	v_fma_f32 v6, v78, s16, v6
	v_fma_f32 v7, v78, s17, v7
	v_readlane_b32 s22, v3, 47
	v_readlane_b32 s23, v11, 47
	v_fma_f32 v6, v79, s18, v6
	v_fma_f32 v7, v79, s19, v7
	v_readlane_b32 s16, v3, 48
	v_readlane_b32 s17, v11, 48
	v_fma_f32 v6, v80, s20, v6
	v_fma_f32 v7, v80, s21, v7
	v_readlane_b32 s18, v3, 49
	v_readlane_b32 s19, v11, 49
	v_fma_f32 v6, v81, s22, v6
	v_fma_f32 v7, v81, s23, v7
	v_readlane_b32 s20, v3, 50
	v_readlane_b32 s21, v11, 50
	v_fma_f32 v6, v82, s16, v6
	v_fma_f32 v7, v82, s17, v7
	v_readlane_b32 s22, v3, 51
	v_readlane_b32 s23, v11, 51
	v_fma_f32 v6, v83, s18, v6
	v_fma_f32 v7, v83, s19, v7
	v_readlane_b32 s16, v3, 52
	v_readlane_b32 s17, v11, 52
	v_fma_f32 v6, v84, s20, v6
	v_fma_f32 v7, v84, s21, v7
	v_readlane_b32 s18, v3, 53
	v_readlane_b32 s19, v11, 53
	v_fma_f32 v6, v85, s22, v6
	v_fma_f32 v7, v85, s23, v7
	v_readlane_b32 s20, v3, 54
	v_readlane_b32 s21, v11, 54
	v_fma_f32 v6, v86, s16, v6
	v_fma_f32 v7, v86, s17, v7
	v_readlane_b32 s22, v3, 55
	v_readlane_b32 s23, v11, 55
	v_fma_f32 v6, v87, s18, v6
	v_fma_f32 v7, v87, s19, v7
	v_readlane_b32 s16, v3, 56
	v_readlane_b32 s17, v11, 56
	v_fma_f32 v6, v88, s20, v6
	v_fma_f32 v7, v88, s21, v7
	v_readlane_b32 s18, v3, 57
	v_readlane_b32 s19, v11, 57
	v_fma_f32 v6, v89, s22, v6
	v_fma_f32 v7, v89, s23, v7
	v_readlane_b32 s20, v3, 58
	v_readlane_b32 s21, v11, 58
	v_fma_f32 v6, v90, s16, v6
	v_fma_f32 v7, v90, s17, v7
	v_readlane_b32 s22, v3, 59
	v_readlane_b32 s23, v11, 59
	v_fma_f32 v6, v91, s18, v6
	v_fma_f32 v7, v91, s19, v7
	v_readlane_b32 s16, v3, 60
	v_readlane_b32 s17, v11, 60
	v_fma_f32 v6, v92, s20, v6
	v_fma_f32 v7, v92, s21, v7
	v_readlane_b32 s18, v3, 61
	v_readlane_b32 s19, v11, 61
	v_fma_f32 v6, v93, s22, v6
	v_fma_f32 v7, v93, s23, v7
	v_readlane_b32 s20, v3, 62
	v_readlane_b32 s21, v11, 62
	v_fma_f32 v6, v94, s16, v6
	v_fma_f32 v7, v94, s17, v7
	v_readlane_b32 s22, v3, 63
	v_readlane_b32 s23, v11, 63
	v_fma_f32 v6, v95, s18, v6
	v_fma_f32 v7, v95, s19, v7
	v_readlane_b32 s16, v28, 0
	v_readlane_b32 s17, v29, 0
	v_fma_f32 v6, v96, s20, v6
	v_fma_f32 v7, v96, s21, v7
	v_readlane_b32 s18, v28, 1
	v_readlane_b32 s19, v29, 1
	v_fma_f32 v6, v97, s22, v6
	v_fma_f32 v7, v97, s23, v7
	v_readlane_b32 s20, v28, 2
	v_readlane_b32 s21, v29, 2
	v_fma_f32 v6, v98, s16, v6
	v_fma_f32 v7, v98, s17, v7
	v_readlane_b32 s22, v28, 3
	v_readlane_b32 s23, v29, 3
	s_waitcnt vmcnt(62)
	v_fma_f32 v6, v99, s18, v6
	v_fma_f32 v7, v99, s19, v7
	v_readlane_b32 s16, v28, 4
	v_readlane_b32 s17, v29, 4
	s_waitcnt vmcnt(61)
	v_fma_f32 v6, v100, s20, v6
	v_fma_f32 v7, v100, s21, v7
	v_readlane_b32 s18, v28, 5
	v_readlane_b32 s19, v29, 5
	s_waitcnt vmcnt(60)
	v_fma_f32 v6, v101, s22, v6
	v_fma_f32 v7, v101, s23, v7
	v_readlane_b32 s20, v28, 6
	v_readlane_b32 s21, v29, 6
	s_waitcnt vmcnt(59)
	v_fma_f32 v6, v102, s16, v6
	v_fma_f32 v7, v102, s17, v7
	v_readlane_b32 s22, v28, 7
	v_readlane_b32 s23, v29, 7
	s_waitcnt vmcnt(58)
	v_fma_f32 v6, v103, s18, v6
	v_fma_f32 v7, v103, s19, v7
	v_readlane_b32 s16, v28, 8
	v_readlane_b32 s17, v29, 8
	s_waitcnt vmcnt(57)
	v_fma_f32 v6, v104, s20, v6
	v_fma_f32 v7, v104, s21, v7
	v_readlane_b32 s18, v28, 9
	v_readlane_b32 s19, v29, 9
	s_waitcnt vmcnt(56)
	v_fma_f32 v6, v105, s22, v6
	v_fma_f32 v7, v105, s23, v7
	v_readlane_b32 s20, v28, 10
	v_readlane_b32 s21, v29, 10
	s_waitcnt vmcnt(55)
	v_fma_f32 v6, v106, s16, v6
	v_fma_f32 v7, v106, s17, v7
	v_readlane_b32 s22, v28, 11
	v_readlane_b32 s23, v29, 11
	s_waitcnt vmcnt(54)
	v_fma_f32 v6, v107, s18, v6
	v_fma_f32 v7, v107, s19, v7
	v_readlane_b32 s16, v28, 12
	v_readlane_b32 s17, v29, 12
	s_waitcnt vmcnt(53)
	v_fma_f32 v6, v108, s20, v6
	v_fma_f32 v7, v108, s21, v7
	v_readlane_b32 s18, v28, 13
	v_readlane_b32 s19, v29, 13
	s_waitcnt vmcnt(52)
	v_fma_f32 v6, v109, s22, v6
	v_fma_f32 v7, v109, s23, v7
	v_readlane_b32 s20, v28, 14
	v_readlane_b32 s21, v29, 14
	s_waitcnt vmcnt(51)
	v_fma_f32 v6, v110, s16, v6
	v_fma_f32 v7, v110, s17, v7
	v_readlane_b32 s22, v28, 15
	v_readlane_b32 s23, v29, 15
	s_waitcnt vmcnt(50)
	v_fma_f32 v6, v111, s18, v6
	v_fma_f32 v7, v111, s19, v7
	v_readlane_b32 s16, v28, 16
	v_readlane_b32 s17, v29, 16
	s_waitcnt vmcnt(49)
	v_fma_f32 v6, v112, s20, v6
	v_fma_f32 v7, v112, s21, v7
	v_readlane_b32 s18, v28, 17
	v_readlane_b32 s19, v29, 17
	s_waitcnt vmcnt(48)
	v_fma_f32 v6, v113, s22, v6
	v_fma_f32 v7, v113, s23, v7
	v_readlane_b32 s20, v28, 18
	v_readlane_b32 s21, v29, 18
	s_waitcnt vmcnt(47)
	v_fma_f32 v6, v114, s16, v6
	v_fma_f32 v7, v114, s17, v7
	v_readlane_b32 s22, v28, 19
	v_readlane_b32 s23, v29, 19
	s_waitcnt vmcnt(46)
	v_fma_f32 v6, v115, s18, v6
	v_fma_f32 v7, v115, s19, v7
	v_readlane_b32 s16, v28, 20
	v_readlane_b32 s17, v29, 20
	s_waitcnt vmcnt(45)
	v_fma_f32 v6, v116, s20, v6
	v_fma_f32 v7, v116, s21, v7
	v_readlane_b32 s18, v28, 21
	v_readlane_b32 s19, v29, 21
	s_waitcnt vmcnt(44)
	v_fma_f32 v6, v117, s22, v6
	v_fma_f32 v7, v117, s23, v7
	v_readlane_b32 s20, v28, 22
	v_readlane_b32 s21, v29, 22
	s_waitcnt vmcnt(43)
	v_fma_f32 v6, v118, s16, v6
	v_fma_f32 v7, v118, s17, v7
	v_readlane_b32 s22, v28, 23
	v_readlane_b32 s23, v29, 23
	s_waitcnt vmcnt(42)
	v_fma_f32 v6, v119, s18, v6
	v_fma_f32 v7, v119, s19, v7
	v_readlane_b32 s16, v28, 24
	v_readlane_b32 s17, v29, 24
	s_waitcnt vmcnt(41)
	v_fma_f32 v6, v120, s20, v6
	v_fma_f32 v7, v120, s21, v7
	v_readlane_b32 s18, v28, 25
	v_readlane_b32 s19, v29, 25
	s_waitcnt vmcnt(40)
	v_fma_f32 v6, v121, s22, v6
	v_fma_f32 v7, v121, s23, v7
	v_readlane_b32 s20, v28, 26
	v_readlane_b32 s21, v29, 26
	s_waitcnt vmcnt(39)
	v_fma_f32 v6, v122, s16, v6
	v_fma_f32 v7, v122, s17, v7
	v_readlane_b32 s22, v28, 27
	v_readlane_b32 s23, v29, 27
	s_waitcnt vmcnt(38)
	v_fma_f32 v6, v123, s18, v6
	v_fma_f32 v7, v123, s19, v7
	v_readlane_b32 s16, v28, 28
	v_readlane_b32 s17, v29, 28
	s_waitcnt vmcnt(37)
	v_fma_f32 v6, v124, s20, v6
	v_fma_f32 v7, v124, s21, v7
	v_readlane_b32 s18, v28, 29
	v_readlane_b32 s19, v29, 29
	s_waitcnt vmcnt(36)
	v_fma_f32 v6, v125, s22, v6
	v_fma_f32 v7, v125, s23, v7
	v_readlane_b32 s20, v28, 30
	v_readlane_b32 s21, v29, 30
	s_waitcnt vmcnt(35)
	v_fma_f32 v6, v126, s16, v6
	v_fma_f32 v7, v126, s17, v7
	v_readlane_b32 s22, v28, 31
	v_readlane_b32 s23, v29, 31
	s_waitcnt vmcnt(34)
	v_fma_f32 v6, v127, s18, v6
	v_fma_f32 v7, v127, s19, v7
	v_readlane_b32 s16, v28, 32
	v_readlane_b32 s17, v29, 32
	s_waitcnt vmcnt(33)
	v_fma_f32 v6, v128, s20, v6
	v_fma_f32 v7, v128, s21, v7
	v_readlane_b32 s18, v28, 33
	v_readlane_b32 s19, v29, 33
	s_waitcnt vmcnt(32)
	v_fma_f32 v6, v129, s22, v6
	v_fma_f32 v7, v129, s23, v7
	v_readlane_b32 s20, v28, 34
	v_readlane_b32 s21, v29, 34
	s_waitcnt vmcnt(31)
	v_fma_f32 v6, v130, s16, v6
	v_fma_f32 v7, v130, s17, v7
	v_readlane_b32 s22, v28, 35
	v_readlane_b32 s23, v29, 35
	s_waitcnt vmcnt(30)
	v_fma_f32 v6, v131, s18, v6
	v_fma_f32 v7, v131, s19, v7
	v_readlane_b32 s16, v28, 36
	v_readlane_b32 s17, v29, 36
	s_waitcnt vmcnt(29)
	v_fma_f32 v6, v132, s20, v6
	v_fma_f32 v7, v132, s21, v7
	v_readlane_b32 s18, v28, 37
	v_readlane_b32 s19, v29, 37
	s_waitcnt vmcnt(28)
	v_fma_f32 v6, v133, s22, v6
	v_fma_f32 v7, v133, s23, v7
	v_readlane_b32 s20, v28, 38
	v_readlane_b32 s21, v29, 38
	s_waitcnt vmcnt(27)
	v_fma_f32 v6, v134, s16, v6
	v_fma_f32 v7, v134, s17, v7
	v_readlane_b32 s22, v28, 39
	v_readlane_b32 s23, v29, 39
	s_waitcnt vmcnt(26)
	v_fma_f32 v6, v135, s18, v6
	v_fma_f32 v7, v135, s19, v7
	v_readlane_b32 s16, v28, 40
	v_readlane_b32 s17, v29, 40
	s_waitcnt vmcnt(25)
	v_fma_f32 v6, v136, s20, v6
	v_fma_f32 v7, v136, s21, v7
	v_readlane_b32 s18, v28, 41
	v_readlane_b32 s19, v29, 41
	s_waitcnt vmcnt(24)
	v_fma_f32 v6, v137, s22, v6
	v_fma_f32 v7, v137, s23, v7
	v_readlane_b32 s20, v28, 42
	v_readlane_b32 s21, v29, 42
	s_waitcnt vmcnt(23)
	v_fma_f32 v6, v138, s16, v6
	v_fma_f32 v7, v138, s17, v7
	v_readlane_b32 s22, v28, 43
	v_readlane_b32 s23, v29, 43
	s_waitcnt vmcnt(22)
	v_fma_f32 v6, v139, s18, v6
	v_fma_f32 v7, v139, s19, v7
	v_readlane_b32 s16, v28, 44
	v_readlane_b32 s17, v29, 44
	s_waitcnt vmcnt(21)
	v_fma_f32 v6, v140, s20, v6
	v_fma_f32 v7, v140, s21, v7
	v_readlane_b32 s18, v28, 45
	v_readlane_b32 s19, v29, 45
	s_waitcnt vmcnt(20)
	v_fma_f32 v6, v141, s22, v6
	v_fma_f32 v7, v141, s23, v7
	v_readlane_b32 s20, v28, 46
	v_readlane_b32 s21, v29, 46
	s_waitcnt vmcnt(19)
	v_fma_f32 v6, v142, s16, v6
	v_fma_f32 v7, v142, s17, v7
	v_readlane_b32 s22, v28, 47
	v_readlane_b32 s23, v29, 47
	s_waitcnt vmcnt(18)
	v_fma_f32 v6, v143, s18, v6
	v_fma_f32 v7, v143, s19, v7
	v_readlane_b32 s16, v28, 48
	v_readlane_b32 s17, v29, 48
	s_waitcnt vmcnt(17)
	v_fma_f32 v6, v144, s20, v6
	v_fma_f32 v7, v144, s21, v7
	v_readlane_b32 s18, v28, 49
	v_readlane_b32 s19, v29, 49
	s_waitcnt vmcnt(16)
	v_fma_f32 v6, v145, s22, v6
	v_fma_f32 v7, v145, s23, v7
	v_readlane_b32 s20, v28, 50
	v_readlane_b32 s21, v29, 50
	s_waitcnt vmcnt(15)
	v_fma_f32 v6, v146, s16, v6
	v_fma_f32 v7, v146, s17, v7
	v_readlane_b32 s22, v28, 51
	v_readlane_b32 s23, v29, 51
	s_waitcnt vmcnt(14)
	v_fma_f32 v6, v147, s18, v6
	v_fma_f32 v7, v147, s19, v7
	v_readlane_b32 s16, v28, 52
	v_readlane_b32 s17, v29, 52
	s_waitcnt vmcnt(13)
	v_fma_f32 v6, v148, s20, v6
	v_fma_f32 v7, v148, s21, v7
	v_readlane_b32 s18, v28, 53
	v_readlane_b32 s19, v29, 53
	s_waitcnt vmcnt(12)
	v_fma_f32 v6, v149, s22, v6
	v_fma_f32 v7, v149, s23, v7
	v_readlane_b32 s20, v28, 54
	v_readlane_b32 s21, v29, 54
	s_waitcnt vmcnt(11)
	v_fma_f32 v6, v150, s16, v6
	v_fma_f32 v7, v150, s17, v7
	v_readlane_b32 s22, v28, 55
	v_readlane_b32 s23, v29, 55
	s_waitcnt vmcnt(10)
	v_fma_f32 v6, v151, s18, v6
	v_fma_f32 v7, v151, s19, v7
	v_readlane_b32 s16, v28, 56
	v_readlane_b32 s17, v29, 56
	s_waitcnt vmcnt(9)
	v_fma_f32 v6, v152, s20, v6
	v_fma_f32 v7, v152, s21, v7
	v_readlane_b32 s18, v28, 57
	v_readlane_b32 s19, v29, 57
	s_waitcnt vmcnt(8)
	v_fma_f32 v6, v153, s22, v6
	v_fma_f32 v7, v153, s23, v7
	v_readlane_b32 s20, v28, 58
	v_readlane_b32 s21, v29, 58
	s_waitcnt vmcnt(7)
	v_fma_f32 v6, v154, s16, v6
	v_fma_f32 v7, v154, s17, v7
	v_readlane_b32 s22, v28, 59
	v_readlane_b32 s23, v29, 59
	s_waitcnt vmcnt(6)
	v_fma_f32 v6, v155, s18, v6
	v_fma_f32 v7, v155, s19, v7
	v_readlane_b32 s16, v28, 60
	v_readlane_b32 s17, v29, 60
	s_waitcnt vmcnt(5)
	v_fma_f32 v6, v156, s20, v6
	v_fma_f32 v7, v156, s21, v7
	v_readlane_b32 s18, v28, 61
	v_readlane_b32 s19, v29, 61
	s_waitcnt vmcnt(4)
	v_fma_f32 v6, v157, s22, v6
	v_fma_f32 v7, v157, s23, v7
	v_readlane_b32 s20, v28, 62
	v_readlane_b32 s21, v29, 62
	s_waitcnt vmcnt(3)
	v_fma_f32 v6, v158, s16, v6
	v_fma_f32 v7, v158, s17, v7
	v_readlane_b32 s22, v28, 63
	v_readlane_b32 s23, v29, 63
	s_waitcnt vmcnt(2)
	v_fma_f32 v6, v159, s18, v6
	v_fma_f32 v7, v159, s19, v7
	s_waitcnt vmcnt(1)
	v_fma_f32 v6, v164, s20, v6
	v_fma_f32 v7, v164, s21, v7
	s_waitcnt vmcnt(0)
	v_fma_f32 v6, v165, s22, v6
	v_fma_f32 v7, v165, s23, v7
	s_mov_b64 s[0:1], 0
	s_and_saveexec_b64 s[0:1], s[6:7]
	s_cbranch_execz .LBB0_754
	v_ashrrev_i32_e32 v3, 31, v2
	v_readlane_b32 s2, v251, 20
	v_lshlrev_b64 v[2:3], 2, v[2:3]
	v_readlane_b32 s3, v251, 21
	s_nop 1
	v_lshl_add_u64 v[4:5], s[2:3], 0, v[2:3]
	v_readlane_b32 s2, v251, 14
	v_readlane_b32 s3, v251, 15
	s_nop 1
	v_lshl_add_u64 v[2:3], s[2:3], 0, v[2:3]
	global_atomic_add_f32 v[2:3], v6, off
	global_atomic_add_f32 v[4:5], v7, off
	s_branch .LBB0_754

.LBB0_825:
	v_cndmask_b32_e64 v0, 0, 1, s[0:1]
	v_cmp_ne_u32_e32 vcc, 1, v0
	v_or_b32_e32 v0, s3, v10
	v_lshlrev_b64 v[8:9], 2, v[0:1]
	v_lshl_add_u64 v[12:13], s[8:9], 0, v[8:9]
	v_lshl_add_u64 v[8:9], s[10:11], 0, v[8:9]
	s_mul_i32 s90, s3, 0x3830
	global_load_dword v3, v[12:13], off
	global_load_dword v11, v[8:9], off
	global_load_dword v28, v[12:13], off offset:256
	global_load_dword v29, v[8:9], off offset:256
	v_lshl_add_u64 v[8:9], s[90:91], 2, v[4:5]
	s_mov_b32 s14, 0xe0c0
	s_mov_b32 s15, 0
	global_load_dword v32, v[8:9], off
	v_lshl_add_u64 v[8:9], v[8:9], 0, s[14:15]
	global_load_dword v33, v[8:9], off
	v_lshl_add_u64 v[8:9], v[8:9], 0, s[14:15]
	global_load_dword v34, v[8:9], off
	v_lshl_add_u64 v[8:9], v[8:9], 0, s[14:15]
	global_load_dword v35, v[8:9], off
	v_lshl_add_u64 v[8:9], v[8:9], 0, s[14:15]
	global_load_dword v36, v[8:9], off
	v_lshl_add_u64 v[8:9], v[8:9], 0, s[14:15]
	global_load_dword v37, v[8:9], off
	v_lshl_add_u64 v[8:9], v[8:9], 0, s[14:15]
	global_load_dword v38, v[8:9], off
	v_lshl_add_u64 v[8:9], v[8:9], 0, s[14:15]
	global_load_dword v39, v[8:9], off
	v_lshl_add_u64 v[8:9], v[8:9], 0, s[14:15]
	global_load_dword v40, v[8:9], off
	v_lshl_add_u64 v[8:9], v[8:9], 0, s[14:15]
	global_load_dword v41, v[8:9], off
	v_lshl_add_u64 v[8:9], v[8:9], 0, s[14:15]
	global_load_dword v42, v[8:9], off
	v_lshl_add_u64 v[8:9], v[8:9], 0, s[14:15]
	global_load_dword v43, v[8:9], off
	v_lshl_add_u64 v[8:9], v[8:9], 0, s[14:15]
	global_load_dword v44, v[8:9], off
	v_lshl_add_u64 v[8:9], v[8:9], 0, s[14:15]
	global_load_dword v45, v[8:9], off
	v_lshl_add_u64 v[8:9], v[8:9], 0, s[14:15]
	global_load_dword v46, v[8:9], off
	v_lshl_add_u64 v[8:9], v[8:9], 0, s[14:15]
	global_load_dword v47, v[8:9], off
	v_lshl_add_u64 v[8:9], v[8:9], 0, s[14:15]
	global_load_dword v48, v[8:9], off
	v_lshl_add_u64 v[8:9], v[8:9], 0, s[14:15]
	global_load_dword v49, v[8:9], off
	v_lshl_add_u64 v[8:9], v[8:9], 0, s[14:15]
	global_load_dword v50, v[8:9], off
	v_lshl_add_u64 v[8:9], v[8:9], 0, s[14:15]
	global_load_dword v51, v[8:9], off
	v_lshl_add_u64 v[8:9], v[8:9], 0, s[14:15]
	global_load_dword v52, v[8:9], off
	v_lshl_add_u64 v[8:9], v[8:9], 0, s[14:15]
	global_load_dword v53, v[8:9], off
	v_lshl_add_u64 v[8:9], v[8:9], 0, s[14:15]
	global_load_dword v54, v[8:9], off
	v_lshl_add_u64 v[8:9], v[8:9], 0, s[14:15]
	global_load_dword v55, v[8:9], off
	v_lshl_add_u64 v[8:9], v[8:9], 0, s[14:15]
	global_load_dword v58, v[8:9], off
	v_lshl_add_u64 v[8:9], v[8:9], 0, s[14:15]
	global_load_dword v59, v[8:9], off
	v_lshl_add_u64 v[8:9], v[8:9], 0, s[14:15]
	global_load_dword v60, v[8:9], off
	v_lshl_add_u64 v[8:9], v[8:9], 0, s[14:15]
	global_load_dword v61, v[8:9], off
	v_lshl_add_u64 v[8:9], v[8:9], 0, s[14:15]
	global_load_dword v62, v[8:9], off
	v_lshl_add_u64 v[8:9], v[8:9], 0, s[14:15]
	global_load_dword v63, v[8:9], off
	v_lshl_add_u64 v[8:9], v[8:9], 0, s[14:15]
	global_load_dword v64, v[8:9], off
	v_lshl_add_u64 v[8:9], v[8:9], 0, s[14:15]
	global_load_dword v65, v[8:9], off
	v_lshl_add_u64 v[8:9], v[8:9], 0, s[14:15]
	global_load_dword v66, v[8:9], off
	v_lshl_add_u64 v[8:9], v[8:9], 0, s[14:15]
	global_load_dword v67, v[8:9], off
	v_lshl_add_u64 v[8:9], v[8:9], 0, s[14:15]
	global_load_dword v68, v[8:9], off
	v_lshl_add_u64 v[8:9], v[8:9], 0, s[14:15]
	global_load_dword v69, v[8:9], off
	v_lshl_add_u64 v[8:9], v[8:9], 0, s[14:15]
	global_load_dword v70, v[8:9], off
	v_lshl_add_u64 v[8:9], v[8:9], 0, s[14:15]
	global_load_dword v71, v[8:9], off
	v_lshl_add_u64 v[8:9], v[8:9], 0, s[14:15]
	global_load_dword v72, v[8:9], off
	v_lshl_add_u64 v[8:9], v[8:9], 0, s[14:15]
	global_load_dword v73, v[8:9], off
	v_lshl_add_u64 v[8:9], v[8:9], 0, s[14:15]
	global_load_dword v74, v[8:9], off
	v_lshl_add_u64 v[8:9], v[8:9], 0, s[14:15]
	global_load_dword v75, v[8:9], off
	v_lshl_add_u64 v[8:9], v[8:9], 0, s[14:15]
	global_load_dword v76, v[8:9], off
	v_lshl_add_u64 v[8:9], v[8:9], 0, s[14:15]
	global_load_dword v77, v[8:9], off
	v_lshl_add_u64 v[8:9], v[8:9], 0, s[14:15]
	global_load_dword v78, v[8:9], off
	v_lshl_add_u64 v[8:9], v[8:9], 0, s[14:15]
	global_load_dword v79, v[8:9], off
	v_lshl_add_u64 v[8:9], v[8:9], 0, s[14:15]
	global_load_dword v80, v[8:9], off
	v_lshl_add_u64 v[8:9], v[8:9], 0, s[14:15]
	global_load_dword v81, v[8:9], off
	v_lshl_add_u64 v[8:9], v[8:9], 0, s[14:15]
	global_load_dword v82, v[8:9], off
	v_lshl_add_u64 v[8:9], v[8:9], 0, s[14:15]
	global_load_dword v83, v[8:9], off
	v_lshl_add_u64 v[8:9], v[8:9], 0, s[14:15]
	global_load_dword v84, v[8:9], off
	v_lshl_add_u64 v[8:9], v[8:9], 0, s[14:15]
	global_load_dword v85, v[8:9], off
	v_lshl_add_u64 v[8:9], v[8:9], 0, s[14:15]
	global_load_dword v86, v[8:9], off
	v_lshl_add_u64 v[8:9], v[8:9], 0, s[14:15]
	global_load_dword v87, v[8:9], off
	v_lshl_add_u64 v[8:9], v[8:9], 0, s[14:15]
	global_load_dword v88, v[8:9], off
	v_lshl_add_u64 v[8:9], v[8:9], 0, s[14:15]
	global_load_dword v89, v[8:9], off
	v_lshl_add_u64 v[8:9], v[8:9], 0, s[14:15]
	global_load_dword v90, v[8:9], off
	v_lshl_add_u64 v[8:9], v[8:9], 0, s[14:15]
	global_load_dword v91, v[8:9], off
	v_lshl_add_u64 v[8:9], v[8:9], 0, s[14:15]
	global_load_dword v92, v[8:9], off
	v_lshl_add_u64 v[8:9], v[8:9], 0, s[14:15]
	global_load_dword v93, v[8:9], off
	v_lshl_add_u64 v[8:9], v[8:9], 0, s[14:15]
	global_load_dword v94, v[8:9], off
	v_lshl_add_u64 v[8:9], v[8:9], 0, s[14:15]
	global_load_dword v95, v[8:9], off
	v_lshl_add_u64 v[8:9], v[8:9], 0, s[14:15]
	global_load_dword v96, v[8:9], off
	v_lshl_add_u64 v[8:9], v[8:9], 0, s[14:15]
	global_load_dword v97, v[8:9], off
	v_lshl_add_u64 v[8:9], v[8:9], 0, s[14:15]
	global_load_dword v98, v[8:9], off
	v_lshl_add_u64 v[8:9], v[8:9], 0, s[14:15]
	global_load_dword v99, v[8:9], off
	v_lshl_add_u64 v[8:9], v[8:9], 0, s[14:15]
	global_load_dword v100, v[8:9], off
	v_lshl_add_u64 v[8:9], v[8:9], 0, s[14:15]
	global_load_dword v101, v[8:9], off
	v_lshl_add_u64 v[8:9], v[8:9], 0, s[14:15]
	global_load_dword v102, v[8:9], off
	v_lshl_add_u64 v[8:9], v[8:9], 0, s[14:15]
	global_load_dword v103, v[8:9], off
	v_lshl_add_u64 v[8:9], v[8:9], 0, s[14:15]
	global_load_dword v104, v[8:9], off
	v_lshl_add_u64 v[8:9], v[8:9], 0, s[14:15]
	global_load_dword v105, v[8:9], off
	v_lshl_add_u64 v[8:9], v[8:9], 0, s[14:15]
	global_load_dword v106, v[8:9], off
	v_lshl_add_u64 v[8:9], v[8:9], 0, s[14:15]
	global_load_dword v107, v[8:9], off
	v_lshl_add_u64 v[8:9], v[8:9], 0, s[14:15]
	global_load_dword v108, v[8:9], off
	v_lshl_add_u64 v[8:9], v[8:9], 0, s[14:15]
	global_load_dword v109, v[8:9], off
	v_lshl_add_u64 v[8:9], v[8:9], 0, s[14:15]
	global_load_dword v110, v[8:9], off
	v_lshl_add_u64 v[8:9], v[8:9], 0, s[14:15]
	global_load_dword v111, v[8:9], off
	v_lshl_add_u64 v[8:9], v[8:9], 0, s[14:15]
	global_load_dword v112, v[8:9], off
	v_lshl_add_u64 v[8:9], v[8:9], 0, s[14:15]
	global_load_dword v113, v[8:9], off
	v_lshl_add_u64 v[8:9], v[8:9], 0, s[14:15]
	global_load_dword v114, v[8:9], off
	v_lshl_add_u64 v[8:9], v[8:9], 0, s[14:15]
	global_load_dword v115, v[8:9], off
	v_lshl_add_u64 v[8:9], v[8:9], 0, s[14:15]
	global_load_dword v116, v[8:9], off
	v_lshl_add_u64 v[8:9], v[8:9], 0, s[14:15]
	global_load_dword v117, v[8:9], off
	v_lshl_add_u64 v[8:9], v[8:9], 0, s[14:15]
	global_load_dword v118, v[8:9], off
	v_lshl_add_u64 v[8:9], v[8:9], 0, s[14:15]
	global_load_dword v119, v[8:9], off
	v_lshl_add_u64 v[8:9], v[8:9], 0, s[14:15]
	global_load_dword v120, v[8:9], off
	v_lshl_add_u64 v[8:9], v[8:9], 0, s[14:15]
	global_load_dword v121, v[8:9], off
	v_lshl_add_u64 v[8:9], v[8:9], 0, s[14:15]
	global_load_dword v122, v[8:9], off
	v_lshl_add_u64 v[8:9], v[8:9], 0, s[14:15]
	global_load_dword v123, v[8:9], off
	v_lshl_add_u64 v[8:9], v[8:9], 0, s[14:15]
	global_load_dword v124, v[8:9], off
	v_lshl_add_u64 v[8:9], v[8:9], 0, s[14:15]
	global_load_dword v125, v[8:9], off
	v_lshl_add_u64 v[8:9], v[8:9], 0, s[14:15]
	global_load_dword v126, v[8:9], off
	v_lshl_add_u64 v[8:9], v[8:9], 0, s[14:15]
	global_load_dword v127, v[8:9], off
	v_lshl_add_u64 v[8:9], v[8:9], 0, s[14:15]
	global_load_dword v128, v[8:9], off
	v_lshl_add_u64 v[8:9], v[8:9], 0, s[14:15]
	global_load_dword v129, v[8:9], off
	v_lshl_add_u64 v[8:9], v[8:9], 0, s[14:15]
	global_load_dword v130, v[8:9], off
	v_lshl_add_u64 v[8:9], v[8:9], 0, s[14:15]
	global_load_dword v131, v[8:9], off
	v_lshl_add_u64 v[8:9], v[8:9], 0, s[14:15]
	global_load_dword v132, v[8:9], off
	v_lshl_add_u64 v[8:9], v[8:9], 0, s[14:15]
	global_load_dword v133, v[8:9], off
	v_lshl_add_u64 v[8:9], v[8:9], 0, s[14:15]
	global_load_dword v134, v[8:9], off
	v_lshl_add_u64 v[8:9], v[8:9], 0, s[14:15]
	global_load_dword v135, v[8:9], off
	v_lshl_add_u64 v[8:9], v[8:9], 0, s[14:15]
	global_load_dword v136, v[8:9], off
	v_lshl_add_u64 v[8:9], v[8:9], 0, s[14:15]
	global_load_dword v137, v[8:9], off
	v_lshl_add_u64 v[8:9], v[8:9], 0, s[14:15]
	global_load_dword v138, v[8:9], off
	v_lshl_add_u64 v[8:9], v[8:9], 0, s[14:15]
	global_load_dword v139, v[8:9], off
	v_lshl_add_u64 v[8:9], v[8:9], 0, s[14:15]
	global_load_dword v140, v[8:9], off
	v_lshl_add_u64 v[8:9], v[8:9], 0, s[14:15]
	global_load_dword v141, v[8:9], off
	v_lshl_add_u64 v[8:9], v[8:9], 0, s[14:15]
	global_load_dword v142, v[8:9], off
	v_lshl_add_u64 v[8:9], v[8:9], 0, s[14:15]
	global_load_dword v143, v[8:9], off
	v_lshl_add_u64 v[8:9], v[8:9], 0, s[14:15]
	global_load_dword v144, v[8:9], off
	v_lshl_add_u64 v[8:9], v[8:9], 0, s[14:15]
	global_load_dword v145, v[8:9], off
	v_lshl_add_u64 v[8:9], v[8:9], 0, s[14:15]
	global_load_dword v146, v[8:9], off
	v_lshl_add_u64 v[8:9], v[8:9], 0, s[14:15]
	global_load_dword v147, v[8:9], off
	v_lshl_add_u64 v[8:9], v[8:9], 0, s[14:15]
	global_load_dword v148, v[8:9], off
	v_lshl_add_u64 v[8:9], v[8:9], 0, s[14:15]
	global_load_dword v149, v[8:9], off
	v_lshl_add_u64 v[8:9], v[8:9], 0, s[14:15]
	global_load_dword v150, v[8:9], off
	v_lshl_add_u64 v[8:9], v[8:9], 0, s[14:15]
	global_load_dword v151, v[8:9], off
	v_lshl_add_u64 v[8:9], v[8:9], 0, s[14:15]
	global_load_dword v152, v[8:9], off
	v_lshl_add_u64 v[8:9], v[8:9], 0, s[14:15]
	global_load_dword v153, v[8:9], off
	v_lshl_add_u64 v[8:9], v[8:9], 0, s[14:15]
	global_load_dword v154, v[8:9], off
	v_lshl_add_u64 v[8:9], v[8:9], 0, s[14:15]
	global_load_dword v155, v[8:9], off
	v_lshl_add_u64 v[8:9], v[8:9], 0, s[14:15]
	global_load_dword v156, v[8:9], off
	v_lshl_add_u64 v[8:9], v[8:9], 0, s[14:15]
	global_load_dword v157, v[8:9], off
	v_lshl_add_u64 v[8:9], v[8:9], 0, s[14:15]
	global_load_dword v158, v[8:9], off
	v_lshl_add_u64 v[8:9], v[8:9], 0, s[14:15]
	global_load_dword v159, v[8:9], off
	v_lshl_add_u64 v[8:9], v[8:9], 0, s[14:15]
	global_load_dword v164, v[8:9], off
	v_lshl_add_u64 v[8:9], v[8:9], 0, s[14:15]
	global_load_dword v165, v[8:9], off
	s_and_b64 vcc, exec, vcc
	s_mov_b32 s3, 64
	s_waitcnt vmcnt(63)
	v_readlane_b32 s16, v3, 0
	v_readlane_b32 s17, v11, 0
	v_readlane_b32 s18, v3, 1
	v_readlane_b32 s19, v11, 1
	v_readlane_b32 s20, v3, 2
	v_readlane_b32 s21, v11, 2
	v_fma_f32 v6, v32, s16, v6
	v_fma_f32 v7, v32, s17, v7
	v_readlane_b32 s22, v3, 3
	v_readlane_b32 s23, v11, 3
	v_fma_f32 v6, v33, s18, v6
	v_fma_f32 v7, v33, s19, v7
	v_readlane_b32 s16, v3, 4
	v_readlane_b32 s17, v11, 4
	v_fma_f32 v6, v34, s20, v6
	v_fma_f32 v7, v34, s21, v7
	v_readlane_b32 s18, v3, 5
	v_readlane_b32 s19, v11, 5
	v_fma_f32 v6, v35, s22, v6
	v_fma_f32 v7, v35, s23, v7
	v_readlane_b32 s20, v3, 6
	v_readlane_b32 s21, v11, 6
	v_fma_f32 v6, v36, s16, v6
	v_fma_f32 v7, v36, s17, v7
	v_readlane_b32 s22, v3, 7
	v_readlane_b32 s23, v11, 7
	v_fma_f32 v6, v37, s18, v6
	v_fma_f32 v7, v37, s19, v7
	v_readlane_b32 s16, v3, 8
	v_readlane_b32 s17, v11, 8
	v_fma_f32 v6, v38, s20, v6
	v_fma_f32 v7, v38, s21, v7
	v_readlane_b32 s18, v3, 9
	v_readlane_b32 s19, v11, 9
	v_fma_f32 v6, v39, s22, v6
	v_fma_f32 v7, v39, s23, v7
	v_readlane_b32 s20, v3, 10
	v_readlane_b32 s21, v11, 10
	v_fma_f32 v6, v40, s16, v6
	v_fma_f32 v7, v40, s17, v7
	v_readlane_b32 s22, v3, 11
	v_readlane_b32 s23, v11, 11
	v_fma_f32 v6, v41, s18, v6
	v_fma_f32 v7, v41, s19, v7
	v_readlane_b32 s16, v3, 12
	v_readlane_b32 s17, v11, 12
	v_fma_f32 v6, v42, s20, v6
	v_fma_f32 v7, v42, s21, v7
	v_readlane_b32 s18, v3, 13
	v_readlane_b32 s19, v11, 13
	v_fma_f32 v6, v43, s22, v6
	v_fma_f32 v7, v43, s23, v7
	v_readlane_b32 s20, v3, 14
	v_readlane_b32 s21, v11, 14
	v_fma_f32 v6, v44, s16, v6
	v_fma_f32 v7, v44, s17, v7
	v_readlane_b32 s22, v3, 15
	v_readlane_b32 s23, v11, 15
	v_fma_f32 v6, v45, s18, v6
	v_fma_f32 v7, v45, s19, v7
	v_readlane_b32 s16, v3, 16
	v_readlane_b32 s17, v11, 16
	v_fma_f32 v6, v46, s20, v6
	v_fma_f32 v7, v46, s21, v7
	v_readlane_b32 s18, v3, 17
	v_readlane_b32 s19, v11, 17
	v_fma_f32 v6, v47, s22, v6
	v_fma_f32 v7, v47, s23, v7
	v_readlane_b32 s20, v3, 18
	v_readlane_b32 s21, v11, 18
	v_fma_f32 v6, v48, s16, v6
	v_fma_f32 v7, v48, s17, v7
	v_readlane_b32 s22, v3, 19
	v_readlane_b32 s23, v11, 19
	v_fma_f32 v6, v49, s18, v6
	v_fma_f32 v7, v49, s19, v7
	v_readlane_b32 s16, v3, 20
	v_readlane_b32 s17, v11, 20
	v_fma_f32 v6, v50, s20, v6
	v_fma_f32 v7, v50, s21, v7
	v_readlane_b32 s18, v3, 21
	v_readlane_b32 s19, v11, 21
	v_fma_f32 v6, v51, s22, v6
	v_fma_f32 v7, v51, s23, v7
	v_readlane_b32 s20, v3, 22
	v_readlane_b32 s21, v11, 22
	v_fma_f32 v6, v52, s16, v6
	v_fma_f32 v7, v52, s17, v7
	v_readlane_b32 s22, v3, 23
	v_readlane_b32 s23, v11, 23
	v_fma_f32 v6, v53, s18, v6
	v_fma_f32 v7, v53, s19, v7
	v_readlane_b32 s16, v3, 24
	v_readlane_b32 s17, v11, 24
	v_fma_f32 v6, v54, s20, v6
	v_fma_f32 v7, v54, s21, v7
	v_readlane_b32 s18, v3, 25
	v_readlane_b32 s19, v11, 25
	v_fma_f32 v6, v55, s22, v6
	v_fma_f32 v7, v55, s23, v7
	v_readlane_b32 s20, v3, 26
	v_readlane_b32 s21, v11, 26
	v_fma_f32 v6, v58, s16, v6
	v_fma_f32 v7, v58, s17, v7
	v_readlane_b32 s22, v3, 27
	v_readlane_b32 s23, v11, 27
	v_fma_f32 v6, v59, s18, v6
	v_fma_f32 v7, v59, s19, v7
	v_readlane_b32 s16, v3, 28
	v_readlane_b32 s17, v11, 28
	v_fma_f32 v6, v60, s20, v6
	v_fma_f32 v7, v60, s21, v7
	v_readlane_b32 s18, v3, 29
	v_readlane_b32 s19, v11, 29
	v_fma_f32 v6, v61, s22, v6
	v_fma_f32 v7, v61, s23, v7
	v_readlane_b32 s20, v3, 30
	v_readlane_b32 s21, v11, 30
	v_fma_f32 v6, v62, s16, v6
	v_fma_f32 v7, v62, s17, v7
	v_readlane_b32 s22, v3, 31
	v_readlane_b32 s23, v11, 31
	v_fma_f32 v6, v63, s18, v6
	v_fma_f32 v7, v63, s19, v7
	v_readlane_b32 s16, v3, 32
	v_readlane_b32 s17, v11, 32
	v_fma_f32 v6, v64, s20, v6
	v_fma_f32 v7, v64, s21, v7
	v_readlane_b32 s18, v3, 33
	v_readlane_b32 s19, v11, 33
	v_fma_f32 v6, v65, s22, v6
	v_fma_f32 v7, v65, s23, v7
	v_readlane_b32 s20, v3, 34
	v_readlane_b32 s21, v11, 34
	v_fma_f32 v6, v66, s16, v6
	v_fma_f32 v7, v66, s17, v7
	v_readlane_b32 s22, v3, 35
	v_readlane_b32 s23, v11, 35
	v_fma_f32 v6, v67, s18, v6
	v_fma_f32 v7, v67, s19, v7
	v_readlane_b32 s16, v3, 36
	v_readlane_b32 s17, v11, 36
	v_fma_f32 v6, v68, s20, v6
	v_fma_f32 v7, v68, s21, v7
	v_readlane_b32 s18, v3, 37
	v_readlane_b32 s19, v11, 37
	v_fma_f32 v6, v69, s22, v6
	v_fma_f32 v7, v69, s23, v7
	v_readlane_b32 s20, v3, 38
	v_readlane_b32 s21, v11, 38
	v_fma_f32 v6, v70, s16, v6
	v_fma_f32 v7, v70, s17, v7
	v_readlane_b32 s22, v3, 39
	v_readlane_b32 s23, v11, 39
	v_fma_f32 v6, v71, s18, v6
	v_fma_f32 v7, v71, s19, v7
	v_readlane_b32 s16, v3, 40
	v_readlane_b32 s17, v11, 40
	v_fma_f32 v6, v72, s20, v6
	v_fma_f32 v7, v72, s21, v7
	v_readlane_b32 s18, v3, 41
	v_readlane_b32 s19, v11, 41
	v_fma_f32 v6, v73, s22, v6
	v_fma_f32 v7, v73, s23, v7
	v_readlane_b32 s20, v3, 42
	v_readlane_b32 s21, v11, 42
	v_fma_f32 v6, v74, s16, v6
	v_fma_f32 v7, v74, s17, v7
	v_readlane_b32 s22, v3, 43
	v_readlane_b32 s23, v11, 43
	v_fma_f32 v6, v75, s18, v6
	v_fma_f32 v7, v75, s19, v7
	v_readlane_b32 s16, v3, 44
	v_readlane_b32 s17, v11, 44
	v_fma_f32 v6, v76, s20, v6
	v_fma_f32 v7, v76, s21, v7
	v_readlane_b32 s18, v3, 45
	v_readlane_b32 s19, v11, 45
	v_fma_f32 v6, v77, s22, v6
	v_fma_f32 v7, v77, s23, v7
	v_readlane_b32 s20, v3, 46
	v_readlane_b32 s21, v11, 46
	v_fma_f32 v6, v78, s16, v6
	v_fma_f32 v7, v78, s17, v7
	v_readlane_b32 s22, v3, 47
	v_readlane_b32 s23, v11, 47
	v_fma_f32 v6, v79, s18, v6
	v_fma_f32 v7, v79, s19, v7
	v_readlane_b32 s16, v3, 48
	v_readlane_b32 s17, v11, 48
	v_fma_f32 v6, v80, s20, v6
	v_fma_f32 v7, v80, s21, v7
	v_readlane_b32 s18, v3, 49
	v_readlane_b32 s19, v11, 49
	v_fma_f32 v6, v81, s22, v6
	v_fma_f32 v7, v81, s23, v7
	v_readlane_b32 s20, v3, 50
	v_readlane_b32 s21, v11, 50
	v_fma_f32 v6, v82, s16, v6
	v_fma_f32 v7, v82, s17, v7
	v_readlane_b32 s22, v3, 51
	v_readlane_b32 s23, v11, 51
	v_fma_f32 v6, v83, s18, v6
	v_fma_f32 v7, v83, s19, v7
	v_readlane_b32 s16, v3, 52
	v_readlane_b32 s17, v11, 52
	v_fma_f32 v6, v84, s20, v6
	v_fma_f32 v7, v84, s21, v7
	v_readlane_b32 s18, v3, 53
	v_readlane_b32 s19, v11, 53
	v_fma_f32 v6, v85, s22, v6
	v_fma_f32 v7, v85, s23, v7
	v_readlane_b32 s20, v3, 54
	v_readlane_b32 s21, v11, 54
	v_fma_f32 v6, v86, s16, v6
	v_fma_f32 v7, v86, s17, v7
	v_readlane_b32 s22, v3, 55
	v_readlane_b32 s23, v11, 55
	v_fma_f32 v6, v87, s18, v6
	v_fma_f32 v7, v87, s19, v7
	v_readlane_b32 s16, v3, 56
	v_readlane_b32 s17, v11, 56
	v_fma_f32 v6, v88, s20, v6
	v_fma_f32 v7, v88, s21, v7
	v_readlane_b32 s18, v3, 57
	v_readlane_b32 s19, v11, 57
	v_fma_f32 v6, v89, s22, v6
	v_fma_f32 v7, v89, s23, v7
	v_readlane_b32 s20, v3, 58
	v_readlane_b32 s21, v11, 58
	v_fma_f32 v6, v90, s16, v6
	v_fma_f32 v7, v90, s17, v7
	v_readlane_b32 s22, v3, 59
	v_readlane_b32 s23, v11, 59
	v_fma_f32 v6, v91, s18, v6
	v_fma_f32 v7, v91, s19, v7
	v_readlane_b32 s16, v3, 60
	v_readlane_b32 s17, v11, 60
	v_fma_f32 v6, v92, s20, v6
	v_fma_f32 v7, v92, s21, v7
	v_readlane_b32 s18, v3, 61
	v_readlane_b32 s19, v11, 61
	v_fma_f32 v6, v93, s22, v6
	v_fma_f32 v7, v93, s23, v7
	v_readlane_b32 s20, v3, 62
	v_readlane_b32 s21, v11, 62
	v_fma_f32 v6, v94, s16, v6
	v_fma_f32 v7, v94, s17, v7
	v_readlane_b32 s22, v3, 63
	v_readlane_b32 s23, v11, 63
	v_fma_f32 v6, v95, s18, v6
	v_fma_f32 v7, v95, s19, v7
	v_readlane_b32 s16, v28, 0
	v_readlane_b32 s17, v29, 0
	v_fma_f32 v6, v96, s20, v6
	v_fma_f32 v7, v96, s21, v7
	v_readlane_b32 s18, v28, 1
	v_readlane_b32 s19, v29, 1
	v_fma_f32 v6, v97, s22, v6
	v_fma_f32 v7, v97, s23, v7
	v_readlane_b32 s20, v28, 2
	v_readlane_b32 s21, v29, 2
	v_fma_f32 v6, v98, s16, v6
	v_fma_f32 v7, v98, s17, v7
	v_readlane_b32 s22, v28, 3
	v_readlane_b32 s23, v29, 3
	s_waitcnt vmcnt(62)
	v_fma_f32 v6, v99, s18, v6
	v_fma_f32 v7, v99, s19, v7
	v_readlane_b32 s16, v28, 4
	v_readlane_b32 s17, v29, 4
	s_waitcnt vmcnt(61)
	v_fma_f32 v6, v100, s20, v6
	v_fma_f32 v7, v100, s21, v7
	v_readlane_b32 s18, v28, 5
	v_readlane_b32 s19, v29, 5
	s_waitcnt vmcnt(60)
	v_fma_f32 v6, v101, s22, v6
	v_fma_f32 v7, v101, s23, v7
	v_readlane_b32 s20, v28, 6
	v_readlane_b32 s21, v29, 6
	s_waitcnt vmcnt(59)
	v_fma_f32 v6, v102, s16, v6
	v_fma_f32 v7, v102, s17, v7
	v_readlane_b32 s22, v28, 7
	v_readlane_b32 s23, v29, 7
	s_waitcnt vmcnt(58)
	v_fma_f32 v6, v103, s18, v6
	v_fma_f32 v7, v103, s19, v7
	v_readlane_b32 s16, v28, 8
	v_readlane_b32 s17, v29, 8
	s_waitcnt vmcnt(57)
	v_fma_f32 v6, v104, s20, v6
	v_fma_f32 v7, v104, s21, v7
	v_readlane_b32 s18, v28, 9
	v_readlane_b32 s19, v29, 9
	s_waitcnt vmcnt(56)
	v_fma_f32 v6, v105, s22, v6
	v_fma_f32 v7, v105, s23, v7
	v_readlane_b32 s20, v28, 10
	v_readlane_b32 s21, v29, 10
	s_waitcnt vmcnt(55)
	v_fma_f32 v6, v106, s16, v6
	v_fma_f32 v7, v106, s17, v7
	v_readlane_b32 s22, v28, 11
	v_readlane_b32 s23, v29, 11
	s_waitcnt vmcnt(54)
	v_fma_f32 v6, v107, s18, v6
	v_fma_f32 v7, v107, s19, v7
	v_readlane_b32 s16, v28, 12
	v_readlane_b32 s17, v29, 12
	s_waitcnt vmcnt(53)
	v_fma_f32 v6, v108, s20, v6
	v_fma_f32 v7, v108, s21, v7
	v_readlane_b32 s18, v28, 13
	v_readlane_b32 s19, v29, 13
	s_waitcnt vmcnt(52)
	v_fma_f32 v6, v109, s22, v6
	v_fma_f32 v7, v109, s23, v7
	v_readlane_b32 s20, v28, 14
	v_readlane_b32 s21, v29, 14
	s_waitcnt vmcnt(51)
	v_fma_f32 v6, v110, s16, v6
	v_fma_f32 v7, v110, s17, v7
	v_readlane_b32 s22, v28, 15
	v_readlane_b32 s23, v29, 15
	s_waitcnt vmcnt(50)
	v_fma_f32 v6, v111, s18, v6
	v_fma_f32 v7, v111, s19, v7
	v_readlane_b32 s16, v28, 16
	v_readlane_b32 s17, v29, 16
	s_waitcnt vmcnt(49)
	v_fma_f32 v6, v112, s20, v6
	v_fma_f32 v7, v112, s21, v7
	v_readlane_b32 s18, v28, 17
	v_readlane_b32 s19, v29, 17
	s_waitcnt vmcnt(48)
	v_fma_f32 v6, v113, s22, v6
	v_fma_f32 v7, v113, s23, v7
	v_readlane_b32 s20, v28, 18
	v_readlane_b32 s21, v29, 18
	s_waitcnt vmcnt(47)
	v_fma_f32 v6, v114, s16, v6
	v_fma_f32 v7, v114, s17, v7
	v_readlane_b32 s22, v28, 19
	v_readlane_b32 s23, v29, 19
	s_waitcnt vmcnt(46)
	v_fma_f32 v6, v115, s18, v6
	v_fma_f32 v7, v115, s19, v7
	v_readlane_b32 s16, v28, 20
	v_readlane_b32 s17, v29, 20
	s_waitcnt vmcnt(45)
	v_fma_f32 v6, v116, s20, v6
	v_fma_f32 v7, v116, s21, v7
	v_readlane_b32 s18, v28, 21
	v_readlane_b32 s19, v29, 21
	s_waitcnt vmcnt(44)
	v_fma_f32 v6, v117, s22, v6
	v_fma_f32 v7, v117, s23, v7
	v_readlane_b32 s20, v28, 22
	v_readlane_b32 s21, v29, 22
	s_waitcnt vmcnt(43)
	v_fma_f32 v6, v118, s16, v6
	v_fma_f32 v7, v118, s17, v7
	v_readlane_b32 s22, v28, 23
	v_readlane_b32 s23, v29, 23
	s_waitcnt vmcnt(42)
	v_fma_f32 v6, v119, s18, v6
	v_fma_f32 v7, v119, s19, v7
	v_readlane_b32 s16, v28, 24
	v_readlane_b32 s17, v29, 24
	s_waitcnt vmcnt(41)
	v_fma_f32 v6, v120, s20, v6
	v_fma_f32 v7, v120, s21, v7
	v_readlane_b32 s18, v28, 25
	v_readlane_b32 s19, v29, 25
	s_waitcnt vmcnt(40)
	v_fma_f32 v6, v121, s22, v6
	v_fma_f32 v7, v121, s23, v7
	v_readlane_b32 s20, v28, 26
	v_readlane_b32 s21, v29, 26
	s_waitcnt vmcnt(39)
	v_fma_f32 v6, v122, s16, v6
	v_fma_f32 v7, v122, s17, v7
	v_readlane_b32 s22, v28, 27
	v_readlane_b32 s23, v29, 27
	s_waitcnt vmcnt(38)
	v_fma_f32 v6, v123, s18, v6
	v_fma_f32 v7, v123, s19, v7
	v_readlane_b32 s16, v28, 28
	v_readlane_b32 s17, v29, 28
	s_waitcnt vmcnt(37)
	v_fma_f32 v6, v124, s20, v6
	v_fma_f32 v7, v124, s21, v7
	v_readlane_b32 s18, v28, 29
	v_readlane_b32 s19, v29, 29
	s_waitcnt vmcnt(36)
	v_fma_f32 v6, v125, s22, v6
	v_fma_f32 v7, v125, s23, v7
	v_readlane_b32 s20, v28, 30
	v_readlane_b32 s21, v29, 30
	s_waitcnt vmcnt(35)
	v_fma_f32 v6, v126, s16, v6
	v_fma_f32 v7, v126, s17, v7
	v_readlane_b32 s22, v28, 31
	v_readlane_b32 s23, v29, 31
	s_waitcnt vmcnt(34)
	v_fma_f32 v6, v127, s18, v6
	v_fma_f32 v7, v127, s19, v7
	v_readlane_b32 s16, v28, 32
	v_readlane_b32 s17, v29, 32
	s_waitcnt vmcnt(33)
	v_fma_f32 v6, v128, s20, v6
	v_fma_f32 v7, v128, s21, v7
	v_readlane_b32 s18, v28, 33
	v_readlane_b32 s19, v29, 33
	s_waitcnt vmcnt(32)
	v_fma_f32 v6, v129, s22, v6
	v_fma_f32 v7, v129, s23, v7
	v_readlane_b32 s20, v28, 34
	v_readlane_b32 s21, v29, 34
	s_waitcnt vmcnt(31)
	v_fma_f32 v6, v130, s16, v6
	v_fma_f32 v7, v130, s17, v7
	v_readlane_b32 s22, v28, 35
	v_readlane_b32 s23, v29, 35
	s_waitcnt vmcnt(30)
	v_fma_f32 v6, v131, s18, v6
	v_fma_f32 v7, v131, s19, v7
	v_readlane_b32 s16, v28, 36
	v_readlane_b32 s17, v29, 36
	s_waitcnt vmcnt(29)
	v_fma_f32 v6, v132, s20, v6
	v_fma_f32 v7, v132, s21, v7
	v_readlane_b32 s18, v28, 37
	v_readlane_b32 s19, v29, 37
	s_waitcnt vmcnt(28)
	v_fma_f32 v6, v133, s22, v6
	v_fma_f32 v7, v133, s23, v7
	v_readlane_b32 s20, v28, 38
	v_readlane_b32 s21, v29, 38
	s_waitcnt vmcnt(27)
	v_fma_f32 v6, v134, s16, v6
	v_fma_f32 v7, v134, s17, v7
	v_readlane_b32 s22, v28, 39
	v_readlane_b32 s23, v29, 39
	s_waitcnt vmcnt(26)
	v_fma_f32 v6, v135, s18, v6
	v_fma_f32 v7, v135, s19, v7
	v_readlane_b32 s16, v28, 40
	v_readlane_b32 s17, v29, 40
	s_waitcnt vmcnt(25)
	v_fma_f32 v6, v136, s20, v6
	v_fma_f32 v7, v136, s21, v7
	v_readlane_b32 s18, v28, 41
	v_readlane_b32 s19, v29, 41
	s_waitcnt vmcnt(24)
	v_fma_f32 v6, v137, s22, v6
	v_fma_f32 v7, v137, s23, v7
	v_readlane_b32 s20, v28, 42
	v_readlane_b32 s21, v29, 42
	s_waitcnt vmcnt(23)
	v_fma_f32 v6, v138, s16, v6
	v_fma_f32 v7, v138, s17, v7
	v_readlane_b32 s22, v28, 43
	v_readlane_b32 s23, v29, 43
	s_waitcnt vmcnt(22)
	v_fma_f32 v6, v139, s18, v6
	v_fma_f32 v7, v139, s19, v7
	v_readlane_b32 s16, v28, 44
	v_readlane_b32 s17, v29, 44
	s_waitcnt vmcnt(21)
	v_fma_f32 v6, v140, s20, v6
	v_fma_f32 v7, v140, s21, v7
	v_readlane_b32 s18, v28, 45
	v_readlane_b32 s19, v29, 45
	s_waitcnt vmcnt(20)
	v_fma_f32 v6, v141, s22, v6
	v_fma_f32 v7, v141, s23, v7
	v_readlane_b32 s20, v28, 46
	v_readlane_b32 s21, v29, 46
	s_waitcnt vmcnt(19)
	v_fma_f32 v6, v142, s16, v6
	v_fma_f32 v7, v142, s17, v7
	v_readlane_b32 s22, v28, 47
	v_readlane_b32 s23, v29, 47
	s_waitcnt vmcnt(18)
	v_fma_f32 v6, v143, s18, v6
	v_fma_f32 v7, v143, s19, v7
	v_readlane_b32 s16, v28, 48
	v_readlane_b32 s17, v29, 48
	s_waitcnt vmcnt(17)
	v_fma_f32 v6, v144, s20, v6
	v_fma_f32 v7, v144, s21, v7
	v_readlane_b32 s18, v28, 49
	v_readlane_b32 s19, v29, 49
	s_waitcnt vmcnt(16)
	v_fma_f32 v6, v145, s22, v6
	v_fma_f32 v7, v145, s23, v7
	v_readlane_b32 s20, v28, 50
	v_readlane_b32 s21, v29, 50
	s_waitcnt vmcnt(15)
	v_fma_f32 v6, v146, s16, v6
	v_fma_f32 v7, v146, s17, v7
	v_readlane_b32 s22, v28, 51
	v_readlane_b32 s23, v29, 51
	s_waitcnt vmcnt(14)
	v_fma_f32 v6, v147, s18, v6
	v_fma_f32 v7, v147, s19, v7
	v_readlane_b32 s16, v28, 52
	v_readlane_b32 s17, v29, 52
	s_waitcnt vmcnt(13)
	v_fma_f32 v6, v148, s20, v6
	v_fma_f32 v7, v148, s21, v7
	v_readlane_b32 s18, v28, 53
	v_readlane_b32 s19, v29, 53
	s_waitcnt vmcnt(12)
	v_fma_f32 v6, v149, s22, v6
	v_fma_f32 v7, v149, s23, v7
	v_readlane_b32 s20, v28, 54
	v_readlane_b32 s21, v29, 54
	s_waitcnt vmcnt(11)
	v_fma_f32 v6, v150, s16, v6
	v_fma_f32 v7, v150, s17, v7
	v_readlane_b32 s22, v28, 55
	v_readlane_b32 s23, v29, 55
	s_waitcnt vmcnt(10)
	v_fma_f32 v6, v151, s18, v6
	v_fma_f32 v7, v151, s19, v7
	v_readlane_b32 s16, v28, 56
	v_readlane_b32 s17, v29, 56
	s_waitcnt vmcnt(9)
	v_fma_f32 v6, v152, s20, v6
	v_fma_f32 v7, v152, s21, v7
	v_readlane_b32 s18, v28, 57
	v_readlane_b32 s19, v29, 57
	s_waitcnt vmcnt(8)
	v_fma_f32 v6, v153, s22, v6
	v_fma_f32 v7, v153, s23, v7
	v_readlane_b32 s20, v28, 58
	v_readlane_b32 s21, v29, 58
	s_waitcnt vmcnt(7)
	v_fma_f32 v6, v154, s16, v6
	v_fma_f32 v7, v154, s17, v7
	v_readlane_b32 s22, v28, 59
	v_readlane_b32 s23, v29, 59
	s_waitcnt vmcnt(6)
	v_fma_f32 v6, v155, s18, v6
	v_fma_f32 v7, v155, s19, v7
	v_readlane_b32 s16, v28, 60
	v_readlane_b32 s17, v29, 60
	s_waitcnt vmcnt(5)
	v_fma_f32 v6, v156, s20, v6
	v_fma_f32 v7, v156, s21, v7
	v_readlane_b32 s18, v28, 61
	v_readlane_b32 s19, v29, 61
	s_waitcnt vmcnt(4)
	v_fma_f32 v6, v157, s22, v6
	v_fma_f32 v7, v157, s23, v7
	v_readlane_b32 s20, v28, 62
	v_readlane_b32 s21, v29, 62
	s_waitcnt vmcnt(3)
	v_fma_f32 v6, v158, s16, v6
	v_fma_f32 v7, v158, s17, v7
	v_readlane_b32 s22, v28, 63
	v_readlane_b32 s23, v29, 63
	s_waitcnt vmcnt(2)
	v_fma_f32 v6, v159, s18, v6
	v_fma_f32 v7, v159, s19, v7
	s_waitcnt vmcnt(1)
	v_fma_f32 v6, v164, s20, v6
	v_fma_f32 v7, v164, s21, v7
	s_waitcnt vmcnt(0)
	v_fma_f32 v6, v165, s22, v6
	v_fma_f32 v7, v165, s23, v7
	s_mov_b64 s[0:1], 0
	v_readlane_b32 s2, v254, 51
	v_readlane_b32 s3, v254, 52
	s_and_saveexec_b64 s[0:1], s[2:3]
	v_readlane_b32 s62, v254, 0
	v_readlane_b32 s63, v254, 1
	s_cbranch_execz .LBB0_823
	v_ashrrev_i32_e32 v3, 31, v2
	v_readlane_b32 s4, v251, 34
	v_lshlrev_b64 v[2:3], 2, v[2:3]
	v_readlane_b32 s5, v251, 35
	s_nop 1
	v_lshl_add_u64 v[4:5], s[4:5], 0, v[2:3]
	v_lshl_add_u64 v[2:3], s[62:63], 0, v[2:3]
	global_atomic_add_f32 v[2:3], v6, off
	global_atomic_add_f32 v[4:5], v7, off
	s_branch .LBB0_823
